# back-edge rotation (asm guide 7.11): K-loop loop-carried pointer/counter increments and the exit compare moved from after the last barrier into the wait shadow at the end of the last load segment (all
# speedup vs baseline: 1.0367x; 1.0005x over previous
; #define PG8_STAGE(bufoff, gbase, voff) do { _Pragma("unroll") for (int _i = 0; _i < 2; ++_i) \
;         __builtin_amdgcn_global_load_lds((const unsigned*)((const char*)(gbase) + (voff)[_i]), (PG8_LAS unsigned*)(lds + (bufoff) + ldsw + _i * 8192), 16, 0, 0); } while (0)
; #define PG8_LDA(dst, b, h) do { _Pragma("unroll") for (int m = 0; m < 4; ++m) _Pragma("unroll") for (int k = 0; k < 2; ++k) dst[m][k] = *(const PG8_LAS bf16x8*)(lds + PG8_SA(b, h) + aoff + m * 2048 + k * 1024); } while (0)
; #define PG8_LDB(dst, b, h) do { _Pragma("unroll") for (int n = 0; n < 2; ++n) _Pragma("unroll") for (int k = 0; k < 2; ++k) dst[n][k] = *(const PG8_LAS bf16x8*)(lds + PG8_SB(b, h) + boff + n * 2048 + k * 1024); } while (0)
; #define PG8_MMA(ai, bj, At, Bt) do { __builtin_amdgcn_s_setprio(1); _Pragma("unroll") for (int m = 0; m < 4; ++m) _Pragma("unroll") for (int n = 0; n < 2; ++n) _Pragma("unroll") for (int k = 0; k < 2; ++k) \
;         acc[ai][bj][m][n] = __builtin_amdgcn_mfma_f32_16x16x32_bf16(Bt[n][k], At[m][k], acc[ai][bj][m][n], 0, 0, 0); __builtin_amdgcn_s_setprio(0); } while (0)
; #define PG8_WAIT_V(n) asm volatile("s_waitcnt vmcnt(" #n ")" ::: "memory")
; #define PG8_WAIT_L(n) asm volatile("s_waitcnt lgkmcnt(" #n ")" ::: "memory")
; #define PG8_BAR __builtin_amdgcn_s_barrier()
; #define PG8_SCHED __builtin_amdgcn_sched_barrier(0)
; template <class Epi, class Sched, bool ALIGN_EPI = false, bool SP2 = false>
; __device__ __forceinline__ void gemm_phase(PG8_LAS unsigned char* lds, const Gemm g, const Sched& S, const Epi& E) {
;     ...
;     f32x4 acc[2][2][4][2];
; #pragma unroll
;     for (int a = 0; a < 2; ++a)
; #pragma unroll
;         for (int b = 0; b < 2; ++b)
; #pragma unroll
;             for (int m = 0; m < 4; ++m)
; #pragma unroll
;                 for (int n = 0; n < 2; ++n) acc[a][b][m][n] = (f32x4){0.f, 0.f, 0.f, 0.f};
;     ...
;             PG8_LDB(B0, 0, 0); PG8_LDB(B1, 0, 1); PG8_SCHED; PG8_LDA(At, 0, 0); PG8_STAGE(PG8_SA(1, 1), a1 + hstep, voffA);
;             PG8_WAIT_V(8); PG8_WAIT_L(0); PG8_BAR; PG8_MMA(0, 0, At, B0); PG8_MMA(0, 1, At, B1); PG8_BAR; PG8_SCHED;
;             PG8_LDA(At, 0, 1); PG8_STAGE(PG8_SB(0, 0), b2, voffB); PG8_STAGE(PG8_SB(0, 1), b2 + hstep, voffB); PG8_STAGE(PG8_SA(0, 0), a2, voffA);
;             PG8_WAIT_V(8); PG8_WAIT_L(0); PG8_BAR; PG8_MMA(1, 0, At, B0); PG8_MMA(1, 1, At, B1); PG8_BAR; PG8_SCHED;
.Labo_peel:
	ds_read_b128 v[68:71], v254
	ds_read_b128 v[72:75], v254 offset:1024
	ds_read_b128 v[76:79], v254 offset:2048
	ds_read_b128 v[80:83], v254 offset:3072
	ds_read_b128 v[174:177], v254 offset:16384
	ds_read_b128 v[182:185], v254 offset:17408
	ds_read_b128 v[186:189], v254 offset:18432
	ds_read_b128 v[210:213], v254 offset:19456
	s_add_u32 s2, s0, 0xfffc0080
	s_addc_u32 s3, s1, -1
	s_cmp_eq_u32 s56, 12
	s_cselect_b32 s5, s27, s3
	s_cselect_b32 s4, s52, s2
	s_cselect_b32 s3, s25, s55
	s_cselect_b32 s2, s53, s54
	s_add_i32 m0, s29, 0xc000
	ds_read_b128 v[214:217], v179
	ds_read_b128 v[218:221], v179 offset:1024
	ds_read_b128 v[222:225], v179 offset:2048
	ds_read_b128 v[226:229], v179 offset:3072
	ds_read_b128 v[230:233], v179 offset:4096
	ds_read_b128 v[234:237], v179 offset:5120
	ds_read_b128 v[238:241], v179 offset:6144
	ds_read_b128 v[242:245], v179 offset:7168
	global_load_lds_dwordx4 v170, s[0:1]
	s_add_i32 m0, s29, 0xe000
	s_nop 0
	global_load_lds_dwordx4 v172, s[0:1]
	s_waitcnt vmcnt(8)
	s_waitcnt lgkmcnt(0)
	s_barrier
	s_setprio 1
	v_mfma_f32_16x16x32_bf16 v[140:143], v[68:71], v[214:217], 0
	v_mfma_f32_16x16x32_bf16 v[136:139], v[76:79], v[214:217], 0
	v_mfma_f32_16x16x32_bf16 v[124:127], v[68:71], v[222:225], 0
	v_mfma_f32_16x16x32_bf16 v[120:123], v[76:79], v[222:225], 0
	v_mfma_f32_16x16x32_bf16 v[108:111], v[68:71], v[230:233], 0
	v_mfma_f32_16x16x32_bf16 v[104:107], v[76:79], v[230:233], 0
	v_mfma_f32_16x16x32_bf16 v[92:95], v[68:71], v[238:241], 0
	v_mfma_f32_16x16x32_bf16 v[88:91], v[76:79], v[238:241], 0
	v_mfma_f32_16x16x32_bf16 v[140:143], v[72:75], v[218:221], v[140:143]
	v_mfma_f32_16x16x32_bf16 v[136:139], v[80:83], v[218:221], v[136:139]
	v_mfma_f32_16x16x32_bf16 v[124:127], v[72:75], v[226:229], v[124:127]
	v_mfma_f32_16x16x32_bf16 v[120:123], v[80:83], v[226:229], v[120:123]
	v_mfma_f32_16x16x32_bf16 v[108:111], v[72:75], v[234:237], v[108:111]
	v_mfma_f32_16x16x32_bf16 v[104:107], v[80:83], v[234:237], v[104:107]
	v_mfma_f32_16x16x32_bf16 v[92:95], v[72:75], v[242:245], v[92:95]
	v_mfma_f32_16x16x32_bf16 v[88:91], v[80:83], v[242:245], v[88:91]
	v_mfma_f32_16x16x32_bf16 v[132:135], v[174:177], v[214:217], 0
	v_mfma_f32_16x16x32_bf16 v[128:131], v[186:189], v[214:217], 0
	v_mfma_f32_16x16x32_bf16 v[116:119], v[174:177], v[222:225], 0
	v_mfma_f32_16x16x32_bf16 v[112:115], v[186:189], v[222:225], 0
	v_mfma_f32_16x16x32_bf16 v[100:103], v[174:177], v[230:233], 0
	v_mfma_f32_16x16x32_bf16 v[96:99], v[186:189], v[230:233], 0
	v_mfma_f32_16x16x32_bf16 v[84:87], v[174:177], v[238:241], 0
	v_mfma_f32_16x16x32_bf16 v[64:67], v[186:189], v[238:241], 0
	v_mfma_f32_16x16x32_bf16 v[132:135], v[182:185], v[218:221], v[132:135]
	v_mfma_f32_16x16x32_bf16 v[128:131], v[210:213], v[218:221], v[128:131]
	v_mfma_f32_16x16x32_bf16 v[116:119], v[182:185], v[226:229], v[116:119]
	v_mfma_f32_16x16x32_bf16 v[112:115], v[210:213], v[226:229], v[112:115]
	v_mfma_f32_16x16x32_bf16 v[100:103], v[182:185], v[234:237], v[100:103]
	v_mfma_f32_16x16x32_bf16 v[96:99], v[210:213], v[234:237], v[96:99]
	v_mfma_f32_16x16x32_bf16 v[84:87], v[182:185], v[242:245], v[84:87]
	v_mfma_f32_16x16x32_bf16 v[64:67], v[210:213], v[242:245], v[64:67]
	s_setprio 0
	s_barrier
	s_mov_b32 m0, s30
	s_add_u32 s58, s2, 0x40000
	s_addc_u32 s59, s3, 0
	ds_read_b128 v[214:217], v179 offset:16384
	ds_read_b128 v[218:221], v179 offset:17408
	ds_read_b128 v[222:225], v179 offset:18432
	ds_read_b128 v[226:229], v179 offset:19456
	ds_read_b128 v[230:233], v179 offset:20480
	ds_read_b128 v[234:237], v179 offset:21504
	ds_read_b128 v[238:241], v179 offset:22528
	ds_read_b128 v[242:245], v179 offset:23552
	global_load_lds_dwordx4 v166, s[2:3]
	s_mov_b32 m0, s31
	s_nop 0
	global_load_lds_dwordx4 v162, s[2:3]
	s_mov_b32 m0, s33
	s_nop 0
	global_load_lds_dwordx4 v166, s[58:59]
	s_mov_b32 m0, s34
	s_nop 0
	global_load_lds_dwordx4 v162, s[58:59]
	s_mov_b32 m0, s29
	s_nop 0
	global_load_lds_dwordx4 v168, s[4:5]
	s_mov_b32 m0, s35
	s_nop 0
	global_load_lds_dwordx4 v164, s[4:5]
	s_waitcnt vmcnt(8)
	s_waitcnt lgkmcnt(0)
	s_barrier
	s_setprio 1
	v_mfma_f32_16x16x32_bf16 v[60:63], v[68:71], v[214:217], 0
	v_mfma_f32_16x16x32_bf16 v[56:59], v[76:79], v[214:217], 0
	v_mfma_f32_16x16x32_bf16 v[44:47], v[68:71], v[222:225], 0
	v_mfma_f32_16x16x32_bf16 v[40:43], v[76:79], v[222:225], 0
	v_mfma_f32_16x16x32_bf16 v[28:31], v[68:71], v[230:233], 0
	v_mfma_f32_16x16x32_bf16 v[24:27], v[76:79], v[230:233], 0
	v_mfma_f32_16x16x32_bf16 v[12:15], v[68:71], v[238:241], 0
	v_mfma_f32_16x16x32_bf16 v[8:11], v[76:79], v[238:241], 0
	v_mfma_f32_16x16x32_bf16 v[60:63], v[72:75], v[218:221], v[60:63]
	v_mfma_f32_16x16x32_bf16 v[56:59], v[80:83], v[218:221], v[56:59]
	v_mfma_f32_16x16x32_bf16 v[44:47], v[72:75], v[226:229], v[44:47]
	v_mfma_f32_16x16x32_bf16 v[40:43], v[80:83], v[226:229], v[40:43]
	v_mfma_f32_16x16x32_bf16 v[28:31], v[72:75], v[234:237], v[28:31]
	v_mfma_f32_16x16x32_bf16 v[24:27], v[80:83], v[234:237], v[24:27]
	v_mfma_f32_16x16x32_bf16 v[12:15], v[72:75], v[242:245], v[12:15]
	v_mfma_f32_16x16x32_bf16 v[8:11], v[80:83], v[242:245], v[8:11]
	v_mfma_f32_16x16x32_bf16 v[52:55], v[174:177], v[214:217], 0
	v_mfma_f32_16x16x32_bf16 v[48:51], v[186:189], v[214:217], 0
	v_mfma_f32_16x16x32_bf16 v[36:39], v[174:177], v[222:225], 0
	v_mfma_f32_16x16x32_bf16 v[32:35], v[186:189], v[222:225], 0
	v_mfma_f32_16x16x32_bf16 v[20:23], v[174:177], v[230:233], 0
	v_mfma_f32_16x16x32_bf16 v[16:19], v[186:189], v[230:233], 0
	v_mfma_f32_16x16x32_bf16 v[4:7], v[174:177], v[238:241], 0
	v_mfma_f32_16x16x32_bf16 v[0:3], v[186:189], v[238:241], 0
	v_mfma_f32_16x16x32_bf16 v[52:55], v[182:185], v[218:221], v[52:55]
	v_mfma_f32_16x16x32_bf16 v[48:51], v[210:213], v[218:221], v[48:51]
	v_mfma_f32_16x16x32_bf16 v[36:39], v[182:185], v[226:229], v[36:39]
	v_mfma_f32_16x16x32_bf16 v[32:35], v[210:213], v[226:229], v[32:35]
	v_mfma_f32_16x16x32_bf16 v[20:23], v[182:185], v[234:237], v[20:23]
	v_mfma_f32_16x16x32_bf16 v[16:19], v[210:213], v[234:237], v[16:19]
	v_mfma_f32_16x16x32_bf16 v[4:7], v[182:185], v[242:245], v[4:7]
	v_mfma_f32_16x16x32_bf16 v[0:3], v[210:213], v[242:245], v[0:3]
	s_setprio 0
	s_barrier
; #define PG8_STAGE(bufoff, gbase, voff) do { _Pragma("unroll") for (int _i = 0; _i < 2; ++_i) \
;         __builtin_amdgcn_global_load_lds((const unsigned*)((const char*)(gbase) + (voff)[_i]), (PG8_LAS unsigned*)(lds + (bufoff) + ldsw + _i * 8192), 16, 0, 0); } while (0)
; #define PG8_LDA(dst, b, h) do { _Pragma("unroll") for (int m = 0; m < 4; ++m) _Pragma("unroll") for (int k = 0; k < 2; ++k) dst[m][k] = *(const PG8_LAS bf16x8*)(lds + PG8_SA(b, h) + aoff + m * 2048 + k * 1024); } while (0)
; #define PG8_LDB(dst, b, h) do { _Pragma("unroll") for (int n = 0; n < 2; ++n) _Pragma("unroll") for (int k = 0; k < 2; ++k) dst[n][k] = *(const PG8_LAS bf16x8*)(lds + PG8_SB(b, h) + boff + n * 2048 + k * 1024); } while (0)
; #define PG8_MMA(ai, bj, At, Bt) do { __builtin_amdgcn_s_setprio(1); _Pragma("unroll") for (int m = 0; m < 4; ++m) _Pragma("unroll") for (int n = 0; n < 2; ++n) _Pragma("unroll") for (int k = 0; k < 2; ++k) \
;         acc[ai][bj][m][n] = __builtin_amdgcn_mfma_f32_16x16x32_bf16(Bt[n][k], At[m][k], acc[ai][bj][m][n], 0, 0, 0); __builtin_amdgcn_s_setprio(0); } while (0)
; #define PG8_WAIT_V(n) asm volatile("s_waitcnt vmcnt(" #n ")" ::: "memory")
; #define PG8_WAIT_L(n) asm volatile("s_waitcnt lgkmcnt(" #n ")" ::: "memory")
; #define PG8_BAR __builtin_amdgcn_s_barrier()
; #define PG8_SCHED __builtin_amdgcn_sched_barrier(0)
; template <class Epi, class Sched, bool ALIGN_EPI = false, bool SP2 = false>
; __device__ __forceinline__ void gemm_phase(PG8_LAS unsigned char* lds, const Gemm g, const Sched& S, const Epi& E) {
;     ...
;             PG8_LDB(B0, 1, 0); PG8_LDB(B1, 1, 1); PG8_SCHED; PG8_LDA(At, 1, 0); PG8_STAGE(PG8_SA(0, 1), a2 + hstep, voffA);
;             PG8_WAIT_V(8); PG8_WAIT_L(0); PG8_BAR; PG8_MMA(0, 0, At, B0); PG8_MMA(0, 1, At, B1); PG8_BAR; PG8_SCHED;
;             PG8_LDA(At, 1, 1); PG8_STAGE(PG8_SB(1, 0), b3, voffB); PG8_STAGE(PG8_SB(1, 1), b3 + hstep, voffB); PG8_STAGE(PG8_SA(1, 0), a3, voffA);
;             PG8_WAIT_V(8); PG8_WAIT_L(0); PG8_BAR; PG8_MMA(1, 0, At, B0); PG8_MMA(1, 1, At, B1); PG8_BAR; PG8_SCHED;
	ds_read_b128 v[68:71], v254 offset:32768
	ds_read_b128 v[72:75], v254 offset:33792
	ds_read_b128 v[76:79], v254 offset:34816
	ds_read_b128 v[80:83], v254 offset:35840
	ds_read_b128 v[174:177], v254 offset:49152
	ds_read_b128 v[182:185], v254 offset:50176
	ds_read_b128 v[186:189], v254 offset:51200
	ds_read_b128 v[210:213], v254 offset:52224
	s_add_u32 s4, s4, 0x40000
	s_addc_u32 s5, s5, 0
	s_mov_b32 m0, s40
	ds_read_b128 v[214:217], v179 offset:32768
	ds_read_b128 v[218:221], v179 offset:33792
	ds_read_b128 v[222:225], v179 offset:34816
	ds_read_b128 v[226:229], v179 offset:35840
	ds_read_b128 v[230:233], v179 offset:36864
	ds_read_b128 v[234:237], v179 offset:37888
	ds_read_b128 v[238:241], v179 offset:38912
	ds_read_b128 v[242:245], v179 offset:39936
	global_load_lds_dwordx4 v168, s[4:5]
	s_mov_b32 m0, s41
	s_nop 0
	global_load_lds_dwordx4 v164, s[4:5]
	s_waitcnt vmcnt(8)
	s_waitcnt lgkmcnt(0)
	s_barrier
	s_setprio 1
	v_mfma_f32_16x16x32_bf16 v[140:143], v[68:71], v[214:217], v[140:143]
	v_mfma_f32_16x16x32_bf16 v[136:139], v[76:79], v[214:217], v[136:139]
	v_mfma_f32_16x16x32_bf16 v[124:127], v[68:71], v[222:225], v[124:127]
	v_mfma_f32_16x16x32_bf16 v[120:123], v[76:79], v[222:225], v[120:123]
	v_mfma_f32_16x16x32_bf16 v[108:111], v[68:71], v[230:233], v[108:111]
	v_mfma_f32_16x16x32_bf16 v[104:107], v[76:79], v[230:233], v[104:107]
	v_mfma_f32_16x16x32_bf16 v[92:95], v[68:71], v[238:241], v[92:95]
	v_mfma_f32_16x16x32_bf16 v[88:91], v[76:79], v[238:241], v[88:91]
	v_mfma_f32_16x16x32_bf16 v[140:143], v[72:75], v[218:221], v[140:143]
	v_mfma_f32_16x16x32_bf16 v[136:139], v[80:83], v[218:221], v[136:139]
	v_mfma_f32_16x16x32_bf16 v[124:127], v[72:75], v[226:229], v[124:127]
	v_mfma_f32_16x16x32_bf16 v[120:123], v[80:83], v[226:229], v[120:123]
	v_mfma_f32_16x16x32_bf16 v[108:111], v[72:75], v[234:237], v[108:111]
	v_mfma_f32_16x16x32_bf16 v[104:107], v[80:83], v[234:237], v[104:107]
	v_mfma_f32_16x16x32_bf16 v[92:95], v[72:75], v[242:245], v[92:95]
	v_mfma_f32_16x16x32_bf16 v[88:91], v[80:83], v[242:245], v[88:91]
	v_mfma_f32_16x16x32_bf16 v[132:135], v[174:177], v[214:217], v[132:135]
	v_mfma_f32_16x16x32_bf16 v[128:131], v[186:189], v[214:217], v[128:131]
	v_mfma_f32_16x16x32_bf16 v[116:119], v[174:177], v[222:225], v[116:119]
	v_mfma_f32_16x16x32_bf16 v[112:115], v[186:189], v[222:225], v[112:115]
	v_mfma_f32_16x16x32_bf16 v[100:103], v[174:177], v[230:233], v[100:103]
	v_mfma_f32_16x16x32_bf16 v[96:99], v[186:189], v[230:233], v[96:99]
	v_mfma_f32_16x16x32_bf16 v[84:87], v[174:177], v[238:241], v[84:87]
	v_mfma_f32_16x16x32_bf16 v[64:67], v[186:189], v[238:241], v[64:67]
	v_mfma_f32_16x16x32_bf16 v[132:135], v[182:185], v[218:221], v[132:135]
	v_mfma_f32_16x16x32_bf16 v[128:131], v[210:213], v[218:221], v[128:131]
	v_mfma_f32_16x16x32_bf16 v[116:119], v[182:185], v[226:229], v[116:119]
	v_mfma_f32_16x16x32_bf16 v[112:115], v[210:213], v[226:229], v[112:115]
	v_mfma_f32_16x16x32_bf16 v[100:103], v[182:185], v[234:237], v[100:103]
	v_mfma_f32_16x16x32_bf16 v[96:99], v[210:213], v[234:237], v[96:99]
	v_mfma_f32_16x16x32_bf16 v[84:87], v[182:185], v[242:245], v[84:87]
	v_mfma_f32_16x16x32_bf16 v[64:67], v[210:213], v[242:245], v[64:67]
	s_setprio 0
	s_barrier
	s_mov_b32 m0, s45
	s_add_u32 s2, s2, 0x40080
	s_addc_u32 s3, s3, 0
	ds_read_b128 v[214:217], v179 offset:49152
	ds_read_b128 v[218:221], v179 offset:50176
	ds_read_b128 v[222:225], v179 offset:51200
	ds_read_b128 v[226:229], v179 offset:52224
	ds_read_b128 v[230:233], v179 offset:53248
	ds_read_b128 v[234:237], v179 offset:54272
	ds_read_b128 v[238:241], v179 offset:55296
	ds_read_b128 v[242:245], v179 offset:56320
	s_add_u32 s98, s2, 0xfffc0000
	s_addc_u32 s99, s3, -1
	global_load_lds_dwordx4 v166, s[98:99]
	s_mov_b32 m0, s46
	s_nop 0
	global_load_lds_dwordx4 v162, s[98:99]
	s_mov_b32 m0, s49
	s_nop 0
	global_load_lds_dwordx4 v166, s[2:3]
	s_mov_b32 m0, s50
	s_nop 0
	global_load_lds_dwordx4 v162, s[2:3]
	s_mov_b32 m0, s47
	s_nop 0
	s_add_u32 s100, s4, 0xfffc0080
	s_addc_u32 s101, s5, -1
	global_load_lds_dwordx4 v168, s[100:101]
	s_mov_b32 m0, s48
	s_nop 0
	global_load_lds_dwordx4 v164, s[100:101]
	s_add_i32 s56, s56, 2
	s_add_u32 s0, s0, 0x100
	s_addc_u32 s1, s1, 0
	s_add_u32 s54, s54, 0x100
	s_addc_u32 s55, s55, 0
	s_cmp_gt_u32 s56, 13
	s_waitcnt vmcnt(8)
	s_waitcnt lgkmcnt(0)
	s_barrier
	s_setprio 1
	v_mfma_f32_16x16x32_bf16 v[60:63], v[68:71], v[214:217], v[60:63]
	v_mfma_f32_16x16x32_bf16 v[56:59], v[76:79], v[214:217], v[56:59]
	v_mfma_f32_16x16x32_bf16 v[44:47], v[68:71], v[222:225], v[44:47]
	v_mfma_f32_16x16x32_bf16 v[40:43], v[76:79], v[222:225], v[40:43]
	v_mfma_f32_16x16x32_bf16 v[28:31], v[68:71], v[230:233], v[28:31]
	v_mfma_f32_16x16x32_bf16 v[24:27], v[76:79], v[230:233], v[24:27]
	v_mfma_f32_16x16x32_bf16 v[12:15], v[68:71], v[238:241], v[12:15]
	v_mfma_f32_16x16x32_bf16 v[8:11], v[76:79], v[238:241], v[8:11]
	v_mfma_f32_16x16x32_bf16 v[60:63], v[72:75], v[218:221], v[60:63]
	v_mfma_f32_16x16x32_bf16 v[56:59], v[80:83], v[218:221], v[56:59]
	v_mfma_f32_16x16x32_bf16 v[44:47], v[72:75], v[226:229], v[44:47]
	v_mfma_f32_16x16x32_bf16 v[40:43], v[80:83], v[226:229], v[40:43]
	v_mfma_f32_16x16x32_bf16 v[28:31], v[72:75], v[234:237], v[28:31]
	v_mfma_f32_16x16x32_bf16 v[24:27], v[80:83], v[234:237], v[24:27]
	v_mfma_f32_16x16x32_bf16 v[12:15], v[72:75], v[242:245], v[12:15]
	v_mfma_f32_16x16x32_bf16 v[8:11], v[80:83], v[242:245], v[8:11]
	v_mfma_f32_16x16x32_bf16 v[52:55], v[174:177], v[214:217], v[52:55]
	v_mfma_f32_16x16x32_bf16 v[48:51], v[186:189], v[214:217], v[48:51]
	v_mfma_f32_16x16x32_bf16 v[36:39], v[174:177], v[222:225], v[36:39]
	v_mfma_f32_16x16x32_bf16 v[32:35], v[186:189], v[222:225], v[32:35]
	v_mfma_f32_16x16x32_bf16 v[20:23], v[174:177], v[230:233], v[20:23]
	v_mfma_f32_16x16x32_bf16 v[16:19], v[186:189], v[230:233], v[16:19]
	v_mfma_f32_16x16x32_bf16 v[4:7], v[174:177], v[238:241], v[4:7]
	v_mfma_f32_16x16x32_bf16 v[0:3], v[186:189], v[238:241], v[0:3]
	v_mfma_f32_16x16x32_bf16 v[52:55], v[182:185], v[218:221], v[52:55]
	v_mfma_f32_16x16x32_bf16 v[48:51], v[210:213], v[218:221], v[48:51]
	v_mfma_f32_16x16x32_bf16 v[36:39], v[182:185], v[226:229], v[36:39]
	v_mfma_f32_16x16x32_bf16 v[32:35], v[210:213], v[226:229], v[32:35]
	v_mfma_f32_16x16x32_bf16 v[20:23], v[182:185], v[234:237], v[20:23]
	v_mfma_f32_16x16x32_bf16 v[16:19], v[210:213], v[234:237], v[16:19]
	v_mfma_f32_16x16x32_bf16 v[4:7], v[182:185], v[242:245], v[4:7]
	v_mfma_f32_16x16x32_bf16 v[0:3], v[210:213], v[242:245], v[0:3]
	s_setprio 0
	s_barrier
; #define PG8_STAGE(bufoff, gbase, voff) do { _Pragma("unroll") for (int _i = 0; _i < 2; ++_i) \
;         __builtin_amdgcn_global_load_lds((const unsigned*)((const char*)(gbase) + (voff)[_i]), (PG8_LAS unsigned*)(lds + (bufoff) + ldsw + _i * 8192), 16, 0, 0); } while (0)
; #define PG8_LDA(dst, b, h) do { _Pragma("unroll") for (int m = 0; m < 4; ++m) _Pragma("unroll") for (int k = 0; k < 2; ++k) dst[m][k] = *(const PG8_LAS bf16x8*)(lds + PG8_SA(b, h) + aoff + m * 2048 + k * 1024); } while (0)
; #define PG8_LDB(dst, b, h) do { _Pragma("unroll") for (int n = 0; n < 2; ++n) _Pragma("unroll") for (int k = 0; k < 2; ++k) dst[n][k] = *(const PG8_LAS bf16x8*)(lds + PG8_SB(b, h) + boff + n * 2048 + k * 1024); } while (0)
; #define PG8_MMA(ai, bj, At, Bt) do { __builtin_amdgcn_s_setprio(1); _Pragma("unroll") for (int m = 0; m < 4; ++m) _Pragma("unroll") for (int n = 0; n < 2; ++n) _Pragma("unroll") for (int k = 0; k < 2; ++k) \
;         acc[ai][bj][m][n] = __builtin_amdgcn_mfma_f32_16x16x32_bf16(Bt[n][k], At[m][k], acc[ai][bj][m][n], 0, 0, 0); __builtin_amdgcn_s_setprio(0); } while (0)
; #define PG8_WAIT_V(n) asm volatile("s_waitcnt vmcnt(" #n ")" ::: "memory")
; #define PG8_BAR __builtin_amdgcn_s_barrier()
; template <class Epi, class Sched, bool ALIGN_EPI = false, bool SP2 = false>
; __device__ __forceinline__ void gemm_phase(PG8_LAS unsigned char* lds, const Gemm g, const Sched& S, const Epi& E) {
;     ...
;         for (int t = 0; t < nt; t += 2) {
;             const bool last = (t == nt - 2);
;             const char* a1 = cA + (size_t)(t + 1) * kstep;
;             const char* a2 = last ? nA : cA + (size_t)(t + 2) * kstep; const char* b2 = last ? nB : cB + (size_t)(t + 2) * kstep;
;             const char* a3 = a2 + kstep; const char* b3 = b2 + kstep;
;             if (last && has_next) S.a_ready(nxt);
;             if constexpr (SP2) {
;             PG8_LDB(B0, 0, 0); PG8_LDB(B1, 0, 1); PG8_SCHED; PG8_LDA(At, 0, 0); PG8_STAGE(PG8_SA(1, 1), a1 + hstep, voffA);
;             PG8_WAIT_V(8); PG8_WAIT_L(0); PG8_BAR; PG8_MMA(0, 0, At, B0); PG8_MMA(0, 1, At, B1); PG8_BAR; PG8_SCHED;
;             PG8_LDA(At, 0, 1); PG8_STAGE(PG8_SB(0, 0), b2, voffB); PG8_STAGE(PG8_SB(0, 1), b2 + hstep, voffB); PG8_STAGE(PG8_SA(0, 0), a2, voffA);
;             PG8_WAIT_V(8); PG8_WAIT_L(0); PG8_BAR; PG8_MMA(1, 0, At, B0); PG8_MMA(1, 1, At, B1); PG8_BAR; PG8_SCHED;
.LBB0_327:
	ds_read_b128 v[68:71], v254
	ds_read_b128 v[72:75], v254 offset:1024
	ds_read_b128 v[76:79], v254 offset:2048
	ds_read_b128 v[80:83], v254 offset:3072
	ds_read_b128 v[174:177], v254 offset:16384
	ds_read_b128 v[182:185], v254 offset:17408
	ds_read_b128 v[186:189], v254 offset:18432
	ds_read_b128 v[210:213], v254 offset:19456
	s_add_u32 s2, s0, 0xfffc0080
	s_addc_u32 s3, s1, -1
	s_cmp_eq_u32 s56, 12
	s_cselect_b32 s5, s27, s3
	s_cselect_b32 s4, s52, s2
	s_cselect_b32 s3, s25, s55
	s_cselect_b32 s2, s53, s54
	s_add_i32 m0, s29, 0xc000
	ds_read_b128 v[214:217], v179
	ds_read_b128 v[218:221], v179 offset:1024
	ds_read_b128 v[222:225], v179 offset:2048
	ds_read_b128 v[226:229], v179 offset:3072
	ds_read_b128 v[230:233], v179 offset:4096
	ds_read_b128 v[234:237], v179 offset:5120
	ds_read_b128 v[238:241], v179 offset:6144
	ds_read_b128 v[242:245], v179 offset:7168
	global_load_lds_dwordx4 v170, s[0:1]
	s_add_i32 m0, s29, 0xe000
	s_nop 0
	global_load_lds_dwordx4 v172, s[0:1]
	s_waitcnt vmcnt(8)
	s_waitcnt lgkmcnt(0)
	s_barrier
	s_setprio 1
	v_mfma_f32_16x16x32_bf16 v[140:143], v[68:71], v[214:217], v[140:143]
	v_mfma_f32_16x16x32_bf16 v[136:139], v[76:79], v[214:217], v[136:139]
	v_mfma_f32_16x16x32_bf16 v[124:127], v[68:71], v[222:225], v[124:127]
	v_mfma_f32_16x16x32_bf16 v[120:123], v[76:79], v[222:225], v[120:123]
	v_mfma_f32_16x16x32_bf16 v[108:111], v[68:71], v[230:233], v[108:111]
	v_mfma_f32_16x16x32_bf16 v[104:107], v[76:79], v[230:233], v[104:107]
	v_mfma_f32_16x16x32_bf16 v[92:95], v[68:71], v[238:241], v[92:95]
	v_mfma_f32_16x16x32_bf16 v[88:91], v[76:79], v[238:241], v[88:91]
	v_mfma_f32_16x16x32_bf16 v[140:143], v[72:75], v[218:221], v[140:143]
	v_mfma_f32_16x16x32_bf16 v[136:139], v[80:83], v[218:221], v[136:139]
	v_mfma_f32_16x16x32_bf16 v[124:127], v[72:75], v[226:229], v[124:127]
	v_mfma_f32_16x16x32_bf16 v[120:123], v[80:83], v[226:229], v[120:123]
	v_mfma_f32_16x16x32_bf16 v[108:111], v[72:75], v[234:237], v[108:111]
	v_mfma_f32_16x16x32_bf16 v[104:107], v[80:83], v[234:237], v[104:107]
	v_mfma_f32_16x16x32_bf16 v[92:95], v[72:75], v[242:245], v[92:95]
	v_mfma_f32_16x16x32_bf16 v[88:91], v[80:83], v[242:245], v[88:91]
	v_mfma_f32_16x16x32_bf16 v[132:135], v[174:177], v[214:217], v[132:135]
	v_mfma_f32_16x16x32_bf16 v[128:131], v[186:189], v[214:217], v[128:131]
	v_mfma_f32_16x16x32_bf16 v[116:119], v[174:177], v[222:225], v[116:119]
	v_mfma_f32_16x16x32_bf16 v[112:115], v[186:189], v[222:225], v[112:115]
	v_mfma_f32_16x16x32_bf16 v[100:103], v[174:177], v[230:233], v[100:103]
	v_mfma_f32_16x16x32_bf16 v[96:99], v[186:189], v[230:233], v[96:99]
	v_mfma_f32_16x16x32_bf16 v[84:87], v[174:177], v[238:241], v[84:87]
	v_mfma_f32_16x16x32_bf16 v[64:67], v[186:189], v[238:241], v[64:67]
	v_mfma_f32_16x16x32_bf16 v[132:135], v[182:185], v[218:221], v[132:135]
	v_mfma_f32_16x16x32_bf16 v[128:131], v[210:213], v[218:221], v[128:131]
	v_mfma_f32_16x16x32_bf16 v[116:119], v[182:185], v[226:229], v[116:119]
	v_mfma_f32_16x16x32_bf16 v[112:115], v[210:213], v[226:229], v[112:115]
	v_mfma_f32_16x16x32_bf16 v[100:103], v[182:185], v[234:237], v[100:103]
	v_mfma_f32_16x16x32_bf16 v[96:99], v[210:213], v[234:237], v[96:99]
	v_mfma_f32_16x16x32_bf16 v[84:87], v[182:185], v[242:245], v[84:87]
	v_mfma_f32_16x16x32_bf16 v[64:67], v[210:213], v[242:245], v[64:67]
	s_setprio 0
	s_barrier
	s_mov_b32 m0, s30
	s_add_u32 s58, s2, 0x40000
	s_addc_u32 s59, s3, 0
	ds_read_b128 v[214:217], v179 offset:16384
	ds_read_b128 v[218:221], v179 offset:17408
	ds_read_b128 v[222:225], v179 offset:18432
	ds_read_b128 v[226:229], v179 offset:19456
	ds_read_b128 v[230:233], v179 offset:20480
	ds_read_b128 v[234:237], v179 offset:21504
	ds_read_b128 v[238:241], v179 offset:22528
	ds_read_b128 v[242:245], v179 offset:23552
	global_load_lds_dwordx4 v166, s[2:3]
	s_mov_b32 m0, s31
	s_nop 0
	global_load_lds_dwordx4 v162, s[2:3]
	s_mov_b32 m0, s33
	s_nop 0
	global_load_lds_dwordx4 v166, s[58:59]
	s_mov_b32 m0, s34
	s_nop 0
	global_load_lds_dwordx4 v162, s[58:59]
	s_mov_b32 m0, s29
	s_nop 0
	global_load_lds_dwordx4 v168, s[4:5]
	s_mov_b32 m0, s35
	s_nop 0
	global_load_lds_dwordx4 v164, s[4:5]
	s_waitcnt vmcnt(8)
	s_waitcnt lgkmcnt(0)
	s_barrier
	s_setprio 1
	v_mfma_f32_16x16x32_bf16 v[60:63], v[68:71], v[214:217], v[60:63]
	v_mfma_f32_16x16x32_bf16 v[56:59], v[76:79], v[214:217], v[56:59]
	v_mfma_f32_16x16x32_bf16 v[44:47], v[68:71], v[222:225], v[44:47]
	v_mfma_f32_16x16x32_bf16 v[40:43], v[76:79], v[222:225], v[40:43]
	v_mfma_f32_16x16x32_bf16 v[28:31], v[68:71], v[230:233], v[28:31]
	v_mfma_f32_16x16x32_bf16 v[24:27], v[76:79], v[230:233], v[24:27]
	v_mfma_f32_16x16x32_bf16 v[12:15], v[68:71], v[238:241], v[12:15]
	v_mfma_f32_16x16x32_bf16 v[8:11], v[76:79], v[238:241], v[8:11]
	v_mfma_f32_16x16x32_bf16 v[60:63], v[72:75], v[218:221], v[60:63]
	v_mfma_f32_16x16x32_bf16 v[56:59], v[80:83], v[218:221], v[56:59]
	v_mfma_f32_16x16x32_bf16 v[44:47], v[72:75], v[226:229], v[44:47]
	v_mfma_f32_16x16x32_bf16 v[40:43], v[80:83], v[226:229], v[40:43]
	v_mfma_f32_16x16x32_bf16 v[28:31], v[72:75], v[234:237], v[28:31]
	v_mfma_f32_16x16x32_bf16 v[24:27], v[80:83], v[234:237], v[24:27]
	v_mfma_f32_16x16x32_bf16 v[12:15], v[72:75], v[242:245], v[12:15]
	v_mfma_f32_16x16x32_bf16 v[8:11], v[80:83], v[242:245], v[8:11]
	v_mfma_f32_16x16x32_bf16 v[52:55], v[174:177], v[214:217], v[52:55]
	v_mfma_f32_16x16x32_bf16 v[48:51], v[186:189], v[214:217], v[48:51]
	v_mfma_f32_16x16x32_bf16 v[36:39], v[174:177], v[222:225], v[36:39]
	v_mfma_f32_16x16x32_bf16 v[32:35], v[186:189], v[222:225], v[32:35]
	v_mfma_f32_16x16x32_bf16 v[20:23], v[174:177], v[230:233], v[20:23]
	v_mfma_f32_16x16x32_bf16 v[16:19], v[186:189], v[230:233], v[16:19]
	v_mfma_f32_16x16x32_bf16 v[4:7], v[174:177], v[238:241], v[4:7]
	v_mfma_f32_16x16x32_bf16 v[0:3], v[186:189], v[238:241], v[0:3]
	v_mfma_f32_16x16x32_bf16 v[52:55], v[182:185], v[218:221], v[52:55]
	v_mfma_f32_16x16x32_bf16 v[48:51], v[210:213], v[218:221], v[48:51]
	v_mfma_f32_16x16x32_bf16 v[36:39], v[182:185], v[226:229], v[36:39]
	v_mfma_f32_16x16x32_bf16 v[32:35], v[210:213], v[226:229], v[32:35]
	v_mfma_f32_16x16x32_bf16 v[20:23], v[182:185], v[234:237], v[20:23]
	v_mfma_f32_16x16x32_bf16 v[16:19], v[210:213], v[234:237], v[16:19]
	v_mfma_f32_16x16x32_bf16 v[4:7], v[182:185], v[242:245], v[4:7]
	v_mfma_f32_16x16x32_bf16 v[0:3], v[210:213], v[242:245], v[0:3]
	s_setprio 0
	s_barrier
; #define PG8_STAGE(bufoff, gbase, voff) do { _Pragma("unroll") for (int _i = 0; _i < 2; ++_i) \
;         __builtin_amdgcn_global_load_lds((const unsigned*)((const char*)(gbase) + (voff)[_i]), (PG8_LAS unsigned*)(lds + (bufoff) + ldsw + _i * 8192), 16, 0, 0); } while (0)
; #define PG8_LDA(dst, b, h) do { _Pragma("unroll") for (int m = 0; m < 4; ++m) _Pragma("unroll") for (int k = 0; k < 2; ++k) dst[m][k] = *(const PG8_LAS bf16x8*)(lds + PG8_SA(b, h) + aoff + m * 2048 + k * 1024); } while (0)
; #define PG8_LDB(dst, b, h) do { _Pragma("unroll") for (int n = 0; n < 2; ++n) _Pragma("unroll") for (int k = 0; k < 2; ++k) dst[n][k] = *(const PG8_LAS bf16x8*)(lds + PG8_SB(b, h) + boff + n * 2048 + k * 1024); } while (0)
; #define PG8_MMA(ai, bj, At, Bt) do { __builtin_amdgcn_s_setprio(1); _Pragma("unroll") for (int m = 0; m < 4; ++m) _Pragma("unroll") for (int n = 0; n < 2; ++n) _Pragma("unroll") for (int k = 0; k < 2; ++k) \
;         acc[ai][bj][m][n] = __builtin_amdgcn_mfma_f32_16x16x32_bf16(Bt[n][k], At[m][k], acc[ai][bj][m][n], 0, 0, 0); __builtin_amdgcn_s_setprio(0); } while (0)
; #define PG8_WAIT_V(n) asm volatile("s_waitcnt vmcnt(" #n ")" ::: "memory")
; #define PG8_WAIT_L(n) asm volatile("s_waitcnt lgkmcnt(" #n ")" ::: "memory")
; #define PG8_BAR __builtin_amdgcn_s_barrier()
; #define PG8_SCHED __builtin_amdgcn_sched_barrier(0)
; template <class Epi, class Sched, bool ALIGN_EPI = false, bool SP2 = false>
; __device__ __forceinline__ void gemm_phase(PG8_LAS unsigned char* lds, const Gemm g, const Sched& S, const Epi& E) {
;     ...
;             PG8_LDB(B0, 1, 0); PG8_LDB(B1, 1, 1); PG8_SCHED; PG8_LDA(At, 1, 0); PG8_STAGE(PG8_SA(0, 1), a2 + hstep, voffA);
;             PG8_WAIT_V(8); PG8_WAIT_L(0); PG8_BAR; PG8_MMA(0, 0, At, B0); PG8_MMA(0, 1, At, B1); PG8_BAR; PG8_SCHED;
;             PG8_LDA(At, 1, 1); PG8_STAGE(PG8_SB(1, 0), b3, voffB); PG8_STAGE(PG8_SB(1, 1), b3 + hstep, voffB); PG8_STAGE(PG8_SA(1, 0), a3, voffA);
;             PG8_WAIT_V(8); PG8_WAIT_L(0); PG8_BAR; PG8_MMA(1, 0, At, B0); PG8_MMA(1, 1, At, B1); PG8_BAR; PG8_SCHED;
	ds_read_b128 v[68:71], v254 offset:32768
	ds_read_b128 v[72:75], v254 offset:33792
	ds_read_b128 v[76:79], v254 offset:34816
	ds_read_b128 v[80:83], v254 offset:35840
	ds_read_b128 v[174:177], v254 offset:49152
	ds_read_b128 v[182:185], v254 offset:50176
	ds_read_b128 v[186:189], v254 offset:51200
	ds_read_b128 v[210:213], v254 offset:52224
	s_add_u32 s4, s4, 0x40000
	s_addc_u32 s5, s5, 0
	s_mov_b32 m0, s40
	ds_read_b128 v[214:217], v179 offset:32768
	ds_read_b128 v[218:221], v179 offset:33792
	ds_read_b128 v[222:225], v179 offset:34816
	ds_read_b128 v[226:229], v179 offset:35840
	ds_read_b128 v[230:233], v179 offset:36864
	ds_read_b128 v[234:237], v179 offset:37888
	ds_read_b128 v[238:241], v179 offset:38912
	ds_read_b128 v[242:245], v179 offset:39936
	global_load_lds_dwordx4 v168, s[4:5]
	s_mov_b32 m0, s41
	s_nop 0
	global_load_lds_dwordx4 v164, s[4:5]
	s_waitcnt vmcnt(8)
	s_waitcnt lgkmcnt(0)
	s_barrier
	s_setprio 1
	v_mfma_f32_16x16x32_bf16 v[140:143], v[68:71], v[214:217], v[140:143]
	v_mfma_f32_16x16x32_bf16 v[136:139], v[76:79], v[214:217], v[136:139]
	v_mfma_f32_16x16x32_bf16 v[124:127], v[68:71], v[222:225], v[124:127]
	v_mfma_f32_16x16x32_bf16 v[120:123], v[76:79], v[222:225], v[120:123]
	v_mfma_f32_16x16x32_bf16 v[108:111], v[68:71], v[230:233], v[108:111]
	v_mfma_f32_16x16x32_bf16 v[104:107], v[76:79], v[230:233], v[104:107]
	v_mfma_f32_16x16x32_bf16 v[92:95], v[68:71], v[238:241], v[92:95]
	v_mfma_f32_16x16x32_bf16 v[88:91], v[76:79], v[238:241], v[88:91]
	v_mfma_f32_16x16x32_bf16 v[140:143], v[72:75], v[218:221], v[140:143]
	v_mfma_f32_16x16x32_bf16 v[136:139], v[80:83], v[218:221], v[136:139]
	v_mfma_f32_16x16x32_bf16 v[124:127], v[72:75], v[226:229], v[124:127]
	v_mfma_f32_16x16x32_bf16 v[120:123], v[80:83], v[226:229], v[120:123]
	v_mfma_f32_16x16x32_bf16 v[108:111], v[72:75], v[234:237], v[108:111]
	v_mfma_f32_16x16x32_bf16 v[104:107], v[80:83], v[234:237], v[104:107]
	v_mfma_f32_16x16x32_bf16 v[92:95], v[72:75], v[242:245], v[92:95]
	v_mfma_f32_16x16x32_bf16 v[88:91], v[80:83], v[242:245], v[88:91]
	v_mfma_f32_16x16x32_bf16 v[132:135], v[174:177], v[214:217], v[132:135]
	v_mfma_f32_16x16x32_bf16 v[128:131], v[186:189], v[214:217], v[128:131]
	v_mfma_f32_16x16x32_bf16 v[116:119], v[174:177], v[222:225], v[116:119]
	v_mfma_f32_16x16x32_bf16 v[112:115], v[186:189], v[222:225], v[112:115]
	v_mfma_f32_16x16x32_bf16 v[100:103], v[174:177], v[230:233], v[100:103]
	v_mfma_f32_16x16x32_bf16 v[96:99], v[186:189], v[230:233], v[96:99]
	v_mfma_f32_16x16x32_bf16 v[84:87], v[174:177], v[238:241], v[84:87]
	v_mfma_f32_16x16x32_bf16 v[64:67], v[186:189], v[238:241], v[64:67]
	v_mfma_f32_16x16x32_bf16 v[132:135], v[182:185], v[218:221], v[132:135]
	v_mfma_f32_16x16x32_bf16 v[128:131], v[210:213], v[218:221], v[128:131]
	v_mfma_f32_16x16x32_bf16 v[116:119], v[182:185], v[226:229], v[116:119]
	v_mfma_f32_16x16x32_bf16 v[112:115], v[210:213], v[226:229], v[112:115]
	v_mfma_f32_16x16x32_bf16 v[100:103], v[182:185], v[234:237], v[100:103]
	v_mfma_f32_16x16x32_bf16 v[96:99], v[210:213], v[234:237], v[96:99]
	v_mfma_f32_16x16x32_bf16 v[84:87], v[182:185], v[242:245], v[84:87]
	v_mfma_f32_16x16x32_bf16 v[64:67], v[210:213], v[242:245], v[64:67]
	s_setprio 0
	s_barrier
	s_mov_b32 m0, s45
	s_add_u32 s2, s2, 0x40080
	s_addc_u32 s3, s3, 0
	ds_read_b128 v[214:217], v179 offset:49152
	ds_read_b128 v[218:221], v179 offset:50176
	ds_read_b128 v[222:225], v179 offset:51200
	ds_read_b128 v[226:229], v179 offset:52224
	ds_read_b128 v[230:233], v179 offset:53248
	ds_read_b128 v[234:237], v179 offset:54272
	ds_read_b128 v[238:241], v179 offset:55296
	ds_read_b128 v[242:245], v179 offset:56320
	s_add_u32 s98, s2, 0xfffc0000
	s_addc_u32 s99, s3, -1
	global_load_lds_dwordx4 v166, s[98:99]
	s_mov_b32 m0, s46
	s_nop 0
	global_load_lds_dwordx4 v162, s[98:99]
	s_mov_b32 m0, s49
	s_nop 0
	global_load_lds_dwordx4 v166, s[2:3]
	s_mov_b32 m0, s50
	s_nop 0
	global_load_lds_dwordx4 v162, s[2:3]
	s_mov_b32 m0, s47
	s_nop 0
	s_add_u32 s100, s4, 0xfffc0080
	s_addc_u32 s101, s5, -1
	global_load_lds_dwordx4 v168, s[100:101]
	s_mov_b32 m0, s48
	s_nop 0
	global_load_lds_dwordx4 v164, s[100:101]
	s_add_i32 s56, s56, 2
	s_add_u32 s0, s0, 0x100
	s_addc_u32 s1, s1, 0
	s_add_u32 s54, s54, 0x100
	s_addc_u32 s55, s55, 0
	s_cmp_gt_u32 s56, 13
	s_waitcnt vmcnt(8)
	s_waitcnt lgkmcnt(0)
	s_barrier
	s_setprio 1
	v_mfma_f32_16x16x32_bf16 v[60:63], v[68:71], v[214:217], v[60:63]
	v_mfma_f32_16x16x32_bf16 v[56:59], v[76:79], v[214:217], v[56:59]
	v_mfma_f32_16x16x32_bf16 v[44:47], v[68:71], v[222:225], v[44:47]
	v_mfma_f32_16x16x32_bf16 v[40:43], v[76:79], v[222:225], v[40:43]
	v_mfma_f32_16x16x32_bf16 v[28:31], v[68:71], v[230:233], v[28:31]
	v_mfma_f32_16x16x32_bf16 v[24:27], v[76:79], v[230:233], v[24:27]
	v_mfma_f32_16x16x32_bf16 v[12:15], v[68:71], v[238:241], v[12:15]
	v_mfma_f32_16x16x32_bf16 v[8:11], v[76:79], v[238:241], v[8:11]
	v_mfma_f32_16x16x32_bf16 v[60:63], v[72:75], v[218:221], v[60:63]
	v_mfma_f32_16x16x32_bf16 v[56:59], v[80:83], v[218:221], v[56:59]
	v_mfma_f32_16x16x32_bf16 v[44:47], v[72:75], v[226:229], v[44:47]
	v_mfma_f32_16x16x32_bf16 v[40:43], v[80:83], v[226:229], v[40:43]
	v_mfma_f32_16x16x32_bf16 v[28:31], v[72:75], v[234:237], v[28:31]
	v_mfma_f32_16x16x32_bf16 v[24:27], v[80:83], v[234:237], v[24:27]
	v_mfma_f32_16x16x32_bf16 v[12:15], v[72:75], v[242:245], v[12:15]
	v_mfma_f32_16x16x32_bf16 v[8:11], v[80:83], v[242:245], v[8:11]
	v_mfma_f32_16x16x32_bf16 v[52:55], v[174:177], v[214:217], v[52:55]
	v_mfma_f32_16x16x32_bf16 v[48:51], v[186:189], v[214:217], v[48:51]
	v_mfma_f32_16x16x32_bf16 v[36:39], v[174:177], v[222:225], v[36:39]
	v_mfma_f32_16x16x32_bf16 v[32:35], v[186:189], v[222:225], v[32:35]
	v_mfma_f32_16x16x32_bf16 v[20:23], v[174:177], v[230:233], v[20:23]
	v_mfma_f32_16x16x32_bf16 v[16:19], v[186:189], v[230:233], v[16:19]
	v_mfma_f32_16x16x32_bf16 v[4:7], v[174:177], v[238:241], v[4:7]
	v_mfma_f32_16x16x32_bf16 v[0:3], v[186:189], v[238:241], v[0:3]
	v_mfma_f32_16x16x32_bf16 v[52:55], v[182:185], v[218:221], v[52:55]
	v_mfma_f32_16x16x32_bf16 v[48:51], v[210:213], v[218:221], v[48:51]
	v_mfma_f32_16x16x32_bf16 v[36:39], v[182:185], v[226:229], v[36:39]
	v_mfma_f32_16x16x32_bf16 v[32:35], v[210:213], v[226:229], v[32:35]
	v_mfma_f32_16x16x32_bf16 v[20:23], v[182:185], v[234:237], v[20:23]
	v_mfma_f32_16x16x32_bf16 v[16:19], v[210:213], v[234:237], v[16:19]
	v_mfma_f32_16x16x32_bf16 v[4:7], v[182:185], v[242:245], v[4:7]
	v_mfma_f32_16x16x32_bf16 v[0:3], v[210:213], v[242:245], v[0:3]
	s_setprio 0
	s_barrier
	s_cbranch_scc0 .LBB0_327
	s_and_b64 vcc, exec, s[22:23]
	s_cbranch_vccz .LBB0_330
	s_barrier

; #define PG8_STAGE(bufoff, gbase, voff) do { _Pragma("unroll") for (int _i = 0; _i < 2; ++_i) \
;         __builtin_amdgcn_global_load_lds((const unsigned*)((const char*)(gbase) + (voff)[_i]), (PG8_LAS unsigned*)(lds + (bufoff) + ldsw + _i * 8192), 16, 0, 0); } while (0)
; #define PG8_LDA(dst, b, h) do { _Pragma("unroll") for (int m = 0; m < 4; ++m) _Pragma("unroll") for (int k = 0; k < 2; ++k) dst[m][k] = *(const PG8_LAS bf16x8*)(lds + PG8_SA(b, h) + aoff + m * 2048 + k * 1024); } while (0)
; #define PG8_LDB(dst, b, h) do { _Pragma("unroll") for (int n = 0; n < 2; ++n) _Pragma("unroll") for (int k = 0; k < 2; ++k) dst[n][k] = *(const PG8_LAS bf16x8*)(lds + PG8_SB(b, h) + boff + n * 2048 + k * 1024); } while (0)
; #define PG8_MMA(ai, bj, At, Bt) do { __builtin_amdgcn_s_setprio(1); _Pragma("unroll") for (int m = 0; m < 4; ++m) _Pragma("unroll") for (int n = 0; n < 2; ++n) _Pragma("unroll") for (int k = 0; k < 2; ++k) \
;         acc[ai][bj][m][n] = __builtin_amdgcn_mfma_f32_16x16x32_bf16(Bt[n][k], At[m][k], acc[ai][bj][m][n], 0, 0, 0); __builtin_amdgcn_s_setprio(0); } while (0)
; #define PG8_WAIT_V(n) asm volatile("s_waitcnt vmcnt(" #n ")" ::: "memory")
; #define PG8_WAIT_L(n) asm volatile("s_waitcnt lgkmcnt(" #n ")" ::: "memory")
; #define PG8_BAR __builtin_amdgcn_s_barrier()
; #define PG8_SCHED __builtin_amdgcn_sched_barrier(0)
; template <class Epi, class Sched, bool ALIGN_EPI = false, bool SP2 = false>
; __device__ __forceinline__ void gemm_phase(PG8_LAS unsigned char* lds, const Gemm g, const Sched& S, const Epi& E) {
;     ...
;     f32x4 acc[2][2][4][2];
; #pragma unroll
;     for (int a = 0; a < 2; ++a)
; #pragma unroll
;         for (int b = 0; b < 2; ++b)
; #pragma unroll
;             for (int m = 0; m < 4; ++m)
; #pragma unroll
;                 for (int n = 0; n < 2; ++n) acc[a][b][m][n] = (f32x4){0.f, 0.f, 0.f, 0.f};
;     ...
;             PG8_LDB(B0, 0, 0); PG8_LDB(B1, 0, 1); PG8_SCHED; PG8_LDA(At, 0, 0); PG8_STAGE(PG8_SA(1, 1), a1 + hstep, voffA);
;             PG8_WAIT_V(8); PG8_WAIT_L(0); PG8_BAR; PG8_MMA(0, 0, At, B0); PG8_MMA(0, 1, At, B1); PG8_BAR; PG8_SCHED;
;             PG8_LDA(At, 0, 1); PG8_STAGE(PG8_SB(0, 0), b2, voffB); PG8_STAGE(PG8_SB(0, 1), b2 + hstep, voffB); PG8_STAGE(PG8_SA(0, 0), a2, voffA);
;             PG8_WAIT_V(8); PG8_WAIT_L(0); PG8_BAR; PG8_MMA(1, 0, At, B0); PG8_MMA(1, 1, At, B1); PG8_BAR; PG8_SCHED;
.Lup_peel:
	ds_read_b128 v[140:143], v254
	ds_read_b128 v[168:171], v254 offset:1024
	ds_read_b128 v[172:175], v254 offset:2048
	ds_read_b128 v[176:179], v254 offset:3072
	ds_read_b128 v[180:183], v254 offset:16384
	ds_read_b128 v[184:187], v254 offset:17408
	ds_read_b128 v[188:191], v254 offset:18432
	ds_read_b128 v[210:213], v254 offset:19456
	s_add_u32 s16, s14, 0xfffc0080
	s_addc_u32 s17, s15, -1
	s_cmp_eq_u32 s53, 12
	s_cselect_b32 s19, s7, s17
	s_cselect_b32 s18, s49, s16
	s_cselect_b32 s17, s5, s52
	s_cselect_b32 s16, s50, s51
	s_mov_b32 m0, s43
	ds_read_b128 v[214:217], v165
	ds_read_b128 v[218:221], v165 offset:1024
	ds_read_b128 v[222:225], v165 offset:2048
	ds_read_b128 v[226:229], v165 offset:3072
	ds_read_b128 v[230:233], v165 offset:4096
	ds_read_b128 v[234:237], v165 offset:5120
	ds_read_b128 v[238:241], v165 offset:6144
	ds_read_b128 v[242:245], v165 offset:7168
	global_load_lds_dwordx4 v136, s[14:15]
	s_mov_b32 m0, s44
	s_nop 0
	global_load_lds_dwordx4 v138, s[14:15]
	s_waitcnt vmcnt(8)
	s_waitcnt lgkmcnt(0)
	s_barrier
	s_setprio 1
	v_mfma_f32_16x16x32_bf16 v[124:127], v[140:143], v[214:217], 0
	v_mfma_f32_16x16x32_bf16 v[116:119], v[172:175], v[214:217], 0
	v_mfma_f32_16x16x32_bf16 v[108:111], v[140:143], v[222:225], 0
	v_mfma_f32_16x16x32_bf16 v[100:103], v[172:175], v[222:225], 0
	v_mfma_f32_16x16x32_bf16 v[92:95], v[140:143], v[230:233], 0
	v_mfma_f32_16x16x32_bf16 v[84:87], v[172:175], v[230:233], 0
	v_mfma_f32_16x16x32_bf16 v[76:79], v[140:143], v[238:241], 0
	v_mfma_f32_16x16x32_bf16 v[68:71], v[172:175], v[238:241], 0
	v_mfma_f32_16x16x32_bf16 v[124:127], v[168:171], v[218:221], v[124:127]
	v_mfma_f32_16x16x32_bf16 v[116:119], v[176:179], v[218:221], v[116:119]
	v_mfma_f32_16x16x32_bf16 v[108:111], v[168:171], v[226:229], v[108:111]
	v_mfma_f32_16x16x32_bf16 v[100:103], v[176:179], v[226:229], v[100:103]
	v_mfma_f32_16x16x32_bf16 v[92:95], v[168:171], v[234:237], v[92:95]
	v_mfma_f32_16x16x32_bf16 v[84:87], v[176:179], v[234:237], v[84:87]
	v_mfma_f32_16x16x32_bf16 v[76:79], v[168:171], v[242:245], v[76:79]
	v_mfma_f32_16x16x32_bf16 v[68:71], v[176:179], v[242:245], v[68:71]
	v_mfma_f32_16x16x32_bf16 v[120:123], v[180:183], v[214:217], 0
	v_mfma_f32_16x16x32_bf16 v[112:115], v[188:191], v[214:217], 0
	v_mfma_f32_16x16x32_bf16 v[104:107], v[180:183], v[222:225], 0
	v_mfma_f32_16x16x32_bf16 v[96:99], v[188:191], v[222:225], 0
	v_mfma_f32_16x16x32_bf16 v[88:91], v[180:183], v[230:233], 0
	v_mfma_f32_16x16x32_bf16 v[80:83], v[188:191], v[230:233], 0
	v_mfma_f32_16x16x32_bf16 v[72:75], v[180:183], v[238:241], 0
	v_mfma_f32_16x16x32_bf16 v[64:67], v[188:191], v[238:241], 0
	v_mfma_f32_16x16x32_bf16 v[120:123], v[184:187], v[218:221], v[120:123]
	v_mfma_f32_16x16x32_bf16 v[112:115], v[210:213], v[218:221], v[112:115]
	v_mfma_f32_16x16x32_bf16 v[104:107], v[184:187], v[226:229], v[104:107]
	v_mfma_f32_16x16x32_bf16 v[96:99], v[210:213], v[226:229], v[96:99]
	v_mfma_f32_16x16x32_bf16 v[88:91], v[184:187], v[234:237], v[88:91]
	v_mfma_f32_16x16x32_bf16 v[80:83], v[210:213], v[234:237], v[80:83]
	v_mfma_f32_16x16x32_bf16 v[72:75], v[184:187], v[242:245], v[72:75]
	v_mfma_f32_16x16x32_bf16 v[64:67], v[210:213], v[242:245], v[64:67]
	s_setprio 0
	s_barrier
	s_mov_b32 m0, s27
	s_add_u32 s54, s16, 0x40000
	s_addc_u32 s55, s17, 0
	ds_read_b128 v[214:217], v165 offset:16384
	ds_read_b128 v[218:221], v165 offset:17408
	ds_read_b128 v[222:225], v165 offset:18432
	ds_read_b128 v[226:229], v165 offset:19456
	ds_read_b128 v[230:233], v165 offset:20480
	ds_read_b128 v[234:237], v165 offset:21504
	ds_read_b128 v[238:241], v165 offset:22528
	ds_read_b128 v[242:245], v165 offset:23552
	global_load_lds_dwordx4 v132, s[16:17]
	s_mov_b32 m0, s28
	s_nop 0
	global_load_lds_dwordx4 v128, s[16:17]
	s_mov_b32 m0, s29
	s_nop 0
	global_load_lds_dwordx4 v132, s[54:55]
	s_mov_b32 m0, s30
	s_nop 0
	global_load_lds_dwordx4 v128, s[54:55]
	s_mov_b32 m0, s22
	s_nop 0
	global_load_lds_dwordx4 v134, s[18:19]
	s_mov_b32 m0, s31
	s_nop 0
	global_load_lds_dwordx4 v130, s[18:19]
	s_waitcnt vmcnt(8)
	s_waitcnt lgkmcnt(0)
	s_barrier
	s_setprio 1
	v_mfma_f32_16x16x32_bf16 v[60:63], v[140:143], v[214:217], 0
	v_mfma_f32_16x16x32_bf16 v[52:55], v[172:175], v[214:217], 0
	v_mfma_f32_16x16x32_bf16 v[44:47], v[140:143], v[222:225], 0
	v_mfma_f32_16x16x32_bf16 v[36:39], v[172:175], v[222:225], 0
	v_mfma_f32_16x16x32_bf16 v[28:31], v[140:143], v[230:233], 0
	v_mfma_f32_16x16x32_bf16 v[20:23], v[172:175], v[230:233], 0
	v_mfma_f32_16x16x32_bf16 v[12:15], v[140:143], v[238:241], 0
	v_mfma_f32_16x16x32_bf16 v[4:7], v[172:175], v[238:241], 0
	v_mfma_f32_16x16x32_bf16 v[60:63], v[168:171], v[218:221], v[60:63]
	v_mfma_f32_16x16x32_bf16 v[52:55], v[176:179], v[218:221], v[52:55]
	v_mfma_f32_16x16x32_bf16 v[44:47], v[168:171], v[226:229], v[44:47]
	v_mfma_f32_16x16x32_bf16 v[36:39], v[176:179], v[226:229], v[36:39]
	v_mfma_f32_16x16x32_bf16 v[28:31], v[168:171], v[234:237], v[28:31]
	v_mfma_f32_16x16x32_bf16 v[20:23], v[176:179], v[234:237], v[20:23]
	v_mfma_f32_16x16x32_bf16 v[12:15], v[168:171], v[242:245], v[12:15]
	v_mfma_f32_16x16x32_bf16 v[4:7], v[176:179], v[242:245], v[4:7]
	v_mfma_f32_16x16x32_bf16 v[56:59], v[180:183], v[214:217], 0
	v_mfma_f32_16x16x32_bf16 v[48:51], v[188:191], v[214:217], 0
	v_mfma_f32_16x16x32_bf16 v[40:43], v[180:183], v[222:225], 0
	v_mfma_f32_16x16x32_bf16 v[32:35], v[188:191], v[222:225], 0
	v_mfma_f32_16x16x32_bf16 v[24:27], v[180:183], v[230:233], 0
	v_mfma_f32_16x16x32_bf16 v[16:19], v[188:191], v[230:233], 0
	v_mfma_f32_16x16x32_bf16 v[8:11], v[180:183], v[238:241], 0
	v_mfma_f32_16x16x32_bf16 v[0:3], v[188:191], v[238:241], 0
	v_mfma_f32_16x16x32_bf16 v[56:59], v[184:187], v[218:221], v[56:59]
	v_mfma_f32_16x16x32_bf16 v[48:51], v[210:213], v[218:221], v[48:51]
	v_mfma_f32_16x16x32_bf16 v[40:43], v[184:187], v[226:229], v[40:43]
	v_mfma_f32_16x16x32_bf16 v[32:35], v[210:213], v[226:229], v[32:35]
	v_mfma_f32_16x16x32_bf16 v[24:27], v[184:187], v[234:237], v[24:27]
	v_mfma_f32_16x16x32_bf16 v[16:19], v[210:213], v[234:237], v[16:19]
	v_mfma_f32_16x16x32_bf16 v[8:11], v[184:187], v[242:245], v[8:11]
	v_mfma_f32_16x16x32_bf16 v[0:3], v[210:213], v[242:245], v[0:3]
	s_setprio 0
	s_barrier
; #define PG8_STAGE(bufoff, gbase, voff) do { _Pragma("unroll") for (int _i = 0; _i < 2; ++_i) \
;         __builtin_amdgcn_global_load_lds((const unsigned*)((const char*)(gbase) + (voff)[_i]), (PG8_LAS unsigned*)(lds + (bufoff) + ldsw + _i * 8192), 16, 0, 0); } while (0)
; #define PG8_LDA(dst, b, h) do { _Pragma("unroll") for (int m = 0; m < 4; ++m) _Pragma("unroll") for (int k = 0; k < 2; ++k) dst[m][k] = *(const PG8_LAS bf16x8*)(lds + PG8_SA(b, h) + aoff + m * 2048 + k * 1024); } while (0)
; #define PG8_LDB(dst, b, h) do { _Pragma("unroll") for (int n = 0; n < 2; ++n) _Pragma("unroll") for (int k = 0; k < 2; ++k) dst[n][k] = *(const PG8_LAS bf16x8*)(lds + PG8_SB(b, h) + boff + n * 2048 + k * 1024); } while (0)
; #define PG8_MMA(ai, bj, At, Bt) do { __builtin_amdgcn_s_setprio(1); _Pragma("unroll") for (int m = 0; m < 4; ++m) _Pragma("unroll") for (int n = 0; n < 2; ++n) _Pragma("unroll") for (int k = 0; k < 2; ++k) \
;         acc[ai][bj][m][n] = __builtin_amdgcn_mfma_f32_16x16x32_bf16(Bt[n][k], At[m][k], acc[ai][bj][m][n], 0, 0, 0); __builtin_amdgcn_s_setprio(0); } while (0)
; #define PG8_WAIT_V(n) asm volatile("s_waitcnt vmcnt(" #n ")" ::: "memory")
; #define PG8_WAIT_L(n) asm volatile("s_waitcnt lgkmcnt(" #n ")" ::: "memory")
; #define PG8_BAR __builtin_amdgcn_s_barrier()
; #define PG8_SCHED __builtin_amdgcn_sched_barrier(0)
; template <class Epi, class Sched, bool ALIGN_EPI = false, bool SP2 = false>
; __device__ __forceinline__ void gemm_phase(PG8_LAS unsigned char* lds, const Gemm g, const Sched& S, const Epi& E) {
;     ...
;             PG8_LDB(B0, 1, 0); PG8_LDB(B1, 1, 1); PG8_SCHED; PG8_LDA(At, 1, 0); PG8_STAGE(PG8_SA(0, 1), a2 + hstep, voffA);
;             PG8_WAIT_V(8); PG8_WAIT_L(0); PG8_BAR; PG8_MMA(0, 0, At, B0); PG8_MMA(0, 1, At, B1); PG8_BAR; PG8_SCHED;
;             PG8_LDA(At, 1, 1); PG8_STAGE(PG8_SB(1, 0), b3, voffB); PG8_STAGE(PG8_SB(1, 1), b3 + hstep, voffB); PG8_STAGE(PG8_SA(1, 0), a3, voffA);
;             PG8_WAIT_V(8); PG8_WAIT_L(0); PG8_BAR; PG8_MMA(1, 0, At, B0); PG8_MMA(1, 1, At, B1); PG8_BAR; PG8_SCHED;
	ds_read_b128 v[140:143], v254 offset:32768
	ds_read_b128 v[168:171], v254 offset:33792
	ds_read_b128 v[172:175], v254 offset:34816
	ds_read_b128 v[176:179], v254 offset:35840
	ds_read_b128 v[180:183], v254 offset:49152
	ds_read_b128 v[184:187], v254 offset:50176
	ds_read_b128 v[188:191], v254 offset:51200
	ds_read_b128 v[210:213], v254 offset:52224
	s_add_u32 s18, s18, 0x40000
	s_addc_u32 s19, s19, 0
	s_mov_b32 m0, s33
	ds_read_b128 v[214:217], v165 offset:32768
	ds_read_b128 v[218:221], v165 offset:33792
	ds_read_b128 v[222:225], v165 offset:34816
	ds_read_b128 v[226:229], v165 offset:35840
	ds_read_b128 v[230:233], v165 offset:36864
	ds_read_b128 v[234:237], v165 offset:37888
	ds_read_b128 v[238:241], v165 offset:38912
	ds_read_b128 v[242:245], v165 offset:39936
	global_load_lds_dwordx4 v134, s[18:19]
	s_mov_b32 m0, s34
	s_nop 0
	global_load_lds_dwordx4 v130, s[18:19]
	s_waitcnt vmcnt(8)
	s_waitcnt lgkmcnt(0)
	s_barrier
	s_setprio 1
	v_mfma_f32_16x16x32_bf16 v[124:127], v[140:143], v[214:217], v[124:127]
	v_mfma_f32_16x16x32_bf16 v[116:119], v[172:175], v[214:217], v[116:119]
	v_mfma_f32_16x16x32_bf16 v[108:111], v[140:143], v[222:225], v[108:111]
	v_mfma_f32_16x16x32_bf16 v[100:103], v[172:175], v[222:225], v[100:103]
	v_mfma_f32_16x16x32_bf16 v[92:95], v[140:143], v[230:233], v[92:95]
	v_mfma_f32_16x16x32_bf16 v[84:87], v[172:175], v[230:233], v[84:87]
	v_mfma_f32_16x16x32_bf16 v[76:79], v[140:143], v[238:241], v[76:79]
	v_mfma_f32_16x16x32_bf16 v[68:71], v[172:175], v[238:241], v[68:71]
	v_mfma_f32_16x16x32_bf16 v[124:127], v[168:171], v[218:221], v[124:127]
	v_mfma_f32_16x16x32_bf16 v[116:119], v[176:179], v[218:221], v[116:119]
	v_mfma_f32_16x16x32_bf16 v[108:111], v[168:171], v[226:229], v[108:111]
	v_mfma_f32_16x16x32_bf16 v[100:103], v[176:179], v[226:229], v[100:103]
	v_mfma_f32_16x16x32_bf16 v[92:95], v[168:171], v[234:237], v[92:95]
	v_mfma_f32_16x16x32_bf16 v[84:87], v[176:179], v[234:237], v[84:87]
	v_mfma_f32_16x16x32_bf16 v[76:79], v[168:171], v[242:245], v[76:79]
	v_mfma_f32_16x16x32_bf16 v[68:71], v[176:179], v[242:245], v[68:71]
	v_mfma_f32_16x16x32_bf16 v[120:123], v[180:183], v[214:217], v[120:123]
	v_mfma_f32_16x16x32_bf16 v[112:115], v[188:191], v[214:217], v[112:115]
	v_mfma_f32_16x16x32_bf16 v[104:107], v[180:183], v[222:225], v[104:107]
	v_mfma_f32_16x16x32_bf16 v[96:99], v[188:191], v[222:225], v[96:99]
	v_mfma_f32_16x16x32_bf16 v[88:91], v[180:183], v[230:233], v[88:91]
	v_mfma_f32_16x16x32_bf16 v[80:83], v[188:191], v[230:233], v[80:83]
	v_mfma_f32_16x16x32_bf16 v[72:75], v[180:183], v[238:241], v[72:75]
	v_mfma_f32_16x16x32_bf16 v[64:67], v[188:191], v[238:241], v[64:67]
	v_mfma_f32_16x16x32_bf16 v[120:123], v[184:187], v[218:221], v[120:123]
	v_mfma_f32_16x16x32_bf16 v[112:115], v[210:213], v[218:221], v[112:115]
	v_mfma_f32_16x16x32_bf16 v[104:107], v[184:187], v[226:229], v[104:107]
	v_mfma_f32_16x16x32_bf16 v[96:99], v[210:213], v[226:229], v[96:99]
	v_mfma_f32_16x16x32_bf16 v[88:91], v[184:187], v[234:237], v[88:91]
	v_mfma_f32_16x16x32_bf16 v[80:83], v[210:213], v[234:237], v[80:83]
	v_mfma_f32_16x16x32_bf16 v[72:75], v[184:187], v[242:245], v[72:75]
	v_mfma_f32_16x16x32_bf16 v[64:67], v[210:213], v[242:245], v[64:67]
	s_setprio 0
	s_barrier
	s_mov_b32 m0, s37
	s_add_u32 s16, s16, 0x40080
	s_addc_u32 s17, s17, 0
	ds_read_b128 v[214:217], v165 offset:49152
	ds_read_b128 v[218:221], v165 offset:50176
	ds_read_b128 v[222:225], v165 offset:51200
	ds_read_b128 v[226:229], v165 offset:52224
	ds_read_b128 v[230:233], v165 offset:53248
	ds_read_b128 v[234:237], v165 offset:54272
	ds_read_b128 v[238:241], v165 offset:55296
	ds_read_b128 v[242:245], v165 offset:56320
	s_add_u32 s98, s16, 0xfffc0000
	s_addc_u32 s99, s17, -1
	global_load_lds_dwordx4 v132, s[98:99]
	s_mov_b32 m0, s38
	s_nop 0
	global_load_lds_dwordx4 v128, s[98:99]
	s_mov_b32 m0, s41
	s_nop 0
	global_load_lds_dwordx4 v132, s[16:17]
	s_mov_b32 m0, s42
	s_nop 0
	global_load_lds_dwordx4 v128, s[16:17]
	s_mov_b32 m0, s39
	s_nop 0
	s_add_u32 s100, s18, 0xfffc0080
	s_addc_u32 s101, s19, -1
	global_load_lds_dwordx4 v134, s[100:101]
	s_mov_b32 m0, s40
	s_nop 0
	global_load_lds_dwordx4 v130, s[100:101]
	s_add_i32 s53, s53, 2
	s_add_u32 s14, s14, 0x100
	s_addc_u32 s15, s15, 0
	s_add_u32 s51, s51, 0x100
	s_addc_u32 s52, s52, 0
	s_cmp_gt_u32 s53, 13
	s_waitcnt vmcnt(8)
	s_waitcnt lgkmcnt(0)
	s_barrier
	s_setprio 1
	v_mfma_f32_16x16x32_bf16 v[60:63], v[140:143], v[214:217], v[60:63]
	v_mfma_f32_16x16x32_bf16 v[52:55], v[172:175], v[214:217], v[52:55]
	v_mfma_f32_16x16x32_bf16 v[44:47], v[140:143], v[222:225], v[44:47]
	v_mfma_f32_16x16x32_bf16 v[36:39], v[172:175], v[222:225], v[36:39]
	v_mfma_f32_16x16x32_bf16 v[28:31], v[140:143], v[230:233], v[28:31]
	v_mfma_f32_16x16x32_bf16 v[20:23], v[172:175], v[230:233], v[20:23]
	v_mfma_f32_16x16x32_bf16 v[12:15], v[140:143], v[238:241], v[12:15]
	v_mfma_f32_16x16x32_bf16 v[4:7], v[172:175], v[238:241], v[4:7]
	v_mfma_f32_16x16x32_bf16 v[60:63], v[168:171], v[218:221], v[60:63]
	v_mfma_f32_16x16x32_bf16 v[52:55], v[176:179], v[218:221], v[52:55]
	v_mfma_f32_16x16x32_bf16 v[44:47], v[168:171], v[226:229], v[44:47]
	v_mfma_f32_16x16x32_bf16 v[36:39], v[176:179], v[226:229], v[36:39]
	v_mfma_f32_16x16x32_bf16 v[28:31], v[168:171], v[234:237], v[28:31]
	v_mfma_f32_16x16x32_bf16 v[20:23], v[176:179], v[234:237], v[20:23]
	v_mfma_f32_16x16x32_bf16 v[12:15], v[168:171], v[242:245], v[12:15]
	v_mfma_f32_16x16x32_bf16 v[4:7], v[176:179], v[242:245], v[4:7]
	v_mfma_f32_16x16x32_bf16 v[56:59], v[180:183], v[214:217], v[56:59]
	v_mfma_f32_16x16x32_bf16 v[48:51], v[188:191], v[214:217], v[48:51]
	v_mfma_f32_16x16x32_bf16 v[40:43], v[180:183], v[222:225], v[40:43]
	v_mfma_f32_16x16x32_bf16 v[32:35], v[188:191], v[222:225], v[32:35]
	v_mfma_f32_16x16x32_bf16 v[24:27], v[180:183], v[230:233], v[24:27]
	v_mfma_f32_16x16x32_bf16 v[16:19], v[188:191], v[230:233], v[16:19]
	v_mfma_f32_16x16x32_bf16 v[8:11], v[180:183], v[238:241], v[8:11]
	v_mfma_f32_16x16x32_bf16 v[0:3], v[188:191], v[238:241], v[0:3]
	v_mfma_f32_16x16x32_bf16 v[56:59], v[184:187], v[218:221], v[56:59]
	v_mfma_f32_16x16x32_bf16 v[48:51], v[210:213], v[218:221], v[48:51]
	v_mfma_f32_16x16x32_bf16 v[40:43], v[184:187], v[226:229], v[40:43]
	v_mfma_f32_16x16x32_bf16 v[32:35], v[210:213], v[226:229], v[32:35]
	v_mfma_f32_16x16x32_bf16 v[24:27], v[184:187], v[234:237], v[24:27]
	v_mfma_f32_16x16x32_bf16 v[16:19], v[210:213], v[234:237], v[16:19]
	v_mfma_f32_16x16x32_bf16 v[8:11], v[184:187], v[242:245], v[8:11]
	v_mfma_f32_16x16x32_bf16 v[0:3], v[210:213], v[242:245], v[0:3]
	s_setprio 0
	s_barrier
; #define PG8_STAGE(bufoff, gbase, voff) do { _Pragma("unroll") for (int _i = 0; _i < 2; ++_i) \
;         __builtin_amdgcn_global_load_lds((const unsigned*)((const char*)(gbase) + (voff)[_i]), (PG8_LAS unsigned*)(lds + (bufoff) + ldsw + _i * 8192), 16, 0, 0); } while (0)
; #define PG8_LDA(dst, b, h) do { _Pragma("unroll") for (int m = 0; m < 4; ++m) _Pragma("unroll") for (int k = 0; k < 2; ++k) dst[m][k] = *(const PG8_LAS bf16x8*)(lds + PG8_SA(b, h) + aoff + m * 2048 + k * 1024); } while (0)
; #define PG8_LDB(dst, b, h) do { _Pragma("unroll") for (int n = 0; n < 2; ++n) _Pragma("unroll") for (int k = 0; k < 2; ++k) dst[n][k] = *(const PG8_LAS bf16x8*)(lds + PG8_SB(b, h) + boff + n * 2048 + k * 1024); } while (0)
; #define PG8_MMA(ai, bj, At, Bt) do { __builtin_amdgcn_s_setprio(1); _Pragma("unroll") for (int m = 0; m < 4; ++m) _Pragma("unroll") for (int n = 0; n < 2; ++n) _Pragma("unroll") for (int k = 0; k < 2; ++k) \
;         acc[ai][bj][m][n] = __builtin_amdgcn_mfma_f32_16x16x32_bf16(Bt[n][k], At[m][k], acc[ai][bj][m][n], 0, 0, 0); __builtin_amdgcn_s_setprio(0); } while (0)
; #define PG8_WAIT_V(n) asm volatile("s_waitcnt vmcnt(" #n ")" ::: "memory")
; #define PG8_BAR __builtin_amdgcn_s_barrier()
; template <class Epi, class Sched, bool ALIGN_EPI = false, bool SP2 = false>
; __device__ __forceinline__ void gemm_phase(PG8_LAS unsigned char* lds, const Gemm g, const Sched& S, const Epi& E) {
;     ...
;         for (int t = 0; t < nt; t += 2) {
;             const bool last = (t == nt - 2);
;             const char* a1 = cA + (size_t)(t + 1) * kstep;
;             const char* a2 = last ? nA : cA + (size_t)(t + 2) * kstep; const char* b2 = last ? nB : cB + (size_t)(t + 2) * kstep;
;             const char* a3 = a2 + kstep; const char* b3 = b2 + kstep;
;             if (last && has_next) S.a_ready(nxt);
;             if constexpr (SP2) {
;             PG8_LDB(B0, 0, 0); PG8_LDB(B1, 0, 1); PG8_SCHED; PG8_LDA(At, 0, 0); PG8_STAGE(PG8_SA(1, 1), a1 + hstep, voffA);
;             PG8_WAIT_V(8); PG8_WAIT_L(0); PG8_BAR; PG8_MMA(0, 0, At, B0); PG8_MMA(0, 1, At, B1); PG8_BAR; PG8_SCHED;
;             PG8_LDA(At, 0, 1); PG8_STAGE(PG8_SB(0, 0), b2, voffB); PG8_STAGE(PG8_SB(0, 1), b2 + hstep, voffB); PG8_STAGE(PG8_SA(0, 0), a2, voffA);
;             PG8_WAIT_V(8); PG8_WAIT_L(0); PG8_BAR; PG8_MMA(1, 0, At, B0); PG8_MMA(1, 1, At, B1); PG8_BAR; PG8_SCHED;
.LBB0_446:
	ds_read_b128 v[140:143], v254
	ds_read_b128 v[168:171], v254 offset:1024
	ds_read_b128 v[172:175], v254 offset:2048
	ds_read_b128 v[176:179], v254 offset:3072
	ds_read_b128 v[180:183], v254 offset:16384
	ds_read_b128 v[184:187], v254 offset:17408
	ds_read_b128 v[188:191], v254 offset:18432
	ds_read_b128 v[210:213], v254 offset:19456
	s_add_u32 s16, s14, 0xfffc0080
	s_addc_u32 s17, s15, -1
	s_cmp_eq_u32 s53, 12
	s_cselect_b32 s19, s7, s17
	s_cselect_b32 s18, s49, s16
	s_cselect_b32 s17, s5, s52
	s_cselect_b32 s16, s50, s51
	s_mov_b32 m0, s43
	ds_read_b128 v[214:217], v165
	ds_read_b128 v[218:221], v165 offset:1024
	ds_read_b128 v[222:225], v165 offset:2048
	ds_read_b128 v[226:229], v165 offset:3072
	ds_read_b128 v[230:233], v165 offset:4096
	ds_read_b128 v[234:237], v165 offset:5120
	ds_read_b128 v[238:241], v165 offset:6144
	ds_read_b128 v[242:245], v165 offset:7168
	global_load_lds_dwordx4 v136, s[14:15]
	s_mov_b32 m0, s44
	s_nop 0
	global_load_lds_dwordx4 v138, s[14:15]
	s_waitcnt vmcnt(8)
	s_waitcnt lgkmcnt(0)
	s_barrier
	s_setprio 1
	v_mfma_f32_16x16x32_bf16 v[124:127], v[140:143], v[214:217], v[124:127]
	v_mfma_f32_16x16x32_bf16 v[116:119], v[172:175], v[214:217], v[116:119]
	v_mfma_f32_16x16x32_bf16 v[108:111], v[140:143], v[222:225], v[108:111]
	v_mfma_f32_16x16x32_bf16 v[100:103], v[172:175], v[222:225], v[100:103]
	v_mfma_f32_16x16x32_bf16 v[92:95], v[140:143], v[230:233], v[92:95]
	v_mfma_f32_16x16x32_bf16 v[84:87], v[172:175], v[230:233], v[84:87]
	v_mfma_f32_16x16x32_bf16 v[76:79], v[140:143], v[238:241], v[76:79]
	v_mfma_f32_16x16x32_bf16 v[68:71], v[172:175], v[238:241], v[68:71]
	v_mfma_f32_16x16x32_bf16 v[124:127], v[168:171], v[218:221], v[124:127]
	v_mfma_f32_16x16x32_bf16 v[116:119], v[176:179], v[218:221], v[116:119]
	v_mfma_f32_16x16x32_bf16 v[108:111], v[168:171], v[226:229], v[108:111]
	v_mfma_f32_16x16x32_bf16 v[100:103], v[176:179], v[226:229], v[100:103]
	v_mfma_f32_16x16x32_bf16 v[92:95], v[168:171], v[234:237], v[92:95]
	v_mfma_f32_16x16x32_bf16 v[84:87], v[176:179], v[234:237], v[84:87]
	v_mfma_f32_16x16x32_bf16 v[76:79], v[168:171], v[242:245], v[76:79]
	v_mfma_f32_16x16x32_bf16 v[68:71], v[176:179], v[242:245], v[68:71]
	v_mfma_f32_16x16x32_bf16 v[120:123], v[180:183], v[214:217], v[120:123]
	v_mfma_f32_16x16x32_bf16 v[112:115], v[188:191], v[214:217], v[112:115]
	v_mfma_f32_16x16x32_bf16 v[104:107], v[180:183], v[222:225], v[104:107]
	v_mfma_f32_16x16x32_bf16 v[96:99], v[188:191], v[222:225], v[96:99]
	v_mfma_f32_16x16x32_bf16 v[88:91], v[180:183], v[230:233], v[88:91]
	v_mfma_f32_16x16x32_bf16 v[80:83], v[188:191], v[230:233], v[80:83]
	v_mfma_f32_16x16x32_bf16 v[72:75], v[180:183], v[238:241], v[72:75]
	v_mfma_f32_16x16x32_bf16 v[64:67], v[188:191], v[238:241], v[64:67]
	v_mfma_f32_16x16x32_bf16 v[120:123], v[184:187], v[218:221], v[120:123]
	v_mfma_f32_16x16x32_bf16 v[112:115], v[210:213], v[218:221], v[112:115]
	v_mfma_f32_16x16x32_bf16 v[104:107], v[184:187], v[226:229], v[104:107]
	v_mfma_f32_16x16x32_bf16 v[96:99], v[210:213], v[226:229], v[96:99]
	v_mfma_f32_16x16x32_bf16 v[88:91], v[184:187], v[234:237], v[88:91]
	v_mfma_f32_16x16x32_bf16 v[80:83], v[210:213], v[234:237], v[80:83]
	v_mfma_f32_16x16x32_bf16 v[72:75], v[184:187], v[242:245], v[72:75]
	v_mfma_f32_16x16x32_bf16 v[64:67], v[210:213], v[242:245], v[64:67]
	s_setprio 0
	s_barrier
	s_mov_b32 m0, s27
	s_add_u32 s54, s16, 0x40000
	s_addc_u32 s55, s17, 0
	ds_read_b128 v[214:217], v165 offset:16384
	ds_read_b128 v[218:221], v165 offset:17408
	ds_read_b128 v[222:225], v165 offset:18432
	ds_read_b128 v[226:229], v165 offset:19456
	ds_read_b128 v[230:233], v165 offset:20480
	ds_read_b128 v[234:237], v165 offset:21504
	ds_read_b128 v[238:241], v165 offset:22528
	ds_read_b128 v[242:245], v165 offset:23552
	global_load_lds_dwordx4 v132, s[16:17]
	s_mov_b32 m0, s28
	s_nop 0
	global_load_lds_dwordx4 v128, s[16:17]
	s_mov_b32 m0, s29
	s_nop 0
	global_load_lds_dwordx4 v132, s[54:55]
	s_mov_b32 m0, s30
	s_nop 0
	global_load_lds_dwordx4 v128, s[54:55]
	s_mov_b32 m0, s22
	s_nop 0
	global_load_lds_dwordx4 v134, s[18:19]
	s_mov_b32 m0, s31
	s_nop 0
	global_load_lds_dwordx4 v130, s[18:19]
	s_waitcnt vmcnt(8)
	s_waitcnt lgkmcnt(0)
	s_barrier
	s_setprio 1
	v_mfma_f32_16x16x32_bf16 v[60:63], v[140:143], v[214:217], v[60:63]
	v_mfma_f32_16x16x32_bf16 v[52:55], v[172:175], v[214:217], v[52:55]
	v_mfma_f32_16x16x32_bf16 v[44:47], v[140:143], v[222:225], v[44:47]
	v_mfma_f32_16x16x32_bf16 v[36:39], v[172:175], v[222:225], v[36:39]
	v_mfma_f32_16x16x32_bf16 v[28:31], v[140:143], v[230:233], v[28:31]
	v_mfma_f32_16x16x32_bf16 v[20:23], v[172:175], v[230:233], v[20:23]
	v_mfma_f32_16x16x32_bf16 v[12:15], v[140:143], v[238:241], v[12:15]
	v_mfma_f32_16x16x32_bf16 v[4:7], v[172:175], v[238:241], v[4:7]
	v_mfma_f32_16x16x32_bf16 v[60:63], v[168:171], v[218:221], v[60:63]
	v_mfma_f32_16x16x32_bf16 v[52:55], v[176:179], v[218:221], v[52:55]
	v_mfma_f32_16x16x32_bf16 v[44:47], v[168:171], v[226:229], v[44:47]
	v_mfma_f32_16x16x32_bf16 v[36:39], v[176:179], v[226:229], v[36:39]
	v_mfma_f32_16x16x32_bf16 v[28:31], v[168:171], v[234:237], v[28:31]
	v_mfma_f32_16x16x32_bf16 v[20:23], v[176:179], v[234:237], v[20:23]
	v_mfma_f32_16x16x32_bf16 v[12:15], v[168:171], v[242:245], v[12:15]
	v_mfma_f32_16x16x32_bf16 v[4:7], v[176:179], v[242:245], v[4:7]
	v_mfma_f32_16x16x32_bf16 v[56:59], v[180:183], v[214:217], v[56:59]
	v_mfma_f32_16x16x32_bf16 v[48:51], v[188:191], v[214:217], v[48:51]
	v_mfma_f32_16x16x32_bf16 v[40:43], v[180:183], v[222:225], v[40:43]
	v_mfma_f32_16x16x32_bf16 v[32:35], v[188:191], v[222:225], v[32:35]
	v_mfma_f32_16x16x32_bf16 v[24:27], v[180:183], v[230:233], v[24:27]
	v_mfma_f32_16x16x32_bf16 v[16:19], v[188:191], v[230:233], v[16:19]
	v_mfma_f32_16x16x32_bf16 v[8:11], v[180:183], v[238:241], v[8:11]
	v_mfma_f32_16x16x32_bf16 v[0:3], v[188:191], v[238:241], v[0:3]
	v_mfma_f32_16x16x32_bf16 v[56:59], v[184:187], v[218:221], v[56:59]
	v_mfma_f32_16x16x32_bf16 v[48:51], v[210:213], v[218:221], v[48:51]
	v_mfma_f32_16x16x32_bf16 v[40:43], v[184:187], v[226:229], v[40:43]
	v_mfma_f32_16x16x32_bf16 v[32:35], v[210:213], v[226:229], v[32:35]
	v_mfma_f32_16x16x32_bf16 v[24:27], v[184:187], v[234:237], v[24:27]
	v_mfma_f32_16x16x32_bf16 v[16:19], v[210:213], v[234:237], v[16:19]
	v_mfma_f32_16x16x32_bf16 v[8:11], v[184:187], v[242:245], v[8:11]
	v_mfma_f32_16x16x32_bf16 v[0:3], v[210:213], v[242:245], v[0:3]
	s_setprio 0
	s_barrier
; #define PG8_STAGE(bufoff, gbase, voff) do { _Pragma("unroll") for (int _i = 0; _i < 2; ++_i) \
;         __builtin_amdgcn_global_load_lds((const unsigned*)((const char*)(gbase) + (voff)[_i]), (PG8_LAS unsigned*)(lds + (bufoff) + ldsw + _i * 8192), 16, 0, 0); } while (0)
; #define PG8_LDA(dst, b, h) do { _Pragma("unroll") for (int m = 0; m < 4; ++m) _Pragma("unroll") for (int k = 0; k < 2; ++k) dst[m][k] = *(const PG8_LAS bf16x8*)(lds + PG8_SA(b, h) + aoff + m * 2048 + k * 1024); } while (0)
; #define PG8_LDB(dst, b, h) do { _Pragma("unroll") for (int n = 0; n < 2; ++n) _Pragma("unroll") for (int k = 0; k < 2; ++k) dst[n][k] = *(const PG8_LAS bf16x8*)(lds + PG8_SB(b, h) + boff + n * 2048 + k * 1024); } while (0)
; #define PG8_MMA(ai, bj, At, Bt) do { __builtin_amdgcn_s_setprio(1); _Pragma("unroll") for (int m = 0; m < 4; ++m) _Pragma("unroll") for (int n = 0; n < 2; ++n) _Pragma("unroll") for (int k = 0; k < 2; ++k) \
;         acc[ai][bj][m][n] = __builtin_amdgcn_mfma_f32_16x16x32_bf16(Bt[n][k], At[m][k], acc[ai][bj][m][n], 0, 0, 0); __builtin_amdgcn_s_setprio(0); } while (0)
; #define PG8_WAIT_V(n) asm volatile("s_waitcnt vmcnt(" #n ")" ::: "memory")
; #define PG8_WAIT_L(n) asm volatile("s_waitcnt lgkmcnt(" #n ")" ::: "memory")
; #define PG8_BAR __builtin_amdgcn_s_barrier()
; #define PG8_SCHED __builtin_amdgcn_sched_barrier(0)
; template <class Epi, class Sched, bool ALIGN_EPI = false, bool SP2 = false>
; __device__ __forceinline__ void gemm_phase(PG8_LAS unsigned char* lds, const Gemm g, const Sched& S, const Epi& E) {
;     ...
;             PG8_LDB(B0, 1, 0); PG8_LDB(B1, 1, 1); PG8_SCHED; PG8_LDA(At, 1, 0); PG8_STAGE(PG8_SA(0, 1), a2 + hstep, voffA);
;             PG8_WAIT_V(8); PG8_WAIT_L(0); PG8_BAR; PG8_MMA(0, 0, At, B0); PG8_MMA(0, 1, At, B1); PG8_BAR; PG8_SCHED;
;             PG8_LDA(At, 1, 1); PG8_STAGE(PG8_SB(1, 0), b3, voffB); PG8_STAGE(PG8_SB(1, 1), b3 + hstep, voffB); PG8_STAGE(PG8_SA(1, 0), a3, voffA);
;             PG8_WAIT_V(8); PG8_WAIT_L(0); PG8_BAR; PG8_MMA(1, 0, At, B0); PG8_MMA(1, 1, At, B1); PG8_BAR; PG8_SCHED;
	ds_read_b128 v[140:143], v254 offset:32768
	ds_read_b128 v[168:171], v254 offset:33792
	ds_read_b128 v[172:175], v254 offset:34816
	ds_read_b128 v[176:179], v254 offset:35840
	ds_read_b128 v[180:183], v254 offset:49152
	ds_read_b128 v[184:187], v254 offset:50176
	ds_read_b128 v[188:191], v254 offset:51200
	ds_read_b128 v[210:213], v254 offset:52224
	s_add_u32 s18, s18, 0x40000
	s_addc_u32 s19, s19, 0
	s_mov_b32 m0, s33
	ds_read_b128 v[214:217], v165 offset:32768
	ds_read_b128 v[218:221], v165 offset:33792
	ds_read_b128 v[222:225], v165 offset:34816
	ds_read_b128 v[226:229], v165 offset:35840
	ds_read_b128 v[230:233], v165 offset:36864
	ds_read_b128 v[234:237], v165 offset:37888
	ds_read_b128 v[238:241], v165 offset:38912
	ds_read_b128 v[242:245], v165 offset:39936
	global_load_lds_dwordx4 v134, s[18:19]
	s_mov_b32 m0, s34
	s_nop 0
	global_load_lds_dwordx4 v130, s[18:19]
	s_waitcnt vmcnt(8)
	s_waitcnt lgkmcnt(0)
	s_barrier
	s_setprio 1
	v_mfma_f32_16x16x32_bf16 v[124:127], v[140:143], v[214:217], v[124:127]
	v_mfma_f32_16x16x32_bf16 v[116:119], v[172:175], v[214:217], v[116:119]
	v_mfma_f32_16x16x32_bf16 v[108:111], v[140:143], v[222:225], v[108:111]
	v_mfma_f32_16x16x32_bf16 v[100:103], v[172:175], v[222:225], v[100:103]
	v_mfma_f32_16x16x32_bf16 v[92:95], v[140:143], v[230:233], v[92:95]
	v_mfma_f32_16x16x32_bf16 v[84:87], v[172:175], v[230:233], v[84:87]
	v_mfma_f32_16x16x32_bf16 v[76:79], v[140:143], v[238:241], v[76:79]
	v_mfma_f32_16x16x32_bf16 v[68:71], v[172:175], v[238:241], v[68:71]
	v_mfma_f32_16x16x32_bf16 v[124:127], v[168:171], v[218:221], v[124:127]
	v_mfma_f32_16x16x32_bf16 v[116:119], v[176:179], v[218:221], v[116:119]
	v_mfma_f32_16x16x32_bf16 v[108:111], v[168:171], v[226:229], v[108:111]
	v_mfma_f32_16x16x32_bf16 v[100:103], v[176:179], v[226:229], v[100:103]
	v_mfma_f32_16x16x32_bf16 v[92:95], v[168:171], v[234:237], v[92:95]
	v_mfma_f32_16x16x32_bf16 v[84:87], v[176:179], v[234:237], v[84:87]
	v_mfma_f32_16x16x32_bf16 v[76:79], v[168:171], v[242:245], v[76:79]
	v_mfma_f32_16x16x32_bf16 v[68:71], v[176:179], v[242:245], v[68:71]
	v_mfma_f32_16x16x32_bf16 v[120:123], v[180:183], v[214:217], v[120:123]
	v_mfma_f32_16x16x32_bf16 v[112:115], v[188:191], v[214:217], v[112:115]
	v_mfma_f32_16x16x32_bf16 v[104:107], v[180:183], v[222:225], v[104:107]
	v_mfma_f32_16x16x32_bf16 v[96:99], v[188:191], v[222:225], v[96:99]
	v_mfma_f32_16x16x32_bf16 v[88:91], v[180:183], v[230:233], v[88:91]
	v_mfma_f32_16x16x32_bf16 v[80:83], v[188:191], v[230:233], v[80:83]
	v_mfma_f32_16x16x32_bf16 v[72:75], v[180:183], v[238:241], v[72:75]
	v_mfma_f32_16x16x32_bf16 v[64:67], v[188:191], v[238:241], v[64:67]
	v_mfma_f32_16x16x32_bf16 v[120:123], v[184:187], v[218:221], v[120:123]
	v_mfma_f32_16x16x32_bf16 v[112:115], v[210:213], v[218:221], v[112:115]
	v_mfma_f32_16x16x32_bf16 v[104:107], v[184:187], v[226:229], v[104:107]
	v_mfma_f32_16x16x32_bf16 v[96:99], v[210:213], v[226:229], v[96:99]
	v_mfma_f32_16x16x32_bf16 v[88:91], v[184:187], v[234:237], v[88:91]
	v_mfma_f32_16x16x32_bf16 v[80:83], v[210:213], v[234:237], v[80:83]
	v_mfma_f32_16x16x32_bf16 v[72:75], v[184:187], v[242:245], v[72:75]
	v_mfma_f32_16x16x32_bf16 v[64:67], v[210:213], v[242:245], v[64:67]
	s_setprio 0
	s_barrier
	s_mov_b32 m0, s37
	s_add_u32 s16, s16, 0x40080
	s_addc_u32 s17, s17, 0
	ds_read_b128 v[214:217], v165 offset:49152
	ds_read_b128 v[218:221], v165 offset:50176
	ds_read_b128 v[222:225], v165 offset:51200
	ds_read_b128 v[226:229], v165 offset:52224
	ds_read_b128 v[230:233], v165 offset:53248
	ds_read_b128 v[234:237], v165 offset:54272
	ds_read_b128 v[238:241], v165 offset:55296
	ds_read_b128 v[242:245], v165 offset:56320
	s_add_u32 s98, s16, 0xfffc0000
	s_addc_u32 s99, s17, -1
	global_load_lds_dwordx4 v132, s[98:99]
	s_mov_b32 m0, s38
	s_nop 0
	global_load_lds_dwordx4 v128, s[98:99]
	s_mov_b32 m0, s41
	s_nop 0
	global_load_lds_dwordx4 v132, s[16:17]
	s_mov_b32 m0, s42
	s_nop 0
	global_load_lds_dwordx4 v128, s[16:17]
	s_mov_b32 m0, s39
	s_nop 0
	s_add_u32 s100, s18, 0xfffc0080
	s_addc_u32 s101, s19, -1
	global_load_lds_dwordx4 v134, s[100:101]
	s_mov_b32 m0, s40
	s_nop 0
	global_load_lds_dwordx4 v130, s[100:101]
	s_add_i32 s53, s53, 2
	s_add_u32 s14, s14, 0x100
	s_addc_u32 s15, s15, 0
	s_add_u32 s51, s51, 0x100
	s_addc_u32 s52, s52, 0
	s_cmp_gt_u32 s53, 13
	s_waitcnt vmcnt(8)
	s_waitcnt lgkmcnt(0)
	s_barrier
	s_setprio 1
	v_mfma_f32_16x16x32_bf16 v[60:63], v[140:143], v[214:217], v[60:63]
	v_mfma_f32_16x16x32_bf16 v[52:55], v[172:175], v[214:217], v[52:55]
	v_mfma_f32_16x16x32_bf16 v[44:47], v[140:143], v[222:225], v[44:47]
	v_mfma_f32_16x16x32_bf16 v[36:39], v[172:175], v[222:225], v[36:39]
	v_mfma_f32_16x16x32_bf16 v[28:31], v[140:143], v[230:233], v[28:31]
	v_mfma_f32_16x16x32_bf16 v[20:23], v[172:175], v[230:233], v[20:23]
	v_mfma_f32_16x16x32_bf16 v[12:15], v[140:143], v[238:241], v[12:15]
	v_mfma_f32_16x16x32_bf16 v[4:7], v[172:175], v[238:241], v[4:7]
	v_mfma_f32_16x16x32_bf16 v[60:63], v[168:171], v[218:221], v[60:63]
	v_mfma_f32_16x16x32_bf16 v[52:55], v[176:179], v[218:221], v[52:55]
	v_mfma_f32_16x16x32_bf16 v[44:47], v[168:171], v[226:229], v[44:47]
	v_mfma_f32_16x16x32_bf16 v[36:39], v[176:179], v[226:229], v[36:39]
	v_mfma_f32_16x16x32_bf16 v[28:31], v[168:171], v[234:237], v[28:31]
	v_mfma_f32_16x16x32_bf16 v[20:23], v[176:179], v[234:237], v[20:23]
	v_mfma_f32_16x16x32_bf16 v[12:15], v[168:171], v[242:245], v[12:15]
	v_mfma_f32_16x16x32_bf16 v[4:7], v[176:179], v[242:245], v[4:7]
	v_mfma_f32_16x16x32_bf16 v[56:59], v[180:183], v[214:217], v[56:59]
	v_mfma_f32_16x16x32_bf16 v[48:51], v[188:191], v[214:217], v[48:51]
	v_mfma_f32_16x16x32_bf16 v[40:43], v[180:183], v[222:225], v[40:43]
	v_mfma_f32_16x16x32_bf16 v[32:35], v[188:191], v[222:225], v[32:35]
	v_mfma_f32_16x16x32_bf16 v[24:27], v[180:183], v[230:233], v[24:27]
	v_mfma_f32_16x16x32_bf16 v[16:19], v[188:191], v[230:233], v[16:19]
	v_mfma_f32_16x16x32_bf16 v[8:11], v[180:183], v[238:241], v[8:11]
	v_mfma_f32_16x16x32_bf16 v[0:3], v[188:191], v[238:241], v[0:3]
	v_mfma_f32_16x16x32_bf16 v[56:59], v[184:187], v[218:221], v[56:59]
	v_mfma_f32_16x16x32_bf16 v[48:51], v[210:213], v[218:221], v[48:51]
	v_mfma_f32_16x16x32_bf16 v[40:43], v[184:187], v[226:229], v[40:43]
	v_mfma_f32_16x16x32_bf16 v[32:35], v[210:213], v[226:229], v[32:35]
	v_mfma_f32_16x16x32_bf16 v[24:27], v[184:187], v[234:237], v[24:27]
	v_mfma_f32_16x16x32_bf16 v[16:19], v[210:213], v[234:237], v[16:19]
	v_mfma_f32_16x16x32_bf16 v[8:11], v[184:187], v[242:245], v[8:11]
	v_mfma_f32_16x16x32_bf16 v[0:3], v[210:213], v[242:245], v[0:3]
	s_setprio 0
	s_barrier
	s_cbranch_scc0 .LBB0_446
	s_and_b64 vcc, exec, s[2:3]
	s_cbranch_vccz .LBB0_449
	s_barrier

; #define PG8_STAGE(bufoff, gbase, voff) do { _Pragma("unroll") for (int _i = 0; _i < 2; ++_i) \
;         __builtin_amdgcn_global_load_lds((const unsigned*)((const char*)(gbase) + (voff)[_i]), (PG8_LAS unsigned*)(lds + (bufoff) + ldsw + _i * 8192), 16, 0, 0); } while (0)
; #define PG8_LDA(dst, b, h) do { _Pragma("unroll") for (int m = 0; m < 4; ++m) _Pragma("unroll") for (int k = 0; k < 2; ++k) dst[m][k] = *(const PG8_LAS bf16x8*)(lds + PG8_SA(b, h) + aoff + m * 2048 + k * 1024); } while (0)
; #define PG8_LDB(dst, b, h) do { _Pragma("unroll") for (int n = 0; n < 2; ++n) _Pragma("unroll") for (int k = 0; k < 2; ++k) dst[n][k] = *(const PG8_LAS bf16x8*)(lds + PG8_SB(b, h) + boff + n * 2048 + k * 1024); } while (0)
; #define PG8_MMA(ai, bj, At, Bt) do { __builtin_amdgcn_s_setprio(1); _Pragma("unroll") for (int m = 0; m < 4; ++m) _Pragma("unroll") for (int n = 0; n < 2; ++n) _Pragma("unroll") for (int k = 0; k < 2; ++k) \
;         acc[ai][bj][m][n] = __builtin_amdgcn_mfma_f32_16x16x32_bf16(Bt[n][k], At[m][k], acc[ai][bj][m][n], 0, 0, 0); __builtin_amdgcn_s_setprio(0); } while (0)
; #define PG8_WAIT_V(n) asm volatile("s_waitcnt vmcnt(" #n ")" ::: "memory")
; #define PG8_WAIT_L(n) asm volatile("s_waitcnt lgkmcnt(" #n ")" ::: "memory")
; #define PG8_BAR __builtin_amdgcn_s_barrier()
; #define PG8_SCHED __builtin_amdgcn_sched_barrier(0)
; template <class Epi, class Sched, bool ALIGN_EPI = false, bool SP2 = false>
; __device__ __forceinline__ void gemm_phase(PG8_LAS unsigned char* lds, const Gemm g, const Sched& S, const Epi& E) {
;     ...
;     f32x4 acc[2][2][4][2];
; #pragma unroll
;     for (int a = 0; a < 2; ++a)
; #pragma unroll
;         for (int b = 0; b < 2; ++b)
; #pragma unroll
;             for (int m = 0; m < 4; ++m)
; #pragma unroll
;                 for (int n = 0; n < 2; ++n) acc[a][b][m][n] = (f32x4){0.f, 0.f, 0.f, 0.f};
;     ...
;             PG8_LDB(B0, 0, 0); PG8_LDB(B1, 0, 1); PG8_SCHED; PG8_LDA(At, 0, 0); PG8_STAGE(PG8_SA(1, 1), a1 + hstep, voffA);
;             PG8_WAIT_V(8); PG8_WAIT_L(0); PG8_BAR; PG8_MMA(0, 0, At, B0); PG8_MMA(0, 1, At, B1); PG8_BAR; PG8_SCHED;
;             PG8_LDA(At, 0, 1); PG8_STAGE(PG8_SB(0, 0), b2, voffB); PG8_STAGE(PG8_SB(0, 1), b2 + hstep, voffB); PG8_STAGE(PG8_SA(0, 0), a2, voffA);
;             PG8_WAIT_V(8); PG8_WAIT_L(0); PG8_BAR; PG8_MMA(1, 0, At, B0); PG8_MMA(1, 1, At, B1); PG8_BAR; PG8_SCHED;
.Ldn_peel:
	ds_read_b128 v[128:131], v254
	ds_read_b128 v[132:135], v254 offset:1024
	ds_read_b128 v[136:139], v254 offset:2048
	ds_read_b128 v[140:143], v254 offset:3072
	ds_read_b128 v[174:177], v254 offset:16384
	ds_read_b128 v[184:187], v254 offset:17408
	ds_read_b128 v[188:191], v254 offset:18432
	ds_read_b128 v[210:213], v254 offset:19456
	s_add_u32 s2, s0, 0x100
	s_addc_u32 s3, s1, 0
	s_cmp_eq_u32 s13, 40
	s_cselect_b32 s7, s27, s3
	s_cselect_b32 s6, s26, s2
	s_cselect_b32 s5, s37, s11
	s_cselect_b32 s4, s36, s10
	s_add_i32 m0, s29, 0xc000
	ds_read_b128 v[214:217], v181
	ds_read_b128 v[218:221], v181 offset:1024
	ds_read_b128 v[222:225], v181 offset:2048
	ds_read_b128 v[226:229], v181 offset:3072
	ds_read_b128 v[230:233], v181 offset:4096
	ds_read_b128 v[234:237], v181 offset:5120
	ds_read_b128 v[238:241], v181 offset:6144
	ds_read_b128 v[242:245], v181 offset:7168
	global_load_lds_dwordx4 v170, s[0:1]
	s_add_i32 m0, s29, 0xe000
	s_nop 0
	global_load_lds_dwordx4 v172, s[0:1]
	s_waitcnt vmcnt(8)
	s_waitcnt lgkmcnt(0)
	s_barrier
	s_setprio 1
	v_mfma_f32_16x16x32_bf16 v[124:127], v[128:131], v[214:217], 0
	v_mfma_f32_16x16x32_bf16 v[120:123], v[136:139], v[214:217], 0
	v_mfma_f32_16x16x32_bf16 v[108:111], v[128:131], v[222:225], 0
	v_mfma_f32_16x16x32_bf16 v[104:107], v[136:139], v[222:225], 0
	v_mfma_f32_16x16x32_bf16 v[92:95], v[128:131], v[230:233], 0
	v_mfma_f32_16x16x32_bf16 v[88:91], v[136:139], v[230:233], 0
	v_mfma_f32_16x16x32_bf16 v[76:79], v[128:131], v[238:241], 0
	v_mfma_f32_16x16x32_bf16 v[72:75], v[136:139], v[238:241], 0
	v_mfma_f32_16x16x32_bf16 v[124:127], v[132:135], v[218:221], v[124:127]
	v_mfma_f32_16x16x32_bf16 v[120:123], v[140:143], v[218:221], v[120:123]
	v_mfma_f32_16x16x32_bf16 v[108:111], v[132:135], v[226:229], v[108:111]
	v_mfma_f32_16x16x32_bf16 v[104:107], v[140:143], v[226:229], v[104:107]
	v_mfma_f32_16x16x32_bf16 v[92:95], v[132:135], v[234:237], v[92:95]
	v_mfma_f32_16x16x32_bf16 v[88:91], v[140:143], v[234:237], v[88:91]
	v_mfma_f32_16x16x32_bf16 v[76:79], v[132:135], v[242:245], v[76:79]
	v_mfma_f32_16x16x32_bf16 v[72:75], v[140:143], v[242:245], v[72:75]
	v_mfma_f32_16x16x32_bf16 v[116:119], v[174:177], v[214:217], 0
	v_mfma_f32_16x16x32_bf16 v[112:115], v[188:191], v[214:217], 0
	v_mfma_f32_16x16x32_bf16 v[100:103], v[174:177], v[222:225], 0
	v_mfma_f32_16x16x32_bf16 v[96:99], v[188:191], v[222:225], 0
	v_mfma_f32_16x16x32_bf16 v[84:87], v[174:177], v[230:233], 0
	v_mfma_f32_16x16x32_bf16 v[80:83], v[188:191], v[230:233], 0
	v_mfma_f32_16x16x32_bf16 v[68:71], v[174:177], v[238:241], 0
	v_mfma_f32_16x16x32_bf16 v[64:67], v[188:191], v[238:241], 0
	v_mfma_f32_16x16x32_bf16 v[116:119], v[184:187], v[218:221], v[116:119]
	v_mfma_f32_16x16x32_bf16 v[112:115], v[210:213], v[218:221], v[112:115]
	v_mfma_f32_16x16x32_bf16 v[100:103], v[184:187], v[226:229], v[100:103]
	v_mfma_f32_16x16x32_bf16 v[96:99], v[210:213], v[226:229], v[96:99]
	v_mfma_f32_16x16x32_bf16 v[84:87], v[184:187], v[234:237], v[84:87]
	v_mfma_f32_16x16x32_bf16 v[80:83], v[210:213], v[234:237], v[80:83]
	v_mfma_f32_16x16x32_bf16 v[68:71], v[184:187], v[242:245], v[68:71]
	v_mfma_f32_16x16x32_bf16 v[64:67], v[210:213], v[242:245], v[64:67]
	s_setprio 0
	s_barrier
	s_mov_b32 m0, s35
	s_add_u32 s0, s4, 0xb0000
	s_addc_u32 s1, s5, 0
	ds_read_b128 v[214:217], v181 offset:16384
	ds_read_b128 v[218:221], v181 offset:17408
	ds_read_b128 v[222:225], v181 offset:18432
	ds_read_b128 v[226:229], v181 offset:19456
	ds_read_b128 v[230:233], v181 offset:20480
	ds_read_b128 v[234:237], v181 offset:21504
	ds_read_b128 v[238:241], v181 offset:22528
	ds_read_b128 v[242:245], v181 offset:23552
	global_load_lds_dwordx4 v166, s[4:5]
	s_mov_b32 m0, s38
	s_nop 0
	global_load_lds_dwordx4 v162, s[4:5]
	s_mov_b32 m0, s39
	s_nop 0
	global_load_lds_dwordx4 v166, s[0:1]
	s_mov_b32 m0, s40
	s_nop 0
	global_load_lds_dwordx4 v162, s[0:1]
	s_mov_b32 m0, s29
	s_nop 0
	global_load_lds_dwordx4 v168, s[6:7]
	s_mov_b32 m0, s41
	s_nop 0
	global_load_lds_dwordx4 v164, s[6:7]
	s_waitcnt vmcnt(8)
	s_waitcnt lgkmcnt(0)
	s_barrier
	s_setprio 1
	v_mfma_f32_16x16x32_bf16 v[60:63], v[128:131], v[214:217], 0
	v_mfma_f32_16x16x32_bf16 v[56:59], v[136:139], v[214:217], 0
	v_mfma_f32_16x16x32_bf16 v[44:47], v[128:131], v[222:225], 0
	v_mfma_f32_16x16x32_bf16 v[40:43], v[136:139], v[222:225], 0
	v_mfma_f32_16x16x32_bf16 v[28:31], v[128:131], v[230:233], 0
	v_mfma_f32_16x16x32_bf16 v[24:27], v[136:139], v[230:233], 0
	v_mfma_f32_16x16x32_bf16 v[12:15], v[128:131], v[238:241], 0
	v_mfma_f32_16x16x32_bf16 v[8:11], v[136:139], v[238:241], 0
	v_mfma_f32_16x16x32_bf16 v[60:63], v[132:135], v[218:221], v[60:63]
	v_mfma_f32_16x16x32_bf16 v[56:59], v[140:143], v[218:221], v[56:59]
	v_mfma_f32_16x16x32_bf16 v[44:47], v[132:135], v[226:229], v[44:47]
	v_mfma_f32_16x16x32_bf16 v[40:43], v[140:143], v[226:229], v[40:43]
	v_mfma_f32_16x16x32_bf16 v[28:31], v[132:135], v[234:237], v[28:31]
	v_mfma_f32_16x16x32_bf16 v[24:27], v[140:143], v[234:237], v[24:27]
	v_mfma_f32_16x16x32_bf16 v[12:15], v[132:135], v[242:245], v[12:15]
	v_mfma_f32_16x16x32_bf16 v[8:11], v[140:143], v[242:245], v[8:11]
	v_mfma_f32_16x16x32_bf16 v[52:55], v[174:177], v[214:217], 0
	v_mfma_f32_16x16x32_bf16 v[48:51], v[188:191], v[214:217], 0
	v_mfma_f32_16x16x32_bf16 v[36:39], v[174:177], v[222:225], 0
	v_mfma_f32_16x16x32_bf16 v[32:35], v[188:191], v[222:225], 0
	v_mfma_f32_16x16x32_bf16 v[20:23], v[174:177], v[230:233], 0
	v_mfma_f32_16x16x32_bf16 v[16:19], v[188:191], v[230:233], 0
	v_mfma_f32_16x16x32_bf16 v[4:7], v[174:177], v[238:241], 0
	v_mfma_f32_16x16x32_bf16 v[0:3], v[188:191], v[238:241], 0
	v_mfma_f32_16x16x32_bf16 v[52:55], v[184:187], v[218:221], v[52:55]
	v_mfma_f32_16x16x32_bf16 v[48:51], v[210:213], v[218:221], v[48:51]
	v_mfma_f32_16x16x32_bf16 v[36:39], v[184:187], v[226:229], v[36:39]
	v_mfma_f32_16x16x32_bf16 v[32:35], v[210:213], v[226:229], v[32:35]
	v_mfma_f32_16x16x32_bf16 v[20:23], v[184:187], v[234:237], v[20:23]
	v_mfma_f32_16x16x32_bf16 v[16:19], v[210:213], v[234:237], v[16:19]
	v_mfma_f32_16x16x32_bf16 v[4:7], v[184:187], v[242:245], v[4:7]
	v_mfma_f32_16x16x32_bf16 v[0:3], v[210:213], v[242:245], v[0:3]
	s_setprio 0
	s_barrier
; #define PG8_STAGE(bufoff, gbase, voff) do { _Pragma("unroll") for (int _i = 0; _i < 2; ++_i) \
;         __builtin_amdgcn_global_load_lds((const unsigned*)((const char*)(gbase) + (voff)[_i]), (PG8_LAS unsigned*)(lds + (bufoff) + ldsw + _i * 8192), 16, 0, 0); } while (0)
; #define PG8_LDA(dst, b, h) do { _Pragma("unroll") for (int m = 0; m < 4; ++m) _Pragma("unroll") for (int k = 0; k < 2; ++k) dst[m][k] = *(const PG8_LAS bf16x8*)(lds + PG8_SA(b, h) + aoff + m * 2048 + k * 1024); } while (0)
; #define PG8_LDB(dst, b, h) do { _Pragma("unroll") for (int n = 0; n < 2; ++n) _Pragma("unroll") for (int k = 0; k < 2; ++k) dst[n][k] = *(const PG8_LAS bf16x8*)(lds + PG8_SB(b, h) + boff + n * 2048 + k * 1024); } while (0)
; #define PG8_MMA(ai, bj, At, Bt) do { __builtin_amdgcn_s_setprio(1); _Pragma("unroll") for (int m = 0; m < 4; ++m) _Pragma("unroll") for (int n = 0; n < 2; ++n) _Pragma("unroll") for (int k = 0; k < 2; ++k) \
;         acc[ai][bj][m][n] = __builtin_amdgcn_mfma_f32_16x16x32_bf16(Bt[n][k], At[m][k], acc[ai][bj][m][n], 0, 0, 0); __builtin_amdgcn_s_setprio(0); } while (0)
; #define PG8_WAIT_V(n) asm volatile("s_waitcnt vmcnt(" #n ")" ::: "memory")
; #define PG8_WAIT_L(n) asm volatile("s_waitcnt lgkmcnt(" #n ")" ::: "memory")
; #define PG8_BAR __builtin_amdgcn_s_barrier()
; #define PG8_SCHED __builtin_amdgcn_sched_barrier(0)
; template <class Epi, class Sched, bool ALIGN_EPI = false, bool SP2 = false>
; __device__ __forceinline__ void gemm_phase(PG8_LAS unsigned char* lds, const Gemm g, const Sched& S, const Epi& E) {
;     ...
;             PG8_LDB(B0, 1, 0); PG8_LDB(B1, 1, 1); PG8_SCHED; PG8_LDA(At, 1, 0); PG8_STAGE(PG8_SA(0, 1), a2 + hstep, voffA);
;             PG8_WAIT_V(8); PG8_WAIT_L(0); PG8_BAR; PG8_MMA(0, 0, At, B0); PG8_MMA(0, 1, At, B1); PG8_BAR; PG8_SCHED;
;             PG8_LDA(At, 1, 1); PG8_STAGE(PG8_SB(1, 0), b3, voffB); PG8_STAGE(PG8_SB(1, 1), b3 + hstep, voffB); PG8_STAGE(PG8_SA(1, 0), a3, voffA);
;             PG8_WAIT_V(8); PG8_WAIT_L(0); PG8_BAR; PG8_MMA(1, 0, At, B0); PG8_MMA(1, 1, At, B1); PG8_BAR; PG8_SCHED;
	ds_read_b128 v[128:131], v254 offset:32768
	ds_read_b128 v[132:135], v254 offset:33792
	ds_read_b128 v[136:139], v254 offset:34816
	ds_read_b128 v[140:143], v254 offset:35840
	ds_read_b128 v[174:177], v254 offset:49152
	ds_read_b128 v[184:187], v254 offset:50176
	ds_read_b128 v[188:191], v254 offset:51200
	ds_read_b128 v[210:213], v254 offset:52224
	s_add_u32 s0, s6, 0xb0000
	s_addc_u32 s1, s7, 0
	s_mov_b32 m0, s42
	ds_read_b128 v[214:217], v181 offset:32768
	ds_read_b128 v[218:221], v181 offset:33792
	ds_read_b128 v[222:225], v181 offset:34816
	ds_read_b128 v[226:229], v181 offset:35840
	ds_read_b128 v[230:233], v181 offset:36864
	ds_read_b128 v[234:237], v181 offset:37888
	ds_read_b128 v[238:241], v181 offset:38912
	ds_read_b128 v[242:245], v181 offset:39936
	global_load_lds_dwordx4 v168, s[0:1]
	s_mov_b32 m0, s43
	s_nop 0
	global_load_lds_dwordx4 v164, s[0:1]
	s_waitcnt vmcnt(8)
	s_waitcnt lgkmcnt(0)
	s_barrier
	s_setprio 1
	v_mfma_f32_16x16x32_bf16 v[124:127], v[128:131], v[214:217], v[124:127]
	v_mfma_f32_16x16x32_bf16 v[120:123], v[136:139], v[214:217], v[120:123]
	v_mfma_f32_16x16x32_bf16 v[108:111], v[128:131], v[222:225], v[108:111]
	v_mfma_f32_16x16x32_bf16 v[104:107], v[136:139], v[222:225], v[104:107]
	v_mfma_f32_16x16x32_bf16 v[92:95], v[128:131], v[230:233], v[92:95]
	v_mfma_f32_16x16x32_bf16 v[88:91], v[136:139], v[230:233], v[88:91]
	v_mfma_f32_16x16x32_bf16 v[76:79], v[128:131], v[238:241], v[76:79]
	v_mfma_f32_16x16x32_bf16 v[72:75], v[136:139], v[238:241], v[72:75]
	v_mfma_f32_16x16x32_bf16 v[124:127], v[132:135], v[218:221], v[124:127]
	v_mfma_f32_16x16x32_bf16 v[120:123], v[140:143], v[218:221], v[120:123]
	v_mfma_f32_16x16x32_bf16 v[108:111], v[132:135], v[226:229], v[108:111]
	v_mfma_f32_16x16x32_bf16 v[104:107], v[140:143], v[226:229], v[104:107]
	v_mfma_f32_16x16x32_bf16 v[92:95], v[132:135], v[234:237], v[92:95]
	v_mfma_f32_16x16x32_bf16 v[88:91], v[140:143], v[234:237], v[88:91]
	v_mfma_f32_16x16x32_bf16 v[76:79], v[132:135], v[242:245], v[76:79]
	v_mfma_f32_16x16x32_bf16 v[72:75], v[140:143], v[242:245], v[72:75]
	v_mfma_f32_16x16x32_bf16 v[116:119], v[174:177], v[214:217], v[116:119]
	v_mfma_f32_16x16x32_bf16 v[112:115], v[188:191], v[214:217], v[112:115]
	v_mfma_f32_16x16x32_bf16 v[100:103], v[174:177], v[222:225], v[100:103]
	v_mfma_f32_16x16x32_bf16 v[96:99], v[188:191], v[222:225], v[96:99]
	v_mfma_f32_16x16x32_bf16 v[84:87], v[174:177], v[230:233], v[84:87]
	v_mfma_f32_16x16x32_bf16 v[80:83], v[188:191], v[230:233], v[80:83]
	v_mfma_f32_16x16x32_bf16 v[68:71], v[174:177], v[238:241], v[68:71]
	v_mfma_f32_16x16x32_bf16 v[64:67], v[188:191], v[238:241], v[64:67]
	v_mfma_f32_16x16x32_bf16 v[116:119], v[184:187], v[218:221], v[116:119]
	v_mfma_f32_16x16x32_bf16 v[112:115], v[210:213], v[218:221], v[112:115]
	v_mfma_f32_16x16x32_bf16 v[100:103], v[184:187], v[226:229], v[100:103]
	v_mfma_f32_16x16x32_bf16 v[96:99], v[210:213], v[226:229], v[96:99]
	v_mfma_f32_16x16x32_bf16 v[84:87], v[184:187], v[234:237], v[84:87]
	v_mfma_f32_16x16x32_bf16 v[80:83], v[210:213], v[234:237], v[80:83]
	v_mfma_f32_16x16x32_bf16 v[68:71], v[184:187], v[242:245], v[68:71]
	v_mfma_f32_16x16x32_bf16 v[64:67], v[210:213], v[242:245], v[64:67]
	s_setprio 0
	s_barrier
	s_mov_b32 m0, s47
	s_add_u32 s0, s4, 0xb0080
	s_addc_u32 s1, s5, 0
	ds_read_b128 v[214:217], v181 offset:49152
	ds_read_b128 v[218:221], v181 offset:50176
	ds_read_b128 v[222:225], v181 offset:51200
	ds_read_b128 v[226:229], v181 offset:52224
	ds_read_b128 v[230:233], v181 offset:53248
	ds_read_b128 v[234:237], v181 offset:54272
	ds_read_b128 v[238:241], v181 offset:55296
	ds_read_b128 v[242:245], v181 offset:56320
	s_add_u32 s98, s4, 0x80
	s_addc_u32 s99, s5, 0
	global_load_lds_dwordx4 v166, s[98:99]
	s_mov_b32 m0, s48
	s_nop 0
	global_load_lds_dwordx4 v162, s[98:99]
	s_mov_b32 m0, s51
	s_nop 0
	global_load_lds_dwordx4 v166, s[0:1]
	s_mov_b32 m0, s52
	s_nop 0
	global_load_lds_dwordx4 v162, s[0:1]
	s_mov_b32 m0, s49
	s_nop 0
	s_add_u32 s100, s6, 0x80
	s_addc_u32 s101, s7, 0
	global_load_lds_dwordx4 v168, s[100:101]
	s_mov_b32 m0, s50
	s_nop 0
	global_load_lds_dwordx4 v164, s[100:101]
	s_add_i32 s13, s13, 2
	s_add_u32 s10, s10, 0x100
	s_addc_u32 s11, s11, 0
	s_cmp_gt_u32 s13, 41
	s_mov_b64 s[0:1], s[2:3]
	s_waitcnt vmcnt(8)
	s_waitcnt lgkmcnt(0)
	s_barrier
	s_setprio 1
	v_mfma_f32_16x16x32_bf16 v[60:63], v[128:131], v[214:217], v[60:63]
	v_mfma_f32_16x16x32_bf16 v[56:59], v[136:139], v[214:217], v[56:59]
	v_mfma_f32_16x16x32_bf16 v[44:47], v[128:131], v[222:225], v[44:47]
	v_mfma_f32_16x16x32_bf16 v[40:43], v[136:139], v[222:225], v[40:43]
	v_mfma_f32_16x16x32_bf16 v[28:31], v[128:131], v[230:233], v[28:31]
	v_mfma_f32_16x16x32_bf16 v[24:27], v[136:139], v[230:233], v[24:27]
	v_mfma_f32_16x16x32_bf16 v[12:15], v[128:131], v[238:241], v[12:15]
	v_mfma_f32_16x16x32_bf16 v[8:11], v[136:139], v[238:241], v[8:11]
	v_mfma_f32_16x16x32_bf16 v[60:63], v[132:135], v[218:221], v[60:63]
	v_mfma_f32_16x16x32_bf16 v[56:59], v[140:143], v[218:221], v[56:59]
	v_mfma_f32_16x16x32_bf16 v[44:47], v[132:135], v[226:229], v[44:47]
	v_mfma_f32_16x16x32_bf16 v[40:43], v[140:143], v[226:229], v[40:43]
	v_mfma_f32_16x16x32_bf16 v[28:31], v[132:135], v[234:237], v[28:31]
	v_mfma_f32_16x16x32_bf16 v[24:27], v[140:143], v[234:237], v[24:27]
	v_mfma_f32_16x16x32_bf16 v[12:15], v[132:135], v[242:245], v[12:15]
	v_mfma_f32_16x16x32_bf16 v[8:11], v[140:143], v[242:245], v[8:11]
	v_mfma_f32_16x16x32_bf16 v[52:55], v[174:177], v[214:217], v[52:55]
	v_mfma_f32_16x16x32_bf16 v[48:51], v[188:191], v[214:217], v[48:51]
	v_mfma_f32_16x16x32_bf16 v[36:39], v[174:177], v[222:225], v[36:39]
	v_mfma_f32_16x16x32_bf16 v[32:35], v[188:191], v[222:225], v[32:35]
	v_mfma_f32_16x16x32_bf16 v[20:23], v[174:177], v[230:233], v[20:23]
	v_mfma_f32_16x16x32_bf16 v[16:19], v[188:191], v[230:233], v[16:19]
	v_mfma_f32_16x16x32_bf16 v[4:7], v[174:177], v[238:241], v[4:7]
	v_mfma_f32_16x16x32_bf16 v[0:3], v[188:191], v[238:241], v[0:3]
	v_mfma_f32_16x16x32_bf16 v[52:55], v[184:187], v[218:221], v[52:55]
	v_mfma_f32_16x16x32_bf16 v[48:51], v[210:213], v[218:221], v[48:51]
	v_mfma_f32_16x16x32_bf16 v[36:39], v[184:187], v[226:229], v[36:39]
	v_mfma_f32_16x16x32_bf16 v[32:35], v[210:213], v[226:229], v[32:35]
	v_mfma_f32_16x16x32_bf16 v[20:23], v[184:187], v[234:237], v[20:23]
	v_mfma_f32_16x16x32_bf16 v[16:19], v[210:213], v[234:237], v[16:19]
	v_mfma_f32_16x16x32_bf16 v[4:7], v[184:187], v[242:245], v[4:7]
	v_mfma_f32_16x16x32_bf16 v[0:3], v[210:213], v[242:245], v[0:3]
	s_setprio 0
	s_barrier
; #define PG8_STAGE(bufoff, gbase, voff) do { _Pragma("unroll") for (int _i = 0; _i < 2; ++_i) \
;         __builtin_amdgcn_global_load_lds((const unsigned*)((const char*)(gbase) + (voff)[_i]), (PG8_LAS unsigned*)(lds + (bufoff) + ldsw + _i * 8192), 16, 0, 0); } while (0)
; #define PG8_LDA(dst, b, h) do { _Pragma("unroll") for (int m = 0; m < 4; ++m) _Pragma("unroll") for (int k = 0; k < 2; ++k) dst[m][k] = *(const PG8_LAS bf16x8*)(lds + PG8_SA(b, h) + aoff + m * 2048 + k * 1024); } while (0)
; #define PG8_LDB(dst, b, h) do { _Pragma("unroll") for (int n = 0; n < 2; ++n) _Pragma("unroll") for (int k = 0; k < 2; ++k) dst[n][k] = *(const PG8_LAS bf16x8*)(lds + PG8_SB(b, h) + boff + n * 2048 + k * 1024); } while (0)
; #define PG8_MMA(ai, bj, At, Bt) do { __builtin_amdgcn_s_setprio(1); _Pragma("unroll") for (int m = 0; m < 4; ++m) _Pragma("unroll") for (int n = 0; n < 2; ++n) _Pragma("unroll") for (int k = 0; k < 2; ++k) \
;         acc[ai][bj][m][n] = __builtin_amdgcn_mfma_f32_16x16x32_bf16(Bt[n][k], At[m][k], acc[ai][bj][m][n], 0, 0, 0); __builtin_amdgcn_s_setprio(0); } while (0)
; #define PG8_WAIT_V(n) asm volatile("s_waitcnt vmcnt(" #n ")" ::: "memory")
; #define PG8_BAR __builtin_amdgcn_s_barrier()
; template <class Epi, class Sched, bool ALIGN_EPI = false, bool SP2 = false>
; __device__ __forceinline__ void gemm_phase(PG8_LAS unsigned char* lds, const Gemm g, const Sched& S, const Epi& E) {
;     ...
;         for (int t = 0; t < nt; t += 2) {
;             const bool last = (t == nt - 2);
;             const char* a1 = cA + (size_t)(t + 1) * kstep;
;             const char* a2 = last ? nA : cA + (size_t)(t + 2) * kstep; const char* b2 = last ? nB : cB + (size_t)(t + 2) * kstep;
;             const char* a3 = a2 + kstep; const char* b3 = b2 + kstep;
;             if (last && has_next) S.a_ready(nxt);
;             if constexpr (SP2) {
;             PG8_LDB(B0, 0, 0); PG8_LDB(B1, 0, 1); PG8_SCHED; PG8_LDA(At, 0, 0); PG8_STAGE(PG8_SA(1, 1), a1 + hstep, voffA);
;             PG8_WAIT_V(8); PG8_WAIT_L(0); PG8_BAR; PG8_MMA(0, 0, At, B0); PG8_MMA(0, 1, At, B1); PG8_BAR; PG8_SCHED;
;             PG8_LDA(At, 0, 1); PG8_STAGE(PG8_SB(0, 0), b2, voffB); PG8_STAGE(PG8_SB(0, 1), b2 + hstep, voffB); PG8_STAGE(PG8_SA(0, 0), a2, voffA);
;             PG8_WAIT_V(8); PG8_WAIT_L(0); PG8_BAR; PG8_MMA(1, 0, At, B0); PG8_MMA(1, 1, At, B1); PG8_BAR; PG8_SCHED;
.LBB0_545:
	ds_read_b128 v[128:131], v254
	ds_read_b128 v[132:135], v254 offset:1024
	ds_read_b128 v[136:139], v254 offset:2048
	ds_read_b128 v[140:143], v254 offset:3072
	ds_read_b128 v[174:177], v254 offset:16384
	ds_read_b128 v[184:187], v254 offset:17408
	ds_read_b128 v[188:191], v254 offset:18432
	ds_read_b128 v[210:213], v254 offset:19456
	s_add_u32 s2, s0, 0x100
	s_addc_u32 s3, s1, 0
	s_cmp_eq_u32 s13, 40
	s_cselect_b32 s7, s27, s3
	s_cselect_b32 s6, s26, s2
	s_cselect_b32 s5, s37, s11
	s_cselect_b32 s4, s36, s10
	s_add_i32 m0, s29, 0xc000
	ds_read_b128 v[214:217], v181
	ds_read_b128 v[218:221], v181 offset:1024
	ds_read_b128 v[222:225], v181 offset:2048
	ds_read_b128 v[226:229], v181 offset:3072
	ds_read_b128 v[230:233], v181 offset:4096
	ds_read_b128 v[234:237], v181 offset:5120
	ds_read_b128 v[238:241], v181 offset:6144
	ds_read_b128 v[242:245], v181 offset:7168
	global_load_lds_dwordx4 v170, s[0:1]
	s_add_i32 m0, s29, 0xe000
	s_nop 0
	global_load_lds_dwordx4 v172, s[0:1]
	s_waitcnt vmcnt(8)
	s_waitcnt lgkmcnt(0)
	s_barrier
	s_setprio 1
	v_mfma_f32_16x16x32_bf16 v[124:127], v[128:131], v[214:217], v[124:127]
	v_mfma_f32_16x16x32_bf16 v[120:123], v[136:139], v[214:217], v[120:123]
	v_mfma_f32_16x16x32_bf16 v[108:111], v[128:131], v[222:225], v[108:111]
	v_mfma_f32_16x16x32_bf16 v[104:107], v[136:139], v[222:225], v[104:107]
	v_mfma_f32_16x16x32_bf16 v[92:95], v[128:131], v[230:233], v[92:95]
	v_mfma_f32_16x16x32_bf16 v[88:91], v[136:139], v[230:233], v[88:91]
	v_mfma_f32_16x16x32_bf16 v[76:79], v[128:131], v[238:241], v[76:79]
	v_mfma_f32_16x16x32_bf16 v[72:75], v[136:139], v[238:241], v[72:75]
	v_mfma_f32_16x16x32_bf16 v[124:127], v[132:135], v[218:221], v[124:127]
	v_mfma_f32_16x16x32_bf16 v[120:123], v[140:143], v[218:221], v[120:123]
	v_mfma_f32_16x16x32_bf16 v[108:111], v[132:135], v[226:229], v[108:111]
	v_mfma_f32_16x16x32_bf16 v[104:107], v[140:143], v[226:229], v[104:107]
	v_mfma_f32_16x16x32_bf16 v[92:95], v[132:135], v[234:237], v[92:95]
	v_mfma_f32_16x16x32_bf16 v[88:91], v[140:143], v[234:237], v[88:91]
	v_mfma_f32_16x16x32_bf16 v[76:79], v[132:135], v[242:245], v[76:79]
	v_mfma_f32_16x16x32_bf16 v[72:75], v[140:143], v[242:245], v[72:75]
	v_mfma_f32_16x16x32_bf16 v[116:119], v[174:177], v[214:217], v[116:119]
	v_mfma_f32_16x16x32_bf16 v[112:115], v[188:191], v[214:217], v[112:115]
	v_mfma_f32_16x16x32_bf16 v[100:103], v[174:177], v[222:225], v[100:103]
	v_mfma_f32_16x16x32_bf16 v[96:99], v[188:191], v[222:225], v[96:99]
	v_mfma_f32_16x16x32_bf16 v[84:87], v[174:177], v[230:233], v[84:87]
	v_mfma_f32_16x16x32_bf16 v[80:83], v[188:191], v[230:233], v[80:83]
	v_mfma_f32_16x16x32_bf16 v[68:71], v[174:177], v[238:241], v[68:71]
	v_mfma_f32_16x16x32_bf16 v[64:67], v[188:191], v[238:241], v[64:67]
	v_mfma_f32_16x16x32_bf16 v[116:119], v[184:187], v[218:221], v[116:119]
	v_mfma_f32_16x16x32_bf16 v[112:115], v[210:213], v[218:221], v[112:115]
	v_mfma_f32_16x16x32_bf16 v[100:103], v[184:187], v[226:229], v[100:103]
	v_mfma_f32_16x16x32_bf16 v[96:99], v[210:213], v[226:229], v[96:99]
	v_mfma_f32_16x16x32_bf16 v[84:87], v[184:187], v[234:237], v[84:87]
	v_mfma_f32_16x16x32_bf16 v[80:83], v[210:213], v[234:237], v[80:83]
	v_mfma_f32_16x16x32_bf16 v[68:71], v[184:187], v[242:245], v[68:71]
	v_mfma_f32_16x16x32_bf16 v[64:67], v[210:213], v[242:245], v[64:67]
	s_setprio 0
	s_barrier
	s_mov_b32 m0, s35
	s_add_u32 s0, s4, 0xb0000
	s_addc_u32 s1, s5, 0
	ds_read_b128 v[214:217], v181 offset:16384
	ds_read_b128 v[218:221], v181 offset:17408
	ds_read_b128 v[222:225], v181 offset:18432
	ds_read_b128 v[226:229], v181 offset:19456
	ds_read_b128 v[230:233], v181 offset:20480
	ds_read_b128 v[234:237], v181 offset:21504
	ds_read_b128 v[238:241], v181 offset:22528
	ds_read_b128 v[242:245], v181 offset:23552
	global_load_lds_dwordx4 v166, s[4:5]
	s_mov_b32 m0, s38
	s_nop 0
	global_load_lds_dwordx4 v162, s[4:5]
	s_mov_b32 m0, s39
	s_nop 0
	global_load_lds_dwordx4 v166, s[0:1]
	s_mov_b32 m0, s40
	s_nop 0
	global_load_lds_dwordx4 v162, s[0:1]
	s_mov_b32 m0, s29
	s_nop 0
	global_load_lds_dwordx4 v168, s[6:7]
	s_mov_b32 m0, s41
	s_nop 0
	global_load_lds_dwordx4 v164, s[6:7]
	s_waitcnt vmcnt(8)
	s_waitcnt lgkmcnt(0)
	s_barrier
	s_setprio 1
	v_mfma_f32_16x16x32_bf16 v[60:63], v[128:131], v[214:217], v[60:63]
	v_mfma_f32_16x16x32_bf16 v[56:59], v[136:139], v[214:217], v[56:59]
	v_mfma_f32_16x16x32_bf16 v[44:47], v[128:131], v[222:225], v[44:47]
	v_mfma_f32_16x16x32_bf16 v[40:43], v[136:139], v[222:225], v[40:43]
	v_mfma_f32_16x16x32_bf16 v[28:31], v[128:131], v[230:233], v[28:31]
	v_mfma_f32_16x16x32_bf16 v[24:27], v[136:139], v[230:233], v[24:27]
	v_mfma_f32_16x16x32_bf16 v[12:15], v[128:131], v[238:241], v[12:15]
	v_mfma_f32_16x16x32_bf16 v[8:11], v[136:139], v[238:241], v[8:11]
	v_mfma_f32_16x16x32_bf16 v[60:63], v[132:135], v[218:221], v[60:63]
	v_mfma_f32_16x16x32_bf16 v[56:59], v[140:143], v[218:221], v[56:59]
	v_mfma_f32_16x16x32_bf16 v[44:47], v[132:135], v[226:229], v[44:47]
	v_mfma_f32_16x16x32_bf16 v[40:43], v[140:143], v[226:229], v[40:43]
	v_mfma_f32_16x16x32_bf16 v[28:31], v[132:135], v[234:237], v[28:31]
	v_mfma_f32_16x16x32_bf16 v[24:27], v[140:143], v[234:237], v[24:27]
	v_mfma_f32_16x16x32_bf16 v[12:15], v[132:135], v[242:245], v[12:15]
	v_mfma_f32_16x16x32_bf16 v[8:11], v[140:143], v[242:245], v[8:11]
	v_mfma_f32_16x16x32_bf16 v[52:55], v[174:177], v[214:217], v[52:55]
	v_mfma_f32_16x16x32_bf16 v[48:51], v[188:191], v[214:217], v[48:51]
	v_mfma_f32_16x16x32_bf16 v[36:39], v[174:177], v[222:225], v[36:39]
	v_mfma_f32_16x16x32_bf16 v[32:35], v[188:191], v[222:225], v[32:35]
	v_mfma_f32_16x16x32_bf16 v[20:23], v[174:177], v[230:233], v[20:23]
	v_mfma_f32_16x16x32_bf16 v[16:19], v[188:191], v[230:233], v[16:19]
	v_mfma_f32_16x16x32_bf16 v[4:7], v[174:177], v[238:241], v[4:7]
	v_mfma_f32_16x16x32_bf16 v[0:3], v[188:191], v[238:241], v[0:3]
	v_mfma_f32_16x16x32_bf16 v[52:55], v[184:187], v[218:221], v[52:55]
	v_mfma_f32_16x16x32_bf16 v[48:51], v[210:213], v[218:221], v[48:51]
	v_mfma_f32_16x16x32_bf16 v[36:39], v[184:187], v[226:229], v[36:39]
	v_mfma_f32_16x16x32_bf16 v[32:35], v[210:213], v[226:229], v[32:35]
	v_mfma_f32_16x16x32_bf16 v[20:23], v[184:187], v[234:237], v[20:23]
	v_mfma_f32_16x16x32_bf16 v[16:19], v[210:213], v[234:237], v[16:19]
	v_mfma_f32_16x16x32_bf16 v[4:7], v[184:187], v[242:245], v[4:7]
	v_mfma_f32_16x16x32_bf16 v[0:3], v[210:213], v[242:245], v[0:3]
	s_setprio 0
	s_barrier
; #define PG8_STAGE(bufoff, gbase, voff) do { _Pragma("unroll") for (int _i = 0; _i < 2; ++_i) \
;         __builtin_amdgcn_global_load_lds((const unsigned*)((const char*)(gbase) + (voff)[_i]), (PG8_LAS unsigned*)(lds + (bufoff) + ldsw + _i * 8192), 16, 0, 0); } while (0)
; #define PG8_LDA(dst, b, h) do { _Pragma("unroll") for (int m = 0; m < 4; ++m) _Pragma("unroll") for (int k = 0; k < 2; ++k) dst[m][k] = *(const PG8_LAS bf16x8*)(lds + PG8_SA(b, h) + aoff + m * 2048 + k * 1024); } while (0)
; #define PG8_LDB(dst, b, h) do { _Pragma("unroll") for (int n = 0; n < 2; ++n) _Pragma("unroll") for (int k = 0; k < 2; ++k) dst[n][k] = *(const PG8_LAS bf16x8*)(lds + PG8_SB(b, h) + boff + n * 2048 + k * 1024); } while (0)
; #define PG8_MMA(ai, bj, At, Bt) do { __builtin_amdgcn_s_setprio(1); _Pragma("unroll") for (int m = 0; m < 4; ++m) _Pragma("unroll") for (int n = 0; n < 2; ++n) _Pragma("unroll") for (int k = 0; k < 2; ++k) \
;         acc[ai][bj][m][n] = __builtin_amdgcn_mfma_f32_16x16x32_bf16(Bt[n][k], At[m][k], acc[ai][bj][m][n], 0, 0, 0); __builtin_amdgcn_s_setprio(0); } while (0)
; #define PG8_WAIT_V(n) asm volatile("s_waitcnt vmcnt(" #n ")" ::: "memory")
; #define PG8_WAIT_L(n) asm volatile("s_waitcnt lgkmcnt(" #n ")" ::: "memory")
; #define PG8_BAR __builtin_amdgcn_s_barrier()
; #define PG8_SCHED __builtin_amdgcn_sched_barrier(0)
; template <class Epi, class Sched, bool ALIGN_EPI = false, bool SP2 = false>
; __device__ __forceinline__ void gemm_phase(PG8_LAS unsigned char* lds, const Gemm g, const Sched& S, const Epi& E) {
;     ...
;             PG8_LDB(B0, 1, 0); PG8_LDB(B1, 1, 1); PG8_SCHED; PG8_LDA(At, 1, 0); PG8_STAGE(PG8_SA(0, 1), a2 + hstep, voffA);
;             PG8_WAIT_V(8); PG8_WAIT_L(0); PG8_BAR; PG8_MMA(0, 0, At, B0); PG8_MMA(0, 1, At, B1); PG8_BAR; PG8_SCHED;
;             PG8_LDA(At, 1, 1); PG8_STAGE(PG8_SB(1, 0), b3, voffB); PG8_STAGE(PG8_SB(1, 1), b3 + hstep, voffB); PG8_STAGE(PG8_SA(1, 0), a3, voffA);
;             PG8_WAIT_V(8); PG8_WAIT_L(0); PG8_BAR; PG8_MMA(1, 0, At, B0); PG8_MMA(1, 1, At, B1); PG8_BAR; PG8_SCHED;
	ds_read_b128 v[128:131], v254 offset:32768
	ds_read_b128 v[132:135], v254 offset:33792
	ds_read_b128 v[136:139], v254 offset:34816
	ds_read_b128 v[140:143], v254 offset:35840
	ds_read_b128 v[174:177], v254 offset:49152
	ds_read_b128 v[184:187], v254 offset:50176
	ds_read_b128 v[188:191], v254 offset:51200
	ds_read_b128 v[210:213], v254 offset:52224
	s_add_u32 s0, s6, 0xb0000
	s_addc_u32 s1, s7, 0
	s_mov_b32 m0, s42
	ds_read_b128 v[214:217], v181 offset:32768
	ds_read_b128 v[218:221], v181 offset:33792
	ds_read_b128 v[222:225], v181 offset:34816
	ds_read_b128 v[226:229], v181 offset:35840
	ds_read_b128 v[230:233], v181 offset:36864
	ds_read_b128 v[234:237], v181 offset:37888
	ds_read_b128 v[238:241], v181 offset:38912
	ds_read_b128 v[242:245], v181 offset:39936
	global_load_lds_dwordx4 v168, s[0:1]
	s_mov_b32 m0, s43
	s_nop 0
	global_load_lds_dwordx4 v164, s[0:1]
	s_waitcnt vmcnt(8)
	s_waitcnt lgkmcnt(0)
	s_barrier
	s_setprio 1
	v_mfma_f32_16x16x32_bf16 v[124:127], v[128:131], v[214:217], v[124:127]
	v_mfma_f32_16x16x32_bf16 v[120:123], v[136:139], v[214:217], v[120:123]
	v_mfma_f32_16x16x32_bf16 v[108:111], v[128:131], v[222:225], v[108:111]
	v_mfma_f32_16x16x32_bf16 v[104:107], v[136:139], v[222:225], v[104:107]
	v_mfma_f32_16x16x32_bf16 v[92:95], v[128:131], v[230:233], v[92:95]
	v_mfma_f32_16x16x32_bf16 v[88:91], v[136:139], v[230:233], v[88:91]
	v_mfma_f32_16x16x32_bf16 v[76:79], v[128:131], v[238:241], v[76:79]
	v_mfma_f32_16x16x32_bf16 v[72:75], v[136:139], v[238:241], v[72:75]
	v_mfma_f32_16x16x32_bf16 v[124:127], v[132:135], v[218:221], v[124:127]
	v_mfma_f32_16x16x32_bf16 v[120:123], v[140:143], v[218:221], v[120:123]
	v_mfma_f32_16x16x32_bf16 v[108:111], v[132:135], v[226:229], v[108:111]
	v_mfma_f32_16x16x32_bf16 v[104:107], v[140:143], v[226:229], v[104:107]
	v_mfma_f32_16x16x32_bf16 v[92:95], v[132:135], v[234:237], v[92:95]
	v_mfma_f32_16x16x32_bf16 v[88:91], v[140:143], v[234:237], v[88:91]
	v_mfma_f32_16x16x32_bf16 v[76:79], v[132:135], v[242:245], v[76:79]
	v_mfma_f32_16x16x32_bf16 v[72:75], v[140:143], v[242:245], v[72:75]
	v_mfma_f32_16x16x32_bf16 v[116:119], v[174:177], v[214:217], v[116:119]
	v_mfma_f32_16x16x32_bf16 v[112:115], v[188:191], v[214:217], v[112:115]
	v_mfma_f32_16x16x32_bf16 v[100:103], v[174:177], v[222:225], v[100:103]
	v_mfma_f32_16x16x32_bf16 v[96:99], v[188:191], v[222:225], v[96:99]
	v_mfma_f32_16x16x32_bf16 v[84:87], v[174:177], v[230:233], v[84:87]
	v_mfma_f32_16x16x32_bf16 v[80:83], v[188:191], v[230:233], v[80:83]
	v_mfma_f32_16x16x32_bf16 v[68:71], v[174:177], v[238:241], v[68:71]
	v_mfma_f32_16x16x32_bf16 v[64:67], v[188:191], v[238:241], v[64:67]
	v_mfma_f32_16x16x32_bf16 v[116:119], v[184:187], v[218:221], v[116:119]
	v_mfma_f32_16x16x32_bf16 v[112:115], v[210:213], v[218:221], v[112:115]
	v_mfma_f32_16x16x32_bf16 v[100:103], v[184:187], v[226:229], v[100:103]
	v_mfma_f32_16x16x32_bf16 v[96:99], v[210:213], v[226:229], v[96:99]
	v_mfma_f32_16x16x32_bf16 v[84:87], v[184:187], v[234:237], v[84:87]
	v_mfma_f32_16x16x32_bf16 v[80:83], v[210:213], v[234:237], v[80:83]
	v_mfma_f32_16x16x32_bf16 v[68:71], v[184:187], v[242:245], v[68:71]
	v_mfma_f32_16x16x32_bf16 v[64:67], v[210:213], v[242:245], v[64:67]
	s_setprio 0
	s_barrier
	s_mov_b32 m0, s47
	s_add_u32 s0, s4, 0xb0080
	s_addc_u32 s1, s5, 0
	ds_read_b128 v[214:217], v181 offset:49152
	ds_read_b128 v[218:221], v181 offset:50176
	ds_read_b128 v[222:225], v181 offset:51200
	ds_read_b128 v[226:229], v181 offset:52224
	ds_read_b128 v[230:233], v181 offset:53248
	ds_read_b128 v[234:237], v181 offset:54272
	ds_read_b128 v[238:241], v181 offset:55296
	ds_read_b128 v[242:245], v181 offset:56320
	s_add_u32 s98, s4, 0x80
	s_addc_u32 s99, s5, 0
	global_load_lds_dwordx4 v166, s[98:99]
	s_mov_b32 m0, s48
	s_nop 0
	global_load_lds_dwordx4 v162, s[98:99]
	s_mov_b32 m0, s51
	s_nop 0
	global_load_lds_dwordx4 v166, s[0:1]
	s_mov_b32 m0, s52
	s_nop 0
	global_load_lds_dwordx4 v162, s[0:1]
	s_mov_b32 m0, s49
	s_nop 0
	s_add_u32 s100, s6, 0x80
	s_addc_u32 s101, s7, 0
	global_load_lds_dwordx4 v168, s[100:101]
	s_mov_b32 m0, s50
	s_nop 0
	global_load_lds_dwordx4 v164, s[100:101]
	s_add_i32 s13, s13, 2
	s_add_u32 s10, s10, 0x100
	s_addc_u32 s11, s11, 0
	s_cmp_gt_u32 s13, 41
	s_mov_b64 s[0:1], s[2:3]
	s_waitcnt vmcnt(8)
	s_waitcnt lgkmcnt(0)
	s_barrier
	s_setprio 1
	v_mfma_f32_16x16x32_bf16 v[60:63], v[128:131], v[214:217], v[60:63]
	v_mfma_f32_16x16x32_bf16 v[56:59], v[136:139], v[214:217], v[56:59]
	v_mfma_f32_16x16x32_bf16 v[44:47], v[128:131], v[222:225], v[44:47]
	v_mfma_f32_16x16x32_bf16 v[40:43], v[136:139], v[222:225], v[40:43]
	v_mfma_f32_16x16x32_bf16 v[28:31], v[128:131], v[230:233], v[28:31]
	v_mfma_f32_16x16x32_bf16 v[24:27], v[136:139], v[230:233], v[24:27]
	v_mfma_f32_16x16x32_bf16 v[12:15], v[128:131], v[238:241], v[12:15]
	v_mfma_f32_16x16x32_bf16 v[8:11], v[136:139], v[238:241], v[8:11]
	v_mfma_f32_16x16x32_bf16 v[60:63], v[132:135], v[218:221], v[60:63]
	v_mfma_f32_16x16x32_bf16 v[56:59], v[140:143], v[218:221], v[56:59]
	v_mfma_f32_16x16x32_bf16 v[44:47], v[132:135], v[226:229], v[44:47]
	v_mfma_f32_16x16x32_bf16 v[40:43], v[140:143], v[226:229], v[40:43]
	v_mfma_f32_16x16x32_bf16 v[28:31], v[132:135], v[234:237], v[28:31]
	v_mfma_f32_16x16x32_bf16 v[24:27], v[140:143], v[234:237], v[24:27]
	v_mfma_f32_16x16x32_bf16 v[12:15], v[132:135], v[242:245], v[12:15]
	v_mfma_f32_16x16x32_bf16 v[8:11], v[140:143], v[242:245], v[8:11]
	v_mfma_f32_16x16x32_bf16 v[52:55], v[174:177], v[214:217], v[52:55]
	v_mfma_f32_16x16x32_bf16 v[48:51], v[188:191], v[214:217], v[48:51]
	v_mfma_f32_16x16x32_bf16 v[36:39], v[174:177], v[222:225], v[36:39]
	v_mfma_f32_16x16x32_bf16 v[32:35], v[188:191], v[222:225], v[32:35]
	v_mfma_f32_16x16x32_bf16 v[20:23], v[174:177], v[230:233], v[20:23]
	v_mfma_f32_16x16x32_bf16 v[16:19], v[188:191], v[230:233], v[16:19]
	v_mfma_f32_16x16x32_bf16 v[4:7], v[174:177], v[238:241], v[4:7]
	v_mfma_f32_16x16x32_bf16 v[0:3], v[188:191], v[238:241], v[0:3]
	v_mfma_f32_16x16x32_bf16 v[52:55], v[184:187], v[218:221], v[52:55]
	v_mfma_f32_16x16x32_bf16 v[48:51], v[210:213], v[218:221], v[48:51]
	v_mfma_f32_16x16x32_bf16 v[36:39], v[184:187], v[226:229], v[36:39]
	v_mfma_f32_16x16x32_bf16 v[32:35], v[210:213], v[226:229], v[32:35]
	v_mfma_f32_16x16x32_bf16 v[20:23], v[184:187], v[234:237], v[20:23]
	v_mfma_f32_16x16x32_bf16 v[16:19], v[210:213], v[234:237], v[16:19]
	v_mfma_f32_16x16x32_bf16 v[4:7], v[184:187], v[242:245], v[4:7]
	v_mfma_f32_16x16x32_bf16 v[0:3], v[210:213], v[242:245], v[0:3]
	s_setprio 0
	s_barrier
	s_cbranch_scc0 .LBB0_545
	s_and_b64 vcc, exec, s[22:23]
	s_cbranch_vccz .LBB0_548
	s_barrier

; #define PG8_STAGE(bufoff, gbase, voff) do { _Pragma("unroll") for (int _i = 0; _i < 2; ++_i) \
;         __builtin_amdgcn_global_load_lds((const unsigned*)((const char*)(gbase) + (voff)[_i]), (PG8_LAS unsigned*)(lds + (bufoff) + ldsw + _i * 8192), 16, 0, 0); } while (0)
; #define PG8_LDA(dst, b, h) do { _Pragma("unroll") for (int m = 0; m < 4; ++m) _Pragma("unroll") for (int k = 0; k < 2; ++k) dst[m][k] = *(const PG8_LAS bf16x8*)(lds + PG8_SA(b, h) + aoff + m * 2048 + k * 1024); } while (0)
; #define PG8_LDB(dst, b, h) do { _Pragma("unroll") for (int n = 0; n < 2; ++n) _Pragma("unroll") for (int k = 0; k < 2; ++k) dst[n][k] = *(const PG8_LAS bf16x8*)(lds + PG8_SB(b, h) + boff + n * 2048 + k * 1024); } while (0)
; #define PG8_MMA(ai, bj, At, Bt) do { __builtin_amdgcn_s_setprio(1); _Pragma("unroll") for (int m = 0; m < 4; ++m) _Pragma("unroll") for (int n = 0; n < 2; ++n) _Pragma("unroll") for (int k = 0; k < 2; ++k) \
;         acc[ai][bj][m][n] = __builtin_amdgcn_mfma_f32_16x16x32_bf16(Bt[n][k], At[m][k], acc[ai][bj][m][n], 0, 0, 0); __builtin_amdgcn_s_setprio(0); } while (0)
; #define PG8_WAIT_V(n) asm volatile("s_waitcnt vmcnt(" #n ")" ::: "memory")
; #define PG8_WAIT_L(n) asm volatile("s_waitcnt lgkmcnt(" #n ")" ::: "memory")
; #define PG8_BAR __builtin_amdgcn_s_barrier()
; #define PG8_SCHED __builtin_amdgcn_sched_barrier(0)
; template <class Epi, class Sched, bool ALIGN_EPI = false, bool SP2 = false>
; __device__ __forceinline__ void gemm_phase(PG8_LAS unsigned char* lds, const Gemm g, const Sched& S, const Epi& E) {
;     ...
;             PG8_LDB(B0, 0, 0); PG8_LDB(B1, 0, 1); PG8_SCHED; PG8_LDA(At, 0, 0); PG8_STAGE(PG8_SA(1, 1), a1 + hstep, voffA);
;             PG8_WAIT_V(8); PG8_WAIT_L(0); PG8_BAR; PG8_MMA(0, 0, At, B0); PG8_MMA(0, 1, At, B1); PG8_BAR; PG8_SCHED;
;             PG8_LDA(At, 0, 1); PG8_STAGE(PG8_SB(0, 0), b2, voffB); PG8_STAGE(PG8_SB(0, 1), b2 + hstep, voffB); PG8_STAGE(PG8_SA(0, 0), a2, voffA);
;             PG8_WAIT_V(8); PG8_WAIT_L(0); PG8_BAR; PG8_MMA(1, 0, At, B0); PG8_MMA(1, 1, At, B1); PG8_BAR; PG8_SCHED;
.Lsgi_peel:
	ds_read_b128 v[140:143], v254
	ds_read_b128 v[162:165], v254 offset:1024
	ds_read_b128 v[166:169], v254 offset:2048
	ds_read_b128 v[170:173], v254 offset:3072
	ds_read_b128 v[180:183], v254 offset:16384
	ds_read_b128 v[184:187], v254 offset:17408
	ds_read_b128 v[188:191], v254 offset:18432
	ds_read_b128 v[210:213], v254 offset:19456
	s_add_u32 s2, s0, 0xfffc0080
	s_addc_u32 s3, s1, -1
	s_cmp_eq_u32 s55, 12
	s_cselect_b32 s5, s13, s3
	s_cselect_b32 s4, s25, s2
	s_cselect_b32 s3, s23, s39
	s_cselect_b32 s2, s33, s38
	s_add_i32 m0, s6, 0xc000
	ds_read_b128 v[214:217], v178
	ds_read_b128 v[218:221], v178 offset:1024
	ds_read_b128 v[222:225], v178 offset:2048
	ds_read_b128 v[226:229], v178 offset:3072
	ds_read_b128 v[230:233], v178 offset:4096
	ds_read_b128 v[234:237], v178 offset:5120
	ds_read_b128 v[238:241], v178 offset:6144
	ds_read_b128 v[242:245], v178 offset:7168
	global_load_lds_dwordx4 v136, s[0:1]
	s_add_i32 m0, s6, 0xe000
	s_nop 0
	global_load_lds_dwordx4 v138, s[0:1]
	s_waitcnt vmcnt(8)
	s_waitcnt lgkmcnt(0)
	s_barrier
	s_setprio 1
	v_mfma_f32_16x16x32_bf16 v[124:127], v[140:143], v[214:217], 0
	v_mfma_f32_16x16x32_bf16 v[120:123], v[166:169], v[214:217], 0
	v_mfma_f32_16x16x32_bf16 v[108:111], v[140:143], v[222:225], 0
	v_mfma_f32_16x16x32_bf16 v[104:107], v[166:169], v[222:225], 0
	v_mfma_f32_16x16x32_bf16 v[92:95], v[140:143], v[230:233], 0
	v_mfma_f32_16x16x32_bf16 v[88:91], v[166:169], v[230:233], 0
	v_mfma_f32_16x16x32_bf16 v[76:79], v[140:143], v[238:241], 0
	v_mfma_f32_16x16x32_bf16 v[72:75], v[166:169], v[238:241], 0
	v_mfma_f32_16x16x32_bf16 v[124:127], v[162:165], v[218:221], v[124:127]
	v_mfma_f32_16x16x32_bf16 v[120:123], v[170:173], v[218:221], v[120:123]
	v_mfma_f32_16x16x32_bf16 v[108:111], v[162:165], v[226:229], v[108:111]
	v_mfma_f32_16x16x32_bf16 v[104:107], v[170:173], v[226:229], v[104:107]
	v_mfma_f32_16x16x32_bf16 v[92:95], v[162:165], v[234:237], v[92:95]
	v_mfma_f32_16x16x32_bf16 v[88:91], v[170:173], v[234:237], v[88:91]
	v_mfma_f32_16x16x32_bf16 v[76:79], v[162:165], v[242:245], v[76:79]
	v_mfma_f32_16x16x32_bf16 v[72:75], v[170:173], v[242:245], v[72:75]
	v_mfma_f32_16x16x32_bf16 v[116:119], v[180:183], v[214:217], 0
	v_mfma_f32_16x16x32_bf16 v[112:115], v[188:191], v[214:217], 0
	v_mfma_f32_16x16x32_bf16 v[100:103], v[180:183], v[222:225], 0
	v_mfma_f32_16x16x32_bf16 v[96:99], v[188:191], v[222:225], 0
	v_mfma_f32_16x16x32_bf16 v[84:87], v[180:183], v[230:233], 0
	v_mfma_f32_16x16x32_bf16 v[80:83], v[188:191], v[230:233], 0
	v_mfma_f32_16x16x32_bf16 v[68:71], v[180:183], v[238:241], 0
	v_mfma_f32_16x16x32_bf16 v[64:67], v[188:191], v[238:241], 0
	v_mfma_f32_16x16x32_bf16 v[116:119], v[184:187], v[218:221], v[116:119]
	v_mfma_f32_16x16x32_bf16 v[112:115], v[210:213], v[218:221], v[112:115]
	v_mfma_f32_16x16x32_bf16 v[100:103], v[184:187], v[226:229], v[100:103]
	v_mfma_f32_16x16x32_bf16 v[96:99], v[210:213], v[226:229], v[96:99]
	v_mfma_f32_16x16x32_bf16 v[84:87], v[184:187], v[234:237], v[84:87]
	v_mfma_f32_16x16x32_bf16 v[80:83], v[210:213], v[234:237], v[80:83]
	v_mfma_f32_16x16x32_bf16 v[68:71], v[184:187], v[242:245], v[68:71]
	v_mfma_f32_16x16x32_bf16 v[64:67], v[210:213], v[242:245], v[64:67]
	s_setprio 0
	s_barrier
	s_mov_b32 m0, s31
	s_add_u32 s56, s2, 0x40000
	s_addc_u32 s57, s3, 0
	ds_read_b128 v[214:217], v178 offset:16384
	ds_read_b128 v[218:221], v178 offset:17408
	ds_read_b128 v[222:225], v178 offset:18432
	ds_read_b128 v[226:229], v178 offset:19456
	ds_read_b128 v[230:233], v178 offset:20480
	ds_read_b128 v[234:237], v178 offset:21504
	ds_read_b128 v[238:241], v178 offset:22528
	ds_read_b128 v[242:245], v178 offset:23552
	global_load_lds_dwordx4 v132, s[2:3]
	s_mov_b32 m0, s34
	s_nop 0
	global_load_lds_dwordx4 v128, s[2:3]
	s_mov_b32 m0, s35
	s_nop 0
	global_load_lds_dwordx4 v132, s[56:57]
	s_mov_b32 m0, s40
	s_nop 0
	global_load_lds_dwordx4 v128, s[56:57]
	s_mov_b32 m0, s6
	s_nop 0
	global_load_lds_dwordx4 v134, s[4:5]
	s_mov_b32 m0, s41
	s_nop 0
	global_load_lds_dwordx4 v130, s[4:5]
	s_waitcnt vmcnt(8)
	s_waitcnt lgkmcnt(0)
	s_barrier
	s_setprio 1
	v_mfma_f32_16x16x32_bf16 v[60:63], v[140:143], v[214:217], 0
	v_mfma_f32_16x16x32_bf16 v[56:59], v[166:169], v[214:217], 0
	v_mfma_f32_16x16x32_bf16 v[44:47], v[140:143], v[222:225], 0
	v_mfma_f32_16x16x32_bf16 v[40:43], v[166:169], v[222:225], 0
	v_mfma_f32_16x16x32_bf16 v[28:31], v[140:143], v[230:233], 0
	v_mfma_f32_16x16x32_bf16 v[24:27], v[166:169], v[230:233], 0
	v_mfma_f32_16x16x32_bf16 v[12:15], v[140:143], v[238:241], 0
	v_mfma_f32_16x16x32_bf16 v[8:11], v[166:169], v[238:241], 0
	v_mfma_f32_16x16x32_bf16 v[60:63], v[162:165], v[218:221], v[60:63]
	v_mfma_f32_16x16x32_bf16 v[56:59], v[170:173], v[218:221], v[56:59]
	v_mfma_f32_16x16x32_bf16 v[44:47], v[162:165], v[226:229], v[44:47]
	v_mfma_f32_16x16x32_bf16 v[40:43], v[170:173], v[226:229], v[40:43]
	v_mfma_f32_16x16x32_bf16 v[28:31], v[162:165], v[234:237], v[28:31]
	v_mfma_f32_16x16x32_bf16 v[24:27], v[170:173], v[234:237], v[24:27]
	v_mfma_f32_16x16x32_bf16 v[12:15], v[162:165], v[242:245], v[12:15]
	v_mfma_f32_16x16x32_bf16 v[8:11], v[170:173], v[242:245], v[8:11]
	v_mfma_f32_16x16x32_bf16 v[52:55], v[180:183], v[214:217], 0
	v_mfma_f32_16x16x32_bf16 v[48:51], v[188:191], v[214:217], 0
	v_mfma_f32_16x16x32_bf16 v[36:39], v[180:183], v[222:225], 0
	v_mfma_f32_16x16x32_bf16 v[32:35], v[188:191], v[222:225], 0
	v_mfma_f32_16x16x32_bf16 v[20:23], v[180:183], v[230:233], 0
	v_mfma_f32_16x16x32_bf16 v[16:19], v[188:191], v[230:233], 0
	v_mfma_f32_16x16x32_bf16 v[4:7], v[180:183], v[238:241], 0
	v_mfma_f32_16x16x32_bf16 v[0:3], v[188:191], v[238:241], 0
	v_mfma_f32_16x16x32_bf16 v[52:55], v[184:187], v[218:221], v[52:55]
	v_mfma_f32_16x16x32_bf16 v[48:51], v[210:213], v[218:221], v[48:51]
	v_mfma_f32_16x16x32_bf16 v[36:39], v[184:187], v[226:229], v[36:39]
	v_mfma_f32_16x16x32_bf16 v[32:35], v[210:213], v[226:229], v[32:35]
	v_mfma_f32_16x16x32_bf16 v[20:23], v[184:187], v[234:237], v[20:23]
	v_mfma_f32_16x16x32_bf16 v[16:19], v[210:213], v[234:237], v[16:19]
	v_mfma_f32_16x16x32_bf16 v[4:7], v[184:187], v[242:245], v[4:7]
	v_mfma_f32_16x16x32_bf16 v[0:3], v[210:213], v[242:245], v[0:3]
	s_setprio 0
	s_barrier
; #define PG8_STAGE(bufoff, gbase, voff) do { _Pragma("unroll") for (int _i = 0; _i < 2; ++_i) \
;         __builtin_amdgcn_global_load_lds((const unsigned*)((const char*)(gbase) + (voff)[_i]), (PG8_LAS unsigned*)(lds + (bufoff) + ldsw + _i * 8192), 16, 0, 0); } while (0)
; #define PG8_LDA(dst, b, h) do { _Pragma("unroll") for (int m = 0; m < 4; ++m) _Pragma("unroll") for (int k = 0; k < 2; ++k) dst[m][k] = *(const PG8_LAS bf16x8*)(lds + PG8_SA(b, h) + aoff + m * 2048 + k * 1024); } while (0)
; #define PG8_LDB(dst, b, h) do { _Pragma("unroll") for (int n = 0; n < 2; ++n) _Pragma("unroll") for (int k = 0; k < 2; ++k) dst[n][k] = *(const PG8_LAS bf16x8*)(lds + PG8_SB(b, h) + boff + n * 2048 + k * 1024); } while (0)
; #define PG8_MMA(ai, bj, At, Bt) do { __builtin_amdgcn_s_setprio(1); _Pragma("unroll") for (int m = 0; m < 4; ++m) _Pragma("unroll") for (int n = 0; n < 2; ++n) _Pragma("unroll") for (int k = 0; k < 2; ++k) \
;         acc[ai][bj][m][n] = __builtin_amdgcn_mfma_f32_16x16x32_bf16(Bt[n][k], At[m][k], acc[ai][bj][m][n], 0, 0, 0); __builtin_amdgcn_s_setprio(0); } while (0)
; #define PG8_WAIT_V(n) asm volatile("s_waitcnt vmcnt(" #n ")" ::: "memory")
; #define PG8_WAIT_L(n) asm volatile("s_waitcnt lgkmcnt(" #n ")" ::: "memory")
; #define PG8_BAR __builtin_amdgcn_s_barrier()
; #define PG8_SCHED __builtin_amdgcn_sched_barrier(0)
; template <class Epi, class Sched, bool ALIGN_EPI = false, bool SP2 = false>
; __device__ __forceinline__ void gemm_phase(PG8_LAS unsigned char* lds, const Gemm g, const Sched& S, const Epi& E) {
;     ...
;             PG8_LDB(B0, 1, 0); PG8_LDB(B1, 1, 1); PG8_SCHED; PG8_LDA(At, 1, 0); PG8_STAGE(PG8_SA(0, 1), a2 + hstep, voffA);
;             PG8_WAIT_V(8); PG8_WAIT_L(0); PG8_BAR; PG8_MMA(0, 0, At, B0); PG8_MMA(0, 1, At, B1); PG8_BAR; PG8_SCHED;
;             PG8_LDA(At, 1, 1); PG8_STAGE(PG8_SB(1, 0), b3, voffB); PG8_STAGE(PG8_SB(1, 1), b3 + hstep, voffB); PG8_STAGE(PG8_SA(1, 0), a3, voffA);
;             PG8_WAIT_V(8); PG8_WAIT_L(0); PG8_BAR; PG8_MMA(1, 0, At, B0); PG8_MMA(1, 1, At, B1); PG8_BAR; PG8_SCHED;
	ds_read_b128 v[140:143], v254 offset:32768
	ds_read_b128 v[162:165], v254 offset:33792
	ds_read_b128 v[166:169], v254 offset:34816
	ds_read_b128 v[170:173], v254 offset:35840
	ds_read_b128 v[180:183], v254 offset:49152
	ds_read_b128 v[184:187], v254 offset:50176
	ds_read_b128 v[188:191], v254 offset:51200
	ds_read_b128 v[210:213], v254 offset:52224
	s_add_u32 s4, s4, 0x40000
	s_addc_u32 s5, s5, 0
	s_mov_b32 m0, s42
	ds_read_b128 v[214:217], v178 offset:32768
	ds_read_b128 v[218:221], v178 offset:33792
	ds_read_b128 v[222:225], v178 offset:34816
	ds_read_b128 v[226:229], v178 offset:35840
	ds_read_b128 v[230:233], v178 offset:36864
	ds_read_b128 v[234:237], v178 offset:37888
	ds_read_b128 v[238:241], v178 offset:38912
	ds_read_b128 v[242:245], v178 offset:39936
	global_load_lds_dwordx4 v134, s[4:5]
	s_mov_b32 m0, s43
	s_nop 0
	global_load_lds_dwordx4 v130, s[4:5]
	s_waitcnt vmcnt(8)
	s_waitcnt lgkmcnt(0)
	s_barrier
	s_setprio 1
	v_mfma_f32_16x16x32_bf16 v[124:127], v[140:143], v[214:217], v[124:127]
	v_mfma_f32_16x16x32_bf16 v[120:123], v[166:169], v[214:217], v[120:123]
	v_mfma_f32_16x16x32_bf16 v[108:111], v[140:143], v[222:225], v[108:111]
	v_mfma_f32_16x16x32_bf16 v[104:107], v[166:169], v[222:225], v[104:107]
	v_mfma_f32_16x16x32_bf16 v[92:95], v[140:143], v[230:233], v[92:95]
	v_mfma_f32_16x16x32_bf16 v[88:91], v[166:169], v[230:233], v[88:91]
	v_mfma_f32_16x16x32_bf16 v[76:79], v[140:143], v[238:241], v[76:79]
	v_mfma_f32_16x16x32_bf16 v[72:75], v[166:169], v[238:241], v[72:75]
	v_mfma_f32_16x16x32_bf16 v[124:127], v[162:165], v[218:221], v[124:127]
	v_mfma_f32_16x16x32_bf16 v[120:123], v[170:173], v[218:221], v[120:123]
	v_mfma_f32_16x16x32_bf16 v[108:111], v[162:165], v[226:229], v[108:111]
	v_mfma_f32_16x16x32_bf16 v[104:107], v[170:173], v[226:229], v[104:107]
	v_mfma_f32_16x16x32_bf16 v[92:95], v[162:165], v[234:237], v[92:95]
	v_mfma_f32_16x16x32_bf16 v[88:91], v[170:173], v[234:237], v[88:91]
	v_mfma_f32_16x16x32_bf16 v[76:79], v[162:165], v[242:245], v[76:79]
	v_mfma_f32_16x16x32_bf16 v[72:75], v[170:173], v[242:245], v[72:75]
	v_mfma_f32_16x16x32_bf16 v[116:119], v[180:183], v[214:217], v[116:119]
	v_mfma_f32_16x16x32_bf16 v[112:115], v[188:191], v[214:217], v[112:115]
	v_mfma_f32_16x16x32_bf16 v[100:103], v[180:183], v[222:225], v[100:103]
	v_mfma_f32_16x16x32_bf16 v[96:99], v[188:191], v[222:225], v[96:99]
	v_mfma_f32_16x16x32_bf16 v[84:87], v[180:183], v[230:233], v[84:87]
	v_mfma_f32_16x16x32_bf16 v[80:83], v[188:191], v[230:233], v[80:83]
	v_mfma_f32_16x16x32_bf16 v[68:71], v[180:183], v[238:241], v[68:71]
	v_mfma_f32_16x16x32_bf16 v[64:67], v[188:191], v[238:241], v[64:67]
	v_mfma_f32_16x16x32_bf16 v[116:119], v[184:187], v[218:221], v[116:119]
	v_mfma_f32_16x16x32_bf16 v[112:115], v[210:213], v[218:221], v[112:115]
	v_mfma_f32_16x16x32_bf16 v[100:103], v[184:187], v[226:229], v[100:103]
	v_mfma_f32_16x16x32_bf16 v[96:99], v[210:213], v[226:229], v[96:99]
	v_mfma_f32_16x16x32_bf16 v[84:87], v[184:187], v[234:237], v[84:87]
	v_mfma_f32_16x16x32_bf16 v[80:83], v[210:213], v[234:237], v[80:83]
	v_mfma_f32_16x16x32_bf16 v[68:71], v[184:187], v[242:245], v[68:71]
	v_mfma_f32_16x16x32_bf16 v[64:67], v[210:213], v[242:245], v[64:67]
	s_setprio 0
	s_barrier
	s_mov_b32 m0, s48
	s_add_u32 s2, s2, 0x40080
	s_addc_u32 s3, s3, 0
	ds_read_b128 v[214:217], v178 offset:49152
	ds_read_b128 v[218:221], v178 offset:50176
	ds_read_b128 v[222:225], v178 offset:51200
	ds_read_b128 v[226:229], v178 offset:52224
	ds_read_b128 v[230:233], v178 offset:53248
	ds_read_b128 v[234:237], v178 offset:54272
	ds_read_b128 v[238:241], v178 offset:55296
	ds_read_b128 v[242:245], v178 offset:56320
	s_add_u32 s98, s2, 0xfffc0000
	s_addc_u32 s99, s3, -1
	global_load_lds_dwordx4 v132, s[98:99]
	s_mov_b32 m0, s49
	s_nop 0
	global_load_lds_dwordx4 v128, s[98:99]
	s_mov_b32 m0, s52
	s_nop 0
	global_load_lds_dwordx4 v132, s[2:3]
	s_mov_b32 m0, s53
	s_nop 0
	global_load_lds_dwordx4 v128, s[2:3]
	s_mov_b32 m0, s50
	s_nop 0
	s_add_u32 s100, s4, 0xfffc0080
	s_addc_u32 s101, s5, -1
	global_load_lds_dwordx4 v134, s[100:101]
	s_mov_b32 m0, s51
	s_nop 0
	global_load_lds_dwordx4 v130, s[100:101]
	s_add_i32 s55, s55, 2
	s_add_u32 s0, s0, 0x100
	s_addc_u32 s1, s1, 0
	s_add_u32 s38, s38, 0x100
	s_addc_u32 s39, s39, 0
	s_cmp_gt_u32 s55, 13
	s_waitcnt vmcnt(8)
	s_waitcnt lgkmcnt(0)
	s_barrier
	s_setprio 1
	v_mfma_f32_16x16x32_bf16 v[60:63], v[140:143], v[214:217], v[60:63]
	v_mfma_f32_16x16x32_bf16 v[56:59], v[166:169], v[214:217], v[56:59]
	v_mfma_f32_16x16x32_bf16 v[44:47], v[140:143], v[222:225], v[44:47]
	v_mfma_f32_16x16x32_bf16 v[40:43], v[166:169], v[222:225], v[40:43]
	v_mfma_f32_16x16x32_bf16 v[28:31], v[140:143], v[230:233], v[28:31]
	v_mfma_f32_16x16x32_bf16 v[24:27], v[166:169], v[230:233], v[24:27]
	v_mfma_f32_16x16x32_bf16 v[12:15], v[140:143], v[238:241], v[12:15]
	v_mfma_f32_16x16x32_bf16 v[8:11], v[166:169], v[238:241], v[8:11]
	v_mfma_f32_16x16x32_bf16 v[60:63], v[162:165], v[218:221], v[60:63]
	v_mfma_f32_16x16x32_bf16 v[56:59], v[170:173], v[218:221], v[56:59]
	v_mfma_f32_16x16x32_bf16 v[44:47], v[162:165], v[226:229], v[44:47]
	v_mfma_f32_16x16x32_bf16 v[40:43], v[170:173], v[226:229], v[40:43]
	v_mfma_f32_16x16x32_bf16 v[28:31], v[162:165], v[234:237], v[28:31]
	v_mfma_f32_16x16x32_bf16 v[24:27], v[170:173], v[234:237], v[24:27]
	v_mfma_f32_16x16x32_bf16 v[12:15], v[162:165], v[242:245], v[12:15]
	v_mfma_f32_16x16x32_bf16 v[8:11], v[170:173], v[242:245], v[8:11]
	v_mfma_f32_16x16x32_bf16 v[52:55], v[180:183], v[214:217], v[52:55]
	v_mfma_f32_16x16x32_bf16 v[48:51], v[188:191], v[214:217], v[48:51]
	v_mfma_f32_16x16x32_bf16 v[36:39], v[180:183], v[222:225], v[36:39]
	v_mfma_f32_16x16x32_bf16 v[32:35], v[188:191], v[222:225], v[32:35]
	v_mfma_f32_16x16x32_bf16 v[20:23], v[180:183], v[230:233], v[20:23]
	v_mfma_f32_16x16x32_bf16 v[16:19], v[188:191], v[230:233], v[16:19]
	v_mfma_f32_16x16x32_bf16 v[4:7], v[180:183], v[238:241], v[4:7]
	v_mfma_f32_16x16x32_bf16 v[0:3], v[188:191], v[238:241], v[0:3]
	v_mfma_f32_16x16x32_bf16 v[52:55], v[184:187], v[218:221], v[52:55]
	v_mfma_f32_16x16x32_bf16 v[48:51], v[210:213], v[218:221], v[48:51]
	v_mfma_f32_16x16x32_bf16 v[36:39], v[184:187], v[226:229], v[36:39]
	v_mfma_f32_16x16x32_bf16 v[32:35], v[210:213], v[226:229], v[32:35]
	v_mfma_f32_16x16x32_bf16 v[20:23], v[184:187], v[234:237], v[20:23]
	v_mfma_f32_16x16x32_bf16 v[16:19], v[210:213], v[234:237], v[16:19]
	v_mfma_f32_16x16x32_bf16 v[4:7], v[184:187], v[242:245], v[4:7]
	v_mfma_f32_16x16x32_bf16 v[0:3], v[210:213], v[242:245], v[0:3]
	s_setprio 0
	s_barrier
; #define PG8_STAGE(bufoff, gbase, voff) do { _Pragma("unroll") for (int _i = 0; _i < 2; ++_i) \
;         __builtin_amdgcn_global_load_lds((const unsigned*)((const char*)(gbase) + (voff)[_i]), (PG8_LAS unsigned*)(lds + (bufoff) + ldsw + _i * 8192), 16, 0, 0); } while (0)
; #define PG8_LDA(dst, b, h) do { _Pragma("unroll") for (int m = 0; m < 4; ++m) _Pragma("unroll") for (int k = 0; k < 2; ++k) dst[m][k] = *(const PG8_LAS bf16x8*)(lds + PG8_SA(b, h) + aoff + m * 2048 + k * 1024); } while (0)
; #define PG8_LDB(dst, b, h) do { _Pragma("unroll") for (int n = 0; n < 2; ++n) _Pragma("unroll") for (int k = 0; k < 2; ++k) dst[n][k] = *(const PG8_LAS bf16x8*)(lds + PG8_SB(b, h) + boff + n * 2048 + k * 1024); } while (0)
; #define PG8_MMA(ai, bj, At, Bt) do { __builtin_amdgcn_s_setprio(1); _Pragma("unroll") for (int m = 0; m < 4; ++m) _Pragma("unroll") for (int n = 0; n < 2; ++n) _Pragma("unroll") for (int k = 0; k < 2; ++k) \
;         acc[ai][bj][m][n] = __builtin_amdgcn_mfma_f32_16x16x32_bf16(Bt[n][k], At[m][k], acc[ai][bj][m][n], 0, 0, 0); __builtin_amdgcn_s_setprio(0); } while (0)
; #define PG8_WAIT_V(n) asm volatile("s_waitcnt vmcnt(" #n ")" ::: "memory")
; #define PG8_WAIT_L(n) asm volatile("s_waitcnt lgkmcnt(" #n ")" ::: "memory")
; #define PG8_BAR __builtin_amdgcn_s_barrier()
; #define PG8_SCHED __builtin_amdgcn_sched_barrier(0)
; template <class Epi, class Sched, bool ALIGN_EPI = false, bool SP2 = false>
; __device__ __forceinline__ void gemm_phase(PG8_LAS unsigned char* lds, const Gemm g, const Sched& S, const Epi& E) {
;     ...
;             PG8_LDB(B0, 0, 0); PG8_LDB(B1, 0, 1); PG8_SCHED; PG8_LDA(At, 0, 0); PG8_STAGE(PG8_SA(1, 1), a1 + hstep, voffA);
;             PG8_WAIT_V(8); PG8_WAIT_L(0); PG8_BAR; PG8_MMA(0, 0, At, B0); PG8_MMA(0, 1, At, B1); PG8_BAR; PG8_SCHED;
;             PG8_LDA(At, 0, 1); PG8_STAGE(PG8_SB(0, 0), b2, voffB); PG8_STAGE(PG8_SB(0, 1), b2 + hstep, voffB); PG8_STAGE(PG8_SA(0, 0), a2, voffA);
;             PG8_WAIT_V(8); PG8_WAIT_L(0); PG8_BAR; PG8_MMA(1, 0, At, B0); PG8_MMA(1, 1, At, B1); PG8_BAR; PG8_SCHED;
.LBB0_749:
	ds_read_b128 v[140:143], v254
	ds_read_b128 v[162:165], v254 offset:1024
	ds_read_b128 v[166:169], v254 offset:2048
	ds_read_b128 v[170:173], v254 offset:3072
	ds_read_b128 v[180:183], v254 offset:16384
	ds_read_b128 v[184:187], v254 offset:17408
	ds_read_b128 v[188:191], v254 offset:18432
	ds_read_b128 v[210:213], v254 offset:19456
	s_add_u32 s2, s0, 0xfffc0080
	s_addc_u32 s3, s1, -1
	s_cmp_eq_u32 s55, 12
	s_cselect_b32 s5, s13, s3
	s_cselect_b32 s4, s25, s2
	s_cselect_b32 s3, s23, s39
	s_cselect_b32 s2, s33, s38
	s_add_i32 m0, s6, 0xc000
	ds_read_b128 v[214:217], v178
	ds_read_b128 v[218:221], v178 offset:1024
	ds_read_b128 v[222:225], v178 offset:2048
	ds_read_b128 v[226:229], v178 offset:3072
	ds_read_b128 v[230:233], v178 offset:4096
	ds_read_b128 v[234:237], v178 offset:5120
	ds_read_b128 v[238:241], v178 offset:6144
	ds_read_b128 v[242:245], v178 offset:7168
	global_load_lds_dwordx4 v136, s[0:1]
	s_add_i32 m0, s6, 0xe000
	s_nop 0
	global_load_lds_dwordx4 v138, s[0:1]
	s_waitcnt vmcnt(8)
	s_waitcnt lgkmcnt(0)
	s_barrier
	s_setprio 1
	v_mfma_f32_16x16x32_bf16 v[124:127], v[140:143], v[214:217], v[124:127]
	v_mfma_f32_16x16x32_bf16 v[120:123], v[166:169], v[214:217], v[120:123]
	v_mfma_f32_16x16x32_bf16 v[108:111], v[140:143], v[222:225], v[108:111]
	v_mfma_f32_16x16x32_bf16 v[104:107], v[166:169], v[222:225], v[104:107]
	v_mfma_f32_16x16x32_bf16 v[92:95], v[140:143], v[230:233], v[92:95]
	v_mfma_f32_16x16x32_bf16 v[88:91], v[166:169], v[230:233], v[88:91]
	v_mfma_f32_16x16x32_bf16 v[76:79], v[140:143], v[238:241], v[76:79]
	v_mfma_f32_16x16x32_bf16 v[72:75], v[166:169], v[238:241], v[72:75]
	v_mfma_f32_16x16x32_bf16 v[124:127], v[162:165], v[218:221], v[124:127]
	v_mfma_f32_16x16x32_bf16 v[120:123], v[170:173], v[218:221], v[120:123]
	v_mfma_f32_16x16x32_bf16 v[108:111], v[162:165], v[226:229], v[108:111]
	v_mfma_f32_16x16x32_bf16 v[104:107], v[170:173], v[226:229], v[104:107]
	v_mfma_f32_16x16x32_bf16 v[92:95], v[162:165], v[234:237], v[92:95]
	v_mfma_f32_16x16x32_bf16 v[88:91], v[170:173], v[234:237], v[88:91]
	v_mfma_f32_16x16x32_bf16 v[76:79], v[162:165], v[242:245], v[76:79]
	v_mfma_f32_16x16x32_bf16 v[72:75], v[170:173], v[242:245], v[72:75]
	v_mfma_f32_16x16x32_bf16 v[116:119], v[180:183], v[214:217], v[116:119]
	v_mfma_f32_16x16x32_bf16 v[112:115], v[188:191], v[214:217], v[112:115]
	v_mfma_f32_16x16x32_bf16 v[100:103], v[180:183], v[222:225], v[100:103]
	v_mfma_f32_16x16x32_bf16 v[96:99], v[188:191], v[222:225], v[96:99]
	v_mfma_f32_16x16x32_bf16 v[84:87], v[180:183], v[230:233], v[84:87]
	v_mfma_f32_16x16x32_bf16 v[80:83], v[188:191], v[230:233], v[80:83]
	v_mfma_f32_16x16x32_bf16 v[68:71], v[180:183], v[238:241], v[68:71]
	v_mfma_f32_16x16x32_bf16 v[64:67], v[188:191], v[238:241], v[64:67]
	v_mfma_f32_16x16x32_bf16 v[116:119], v[184:187], v[218:221], v[116:119]
	v_mfma_f32_16x16x32_bf16 v[112:115], v[210:213], v[218:221], v[112:115]
	v_mfma_f32_16x16x32_bf16 v[100:103], v[184:187], v[226:229], v[100:103]
	v_mfma_f32_16x16x32_bf16 v[96:99], v[210:213], v[226:229], v[96:99]
	v_mfma_f32_16x16x32_bf16 v[84:87], v[184:187], v[234:237], v[84:87]
	v_mfma_f32_16x16x32_bf16 v[80:83], v[210:213], v[234:237], v[80:83]
	v_mfma_f32_16x16x32_bf16 v[68:71], v[184:187], v[242:245], v[68:71]
	v_mfma_f32_16x16x32_bf16 v[64:67], v[210:213], v[242:245], v[64:67]
	s_setprio 0
	s_barrier
	s_mov_b32 m0, s31
	s_add_u32 s56, s2, 0x40000
	s_addc_u32 s57, s3, 0
	ds_read_b128 v[214:217], v178 offset:16384
	ds_read_b128 v[218:221], v178 offset:17408
	ds_read_b128 v[222:225], v178 offset:18432
	ds_read_b128 v[226:229], v178 offset:19456
	ds_read_b128 v[230:233], v178 offset:20480
	ds_read_b128 v[234:237], v178 offset:21504
	ds_read_b128 v[238:241], v178 offset:22528
	ds_read_b128 v[242:245], v178 offset:23552
	global_load_lds_dwordx4 v132, s[2:3]
	s_mov_b32 m0, s34
	s_nop 0
	global_load_lds_dwordx4 v128, s[2:3]
	s_mov_b32 m0, s35
	s_nop 0
	global_load_lds_dwordx4 v132, s[56:57]
	s_mov_b32 m0, s40
	s_nop 0
	global_load_lds_dwordx4 v128, s[56:57]
	s_mov_b32 m0, s6
	s_nop 0
	global_load_lds_dwordx4 v134, s[4:5]
	s_mov_b32 m0, s41
	s_nop 0
	global_load_lds_dwordx4 v130, s[4:5]
	s_waitcnt vmcnt(8)
	s_waitcnt lgkmcnt(0)
	s_barrier
	s_setprio 1
	v_mfma_f32_16x16x32_bf16 v[60:63], v[140:143], v[214:217], v[60:63]
	v_mfma_f32_16x16x32_bf16 v[56:59], v[166:169], v[214:217], v[56:59]
	v_mfma_f32_16x16x32_bf16 v[44:47], v[140:143], v[222:225], v[44:47]
	v_mfma_f32_16x16x32_bf16 v[40:43], v[166:169], v[222:225], v[40:43]
	v_mfma_f32_16x16x32_bf16 v[28:31], v[140:143], v[230:233], v[28:31]
	v_mfma_f32_16x16x32_bf16 v[24:27], v[166:169], v[230:233], v[24:27]
	v_mfma_f32_16x16x32_bf16 v[12:15], v[140:143], v[238:241], v[12:15]
	v_mfma_f32_16x16x32_bf16 v[8:11], v[166:169], v[238:241], v[8:11]
	v_mfma_f32_16x16x32_bf16 v[60:63], v[162:165], v[218:221], v[60:63]
	v_mfma_f32_16x16x32_bf16 v[56:59], v[170:173], v[218:221], v[56:59]
	v_mfma_f32_16x16x32_bf16 v[44:47], v[162:165], v[226:229], v[44:47]
	v_mfma_f32_16x16x32_bf16 v[40:43], v[170:173], v[226:229], v[40:43]
	v_mfma_f32_16x16x32_bf16 v[28:31], v[162:165], v[234:237], v[28:31]
	v_mfma_f32_16x16x32_bf16 v[24:27], v[170:173], v[234:237], v[24:27]
	v_mfma_f32_16x16x32_bf16 v[12:15], v[162:165], v[242:245], v[12:15]
	v_mfma_f32_16x16x32_bf16 v[8:11], v[170:173], v[242:245], v[8:11]
	v_mfma_f32_16x16x32_bf16 v[52:55], v[180:183], v[214:217], v[52:55]
	v_mfma_f32_16x16x32_bf16 v[48:51], v[188:191], v[214:217], v[48:51]
	v_mfma_f32_16x16x32_bf16 v[36:39], v[180:183], v[222:225], v[36:39]
	v_mfma_f32_16x16x32_bf16 v[32:35], v[188:191], v[222:225], v[32:35]
	v_mfma_f32_16x16x32_bf16 v[20:23], v[180:183], v[230:233], v[20:23]
	v_mfma_f32_16x16x32_bf16 v[16:19], v[188:191], v[230:233], v[16:19]
	v_mfma_f32_16x16x32_bf16 v[4:7], v[180:183], v[238:241], v[4:7]
	v_mfma_f32_16x16x32_bf16 v[0:3], v[188:191], v[238:241], v[0:3]
	v_mfma_f32_16x16x32_bf16 v[52:55], v[184:187], v[218:221], v[52:55]
	v_mfma_f32_16x16x32_bf16 v[48:51], v[210:213], v[218:221], v[48:51]
	v_mfma_f32_16x16x32_bf16 v[36:39], v[184:187], v[226:229], v[36:39]
	v_mfma_f32_16x16x32_bf16 v[32:35], v[210:213], v[226:229], v[32:35]
	v_mfma_f32_16x16x32_bf16 v[20:23], v[184:187], v[234:237], v[20:23]
	v_mfma_f32_16x16x32_bf16 v[16:19], v[210:213], v[234:237], v[16:19]
	v_mfma_f32_16x16x32_bf16 v[4:7], v[184:187], v[242:245], v[4:7]
	v_mfma_f32_16x16x32_bf16 v[0:3], v[210:213], v[242:245], v[0:3]
	s_setprio 0
	s_barrier
; #define PG8_STAGE(bufoff, gbase, voff) do { _Pragma("unroll") for (int _i = 0; _i < 2; ++_i) \
;         __builtin_amdgcn_global_load_lds((const unsigned*)((const char*)(gbase) + (voff)[_i]), (PG8_LAS unsigned*)(lds + (bufoff) + ldsw + _i * 8192), 16, 0, 0); } while (0)
; #define PG8_LDA(dst, b, h) do { _Pragma("unroll") for (int m = 0; m < 4; ++m) _Pragma("unroll") for (int k = 0; k < 2; ++k) dst[m][k] = *(const PG8_LAS bf16x8*)(lds + PG8_SA(b, h) + aoff + m * 2048 + k * 1024); } while (0)
; #define PG8_LDB(dst, b, h) do { _Pragma("unroll") for (int n = 0; n < 2; ++n) _Pragma("unroll") for (int k = 0; k < 2; ++k) dst[n][k] = *(const PG8_LAS bf16x8*)(lds + PG8_SB(b, h) + boff + n * 2048 + k * 1024); } while (0)
; #define PG8_MMA(ai, bj, At, Bt) do { __builtin_amdgcn_s_setprio(1); _Pragma("unroll") for (int m = 0; m < 4; ++m) _Pragma("unroll") for (int n = 0; n < 2; ++n) _Pragma("unroll") for (int k = 0; k < 2; ++k) \
;         acc[ai][bj][m][n] = __builtin_amdgcn_mfma_f32_16x16x32_bf16(Bt[n][k], At[m][k], acc[ai][bj][m][n], 0, 0, 0); __builtin_amdgcn_s_setprio(0); } while (0)
; #define PG8_WAIT_V(n) asm volatile("s_waitcnt vmcnt(" #n ")" ::: "memory")
; #define PG8_WAIT_L(n) asm volatile("s_waitcnt lgkmcnt(" #n ")" ::: "memory")
; #define PG8_BAR __builtin_amdgcn_s_barrier()
; #define PG8_SCHED __builtin_amdgcn_sched_barrier(0)
; template <class Epi, class Sched, bool ALIGN_EPI = false, bool SP2 = false>
; __device__ __forceinline__ void gemm_phase(PG8_LAS unsigned char* lds, const Gemm g, const Sched& S, const Epi& E) {
;     ...
;             PG8_LDB(B0, 1, 0); PG8_LDB(B1, 1, 1); PG8_SCHED; PG8_LDA(At, 1, 0); PG8_STAGE(PG8_SA(0, 1), a2 + hstep, voffA);
;             PG8_WAIT_V(8); PG8_WAIT_L(0); PG8_BAR; PG8_MMA(0, 0, At, B0); PG8_MMA(0, 1, At, B1); PG8_BAR; PG8_SCHED;
;             PG8_LDA(At, 1, 1); PG8_STAGE(PG8_SB(1, 0), b3, voffB); PG8_STAGE(PG8_SB(1, 1), b3 + hstep, voffB); PG8_STAGE(PG8_SA(1, 0), a3, voffA);
;             PG8_WAIT_V(8); PG8_WAIT_L(0); PG8_BAR; PG8_MMA(1, 0, At, B0); PG8_MMA(1, 1, At, B1); PG8_BAR; PG8_SCHED;
;     ...
;         if constexpr (ALIGN_EPI) { if (wr == 0) PG8_BAR; }
	ds_read_b128 v[140:143], v254 offset:32768
	ds_read_b128 v[162:165], v254 offset:33792
	ds_read_b128 v[166:169], v254 offset:34816
	ds_read_b128 v[170:173], v254 offset:35840
	ds_read_b128 v[180:183], v254 offset:49152
	ds_read_b128 v[184:187], v254 offset:50176
	ds_read_b128 v[188:191], v254 offset:51200
	ds_read_b128 v[210:213], v254 offset:52224
	s_add_u32 s4, s4, 0x40000
	s_addc_u32 s5, s5, 0
	s_mov_b32 m0, s42
	ds_read_b128 v[214:217], v178 offset:32768
	ds_read_b128 v[218:221], v178 offset:33792
	ds_read_b128 v[222:225], v178 offset:34816
	ds_read_b128 v[226:229], v178 offset:35840
	ds_read_b128 v[230:233], v178 offset:36864
	ds_read_b128 v[234:237], v178 offset:37888
	ds_read_b128 v[238:241], v178 offset:38912
	ds_read_b128 v[242:245], v178 offset:39936
	global_load_lds_dwordx4 v134, s[4:5]
	s_mov_b32 m0, s43
	s_nop 0
	global_load_lds_dwordx4 v130, s[4:5]
	s_waitcnt vmcnt(8)
	s_waitcnt lgkmcnt(0)
	s_barrier
	s_setprio 1
	v_mfma_f32_16x16x32_bf16 v[124:127], v[140:143], v[214:217], v[124:127]
	v_mfma_f32_16x16x32_bf16 v[120:123], v[166:169], v[214:217], v[120:123]
	v_mfma_f32_16x16x32_bf16 v[108:111], v[140:143], v[222:225], v[108:111]
	v_mfma_f32_16x16x32_bf16 v[104:107], v[166:169], v[222:225], v[104:107]
	v_mfma_f32_16x16x32_bf16 v[92:95], v[140:143], v[230:233], v[92:95]
	v_mfma_f32_16x16x32_bf16 v[88:91], v[166:169], v[230:233], v[88:91]
	v_mfma_f32_16x16x32_bf16 v[76:79], v[140:143], v[238:241], v[76:79]
	v_mfma_f32_16x16x32_bf16 v[72:75], v[166:169], v[238:241], v[72:75]
	v_mfma_f32_16x16x32_bf16 v[124:127], v[162:165], v[218:221], v[124:127]
	v_mfma_f32_16x16x32_bf16 v[120:123], v[170:173], v[218:221], v[120:123]
	v_mfma_f32_16x16x32_bf16 v[108:111], v[162:165], v[226:229], v[108:111]
	v_mfma_f32_16x16x32_bf16 v[104:107], v[170:173], v[226:229], v[104:107]
	v_mfma_f32_16x16x32_bf16 v[92:95], v[162:165], v[234:237], v[92:95]
	v_mfma_f32_16x16x32_bf16 v[88:91], v[170:173], v[234:237], v[88:91]
	v_mfma_f32_16x16x32_bf16 v[76:79], v[162:165], v[242:245], v[76:79]
	v_mfma_f32_16x16x32_bf16 v[72:75], v[170:173], v[242:245], v[72:75]
	v_mfma_f32_16x16x32_bf16 v[116:119], v[180:183], v[214:217], v[116:119]
	v_mfma_f32_16x16x32_bf16 v[112:115], v[188:191], v[214:217], v[112:115]
	v_mfma_f32_16x16x32_bf16 v[100:103], v[180:183], v[222:225], v[100:103]
	v_mfma_f32_16x16x32_bf16 v[96:99], v[188:191], v[222:225], v[96:99]
	v_mfma_f32_16x16x32_bf16 v[84:87], v[180:183], v[230:233], v[84:87]
	v_mfma_f32_16x16x32_bf16 v[80:83], v[188:191], v[230:233], v[80:83]
	v_mfma_f32_16x16x32_bf16 v[68:71], v[180:183], v[238:241], v[68:71]
	v_mfma_f32_16x16x32_bf16 v[64:67], v[188:191], v[238:241], v[64:67]
	v_mfma_f32_16x16x32_bf16 v[116:119], v[184:187], v[218:221], v[116:119]
	v_mfma_f32_16x16x32_bf16 v[112:115], v[210:213], v[218:221], v[112:115]
	v_mfma_f32_16x16x32_bf16 v[100:103], v[184:187], v[226:229], v[100:103]
	v_mfma_f32_16x16x32_bf16 v[96:99], v[210:213], v[226:229], v[96:99]
	v_mfma_f32_16x16x32_bf16 v[84:87], v[184:187], v[234:237], v[84:87]
	v_mfma_f32_16x16x32_bf16 v[80:83], v[210:213], v[234:237], v[80:83]
	v_mfma_f32_16x16x32_bf16 v[68:71], v[184:187], v[242:245], v[68:71]
	v_mfma_f32_16x16x32_bf16 v[64:67], v[210:213], v[242:245], v[64:67]
	s_setprio 0
	s_barrier
	s_mov_b32 m0, s48
	s_add_u32 s2, s2, 0x40080
	s_addc_u32 s3, s3, 0
	ds_read_b128 v[214:217], v178 offset:49152
	ds_read_b128 v[218:221], v178 offset:50176
	ds_read_b128 v[222:225], v178 offset:51200
	ds_read_b128 v[226:229], v178 offset:52224
	ds_read_b128 v[230:233], v178 offset:53248
	ds_read_b128 v[234:237], v178 offset:54272
	ds_read_b128 v[238:241], v178 offset:55296
	ds_read_b128 v[242:245], v178 offset:56320
	s_add_u32 s98, s2, 0xfffc0000
	s_addc_u32 s99, s3, -1
	global_load_lds_dwordx4 v132, s[98:99]
	s_mov_b32 m0, s49
	s_nop 0
	global_load_lds_dwordx4 v128, s[98:99]
	s_mov_b32 m0, s52
	s_nop 0
	global_load_lds_dwordx4 v132, s[2:3]
	s_mov_b32 m0, s53
	s_nop 0
	global_load_lds_dwordx4 v128, s[2:3]
	s_mov_b32 m0, s50
	s_nop 0
	s_add_u32 s100, s4, 0xfffc0080
	s_addc_u32 s101, s5, -1
	global_load_lds_dwordx4 v134, s[100:101]
	s_mov_b32 m0, s51
	s_nop 0
	global_load_lds_dwordx4 v130, s[100:101]
	s_add_i32 s55, s55, 2
	s_add_u32 s0, s0, 0x100
	s_addc_u32 s1, s1, 0
	s_add_u32 s38, s38, 0x100
	s_addc_u32 s39, s39, 0
	s_cmp_gt_u32 s55, 13
	s_waitcnt vmcnt(8)
	s_waitcnt lgkmcnt(0)
	s_barrier
	s_setprio 1
	v_mfma_f32_16x16x32_bf16 v[60:63], v[140:143], v[214:217], v[60:63]
	v_mfma_f32_16x16x32_bf16 v[56:59], v[166:169], v[214:217], v[56:59]
	v_mfma_f32_16x16x32_bf16 v[44:47], v[140:143], v[222:225], v[44:47]
	v_mfma_f32_16x16x32_bf16 v[40:43], v[166:169], v[222:225], v[40:43]
	v_mfma_f32_16x16x32_bf16 v[28:31], v[140:143], v[230:233], v[28:31]
	v_mfma_f32_16x16x32_bf16 v[24:27], v[166:169], v[230:233], v[24:27]
	v_mfma_f32_16x16x32_bf16 v[12:15], v[140:143], v[238:241], v[12:15]
	v_mfma_f32_16x16x32_bf16 v[8:11], v[166:169], v[238:241], v[8:11]
	v_mfma_f32_16x16x32_bf16 v[60:63], v[162:165], v[218:221], v[60:63]
	v_mfma_f32_16x16x32_bf16 v[56:59], v[170:173], v[218:221], v[56:59]
	v_mfma_f32_16x16x32_bf16 v[44:47], v[162:165], v[226:229], v[44:47]
	v_mfma_f32_16x16x32_bf16 v[40:43], v[170:173], v[226:229], v[40:43]
	v_mfma_f32_16x16x32_bf16 v[28:31], v[162:165], v[234:237], v[28:31]
	v_mfma_f32_16x16x32_bf16 v[24:27], v[170:173], v[234:237], v[24:27]
	v_mfma_f32_16x16x32_bf16 v[12:15], v[162:165], v[242:245], v[12:15]
	v_mfma_f32_16x16x32_bf16 v[8:11], v[170:173], v[242:245], v[8:11]
	v_mfma_f32_16x16x32_bf16 v[52:55], v[180:183], v[214:217], v[52:55]
	v_mfma_f32_16x16x32_bf16 v[48:51], v[188:191], v[214:217], v[48:51]
	v_mfma_f32_16x16x32_bf16 v[36:39], v[180:183], v[222:225], v[36:39]
	v_mfma_f32_16x16x32_bf16 v[32:35], v[188:191], v[222:225], v[32:35]
	v_mfma_f32_16x16x32_bf16 v[20:23], v[180:183], v[230:233], v[20:23]
	v_mfma_f32_16x16x32_bf16 v[16:19], v[188:191], v[230:233], v[16:19]
	v_mfma_f32_16x16x32_bf16 v[4:7], v[180:183], v[238:241], v[4:7]
	v_mfma_f32_16x16x32_bf16 v[0:3], v[188:191], v[238:241], v[0:3]
	v_mfma_f32_16x16x32_bf16 v[52:55], v[184:187], v[218:221], v[52:55]
	v_mfma_f32_16x16x32_bf16 v[48:51], v[210:213], v[218:221], v[48:51]
	v_mfma_f32_16x16x32_bf16 v[36:39], v[184:187], v[226:229], v[36:39]
	v_mfma_f32_16x16x32_bf16 v[32:35], v[210:213], v[226:229], v[32:35]
	v_mfma_f32_16x16x32_bf16 v[20:23], v[184:187], v[234:237], v[20:23]
	v_mfma_f32_16x16x32_bf16 v[16:19], v[210:213], v[234:237], v[16:19]
	v_mfma_f32_16x16x32_bf16 v[4:7], v[184:187], v[242:245], v[4:7]
	v_mfma_f32_16x16x32_bf16 v[0:3], v[210:213], v[242:245], v[0:3]
	s_setprio 0
	s_barrier
	s_cbranch_scc0 .LBB0_749
	s_and_b64 vcc, exec, s[18:19]
	s_cbranch_vccz .LBB0_752
	s_barrier

; #define PG8_STAGE(bufoff, gbase, voff) do { _Pragma("unroll") for (int _i = 0; _i < 2; ++_i) \
;         __builtin_amdgcn_global_load_lds((const unsigned*)((const char*)(gbase) + (voff)[_i]), (PG8_LAS unsigned*)(lds + (bufoff) + ldsw + _i * 8192), 16, 0, 0); } while (0)
; #define PG8_LDA(dst, b, h) do { _Pragma("unroll") for (int m = 0; m < 4; ++m) _Pragma("unroll") for (int k = 0; k < 2; ++k) dst[m][k] = *(const PG8_LAS bf16x8*)(lds + PG8_SA(b, h) + aoff + m * 2048 + k * 1024); } while (0)
; #define PG8_LDB(dst, b, h) do { _Pragma("unroll") for (int n = 0; n < 2; ++n) _Pragma("unroll") for (int k = 0; k < 2; ++k) dst[n][k] = *(const PG8_LAS bf16x8*)(lds + PG8_SB(b, h) + boff + n * 2048 + k * 1024); } while (0)
; #define PG8_MMA(ai, bj, At, Bt) do { __builtin_amdgcn_s_setprio(1); _Pragma("unroll") for (int m = 0; m < 4; ++m) _Pragma("unroll") for (int n = 0; n < 2; ++n) _Pragma("unroll") for (int k = 0; k < 2; ++k) \
;         acc[ai][bj][m][n] = __builtin_amdgcn_mfma_f32_16x16x32_bf16(Bt[n][k], At[m][k], acc[ai][bj][m][n], 0, 0, 0); __builtin_amdgcn_s_setprio(0); } while (0)
; #define PG8_WAIT_V(n) asm volatile("s_waitcnt vmcnt(" #n ")" ::: "memory")
; #define PG8_WAIT_L(n) asm volatile("s_waitcnt lgkmcnt(" #n ")" ::: "memory")
; #define PG8_BAR __builtin_amdgcn_s_barrier()
; #define PG8_SCHED __builtin_amdgcn_sched_barrier(0)
; template <class Epi, class Sched, bool ALIGN_EPI = false, bool SP2 = false>
; __device__ __forceinline__ void gemm_phase(PG8_LAS unsigned char* lds, const Gemm g, const Sched& S, const Epi& E) {
;     ...
;             PG8_LDB(B0, 0, 0); PG8_LDB(B1, 0, 1); PG8_SCHED; PG8_LDA(At, 0, 0); PG8_STAGE(PG8_SA(1, 1), a1 + hstep, voffA);
;             PG8_WAIT_V(8); PG8_WAIT_L(0); PG8_BAR; PG8_MMA(0, 0, At, B0); PG8_MMA(0, 1, At, B1); PG8_BAR; PG8_SCHED;
;             PG8_LDA(At, 0, 1); PG8_STAGE(PG8_SB(0, 0), b2, voffB); PG8_STAGE(PG8_SB(0, 1), b2 + hstep, voffB); PG8_STAGE(PG8_SA(0, 0), a2, voffA);
;             PG8_WAIT_V(8); PG8_WAIT_L(0); PG8_BAR; PG8_MMA(1, 0, At, B0); PG8_MMA(1, 1, At, B1); PG8_BAR; PG8_SCHED;
.Labi_peel:
	s_waitcnt lgkmcnt(0)
	ds_read_b128 v[140:143], v254
	ds_read_b128 v[162:165], v254 offset:1024
	ds_read_b128 v[166:169], v254 offset:2048
	ds_read_b128 v[176:179], v254 offset:3072
	ds_read_b128 v[180:183], v254 offset:16384
	ds_read_b128 v[184:187], v254 offset:17408
	ds_read_b128 v[188:191], v254 offset:18432
	ds_read_b128 v[210:213], v254 offset:19456
	s_add_u32 s2, s0, 0xfffc0080
	s_addc_u32 s3, s1, -1
	s_cmp_eq_u32 s52, 12
	s_cselect_b32 s5, s17, s3
	s_cselect_b32 s4, s48, s2
	s_cselect_b32 s3, s15, s51
	s_cselect_b32 s2, s49, s50
	s_add_i32 m0, s6, 0xc000
	ds_read_b128 v[214:217], v173
	ds_read_b128 v[218:221], v173 offset:1024
	ds_read_b128 v[222:225], v173 offset:2048
	ds_read_b128 v[226:229], v173 offset:3072
	ds_read_b128 v[230:233], v173 offset:4096
	ds_read_b128 v[234:237], v173 offset:5120
	ds_read_b128 v[238:241], v173 offset:6144
	ds_read_b128 v[242:245], v173 offset:7168
	global_load_lds_dwordx4 v136, s[0:1]
	s_add_i32 m0, s6, 0xe000
	s_nop 0
	global_load_lds_dwordx4 v138, s[0:1]
	s_waitcnt vmcnt(8)
	s_waitcnt lgkmcnt(0)
	s_barrier
	s_setprio 1
	v_mfma_f32_16x16x32_bf16 v[124:127], v[140:143], v[214:217], 0
	v_mfma_f32_16x16x32_bf16 v[120:123], v[166:169], v[214:217], 0
	v_mfma_f32_16x16x32_bf16 v[112:115], v[140:143], v[222:225], 0
	v_mfma_f32_16x16x32_bf16 v[104:107], v[166:169], v[222:225], 0
	v_mfma_f32_16x16x32_bf16 v[96:99], v[140:143], v[230:233], 0
	v_mfma_f32_16x16x32_bf16 v[88:91], v[166:169], v[230:233], 0
	v_mfma_f32_16x16x32_bf16 v[80:83], v[140:143], v[238:241], 0
	v_mfma_f32_16x16x32_bf16 v[72:75], v[166:169], v[238:241], 0
	v_mfma_f32_16x16x32_bf16 v[124:127], v[162:165], v[218:221], v[124:127]
	v_mfma_f32_16x16x32_bf16 v[120:123], v[176:179], v[218:221], v[120:123]
	v_mfma_f32_16x16x32_bf16 v[112:115], v[162:165], v[226:229], v[112:115]
	v_mfma_f32_16x16x32_bf16 v[104:107], v[176:179], v[226:229], v[104:107]
	v_mfma_f32_16x16x32_bf16 v[96:99], v[162:165], v[234:237], v[96:99]
	v_mfma_f32_16x16x32_bf16 v[88:91], v[176:179], v[234:237], v[88:91]
	v_mfma_f32_16x16x32_bf16 v[80:83], v[162:165], v[242:245], v[80:83]
	v_mfma_f32_16x16x32_bf16 v[72:75], v[176:179], v[242:245], v[72:75]
	v_mfma_f32_16x16x32_bf16 v[116:119], v[180:183], v[214:217], 0
	v_mfma_f32_16x16x32_bf16 v[108:111], v[188:191], v[214:217], 0
	v_mfma_f32_16x16x32_bf16 v[100:103], v[180:183], v[222:225], 0
	v_mfma_f32_16x16x32_bf16 v[92:95], v[188:191], v[222:225], 0
	v_mfma_f32_16x16x32_bf16 v[84:87], v[180:183], v[230:233], 0
	v_mfma_f32_16x16x32_bf16 v[76:79], v[188:191], v[230:233], 0
	v_mfma_f32_16x16x32_bf16 v[68:71], v[180:183], v[238:241], 0
	v_mfma_f32_16x16x32_bf16 v[64:67], v[188:191], v[238:241], 0
	v_mfma_f32_16x16x32_bf16 v[116:119], v[184:187], v[218:221], v[116:119]
	v_mfma_f32_16x16x32_bf16 v[108:111], v[210:213], v[218:221], v[108:111]
	v_mfma_f32_16x16x32_bf16 v[100:103], v[184:187], v[226:229], v[100:103]
	v_mfma_f32_16x16x32_bf16 v[92:95], v[210:213], v[226:229], v[92:95]
	v_mfma_f32_16x16x32_bf16 v[84:87], v[184:187], v[234:237], v[84:87]
	v_mfma_f32_16x16x32_bf16 v[76:79], v[210:213], v[234:237], v[76:79]
	v_mfma_f32_16x16x32_bf16 v[68:71], v[184:187], v[242:245], v[68:71]
	v_mfma_f32_16x16x32_bf16 v[64:67], v[210:213], v[242:245], v[64:67]
	s_setprio 0
	s_barrier
	s_mov_b32 m0, s27
	s_add_u32 s54, s2, 0x40000
	s_addc_u32 s55, s3, 0
	ds_read_b128 v[214:217], v173 offset:16384
	ds_read_b128 v[218:221], v173 offset:17408
	ds_read_b128 v[222:225], v173 offset:18432
	ds_read_b128 v[226:229], v173 offset:19456
	ds_read_b128 v[230:233], v173 offset:20480
	ds_read_b128 v[234:237], v173 offset:21504
	ds_read_b128 v[238:241], v173 offset:22528
	ds_read_b128 v[242:245], v173 offset:23552
	global_load_lds_dwordx4 v132, s[2:3]
	s_mov_b32 m0, s28
	s_nop 0
	global_load_lds_dwordx4 v128, s[2:3]
	s_mov_b32 m0, s29
	s_nop 0
	global_load_lds_dwordx4 v132, s[54:55]
	s_mov_b32 m0, s30
	s_nop 0
	global_load_lds_dwordx4 v128, s[54:55]
	s_mov_b32 m0, s6
	s_nop 0
	global_load_lds_dwordx4 v134, s[4:5]
	s_mov_b32 m0, s31
	s_nop 0
	global_load_lds_dwordx4 v130, s[4:5]
	s_waitcnt vmcnt(8)
	s_waitcnt lgkmcnt(0)
	s_barrier
	s_setprio 1
	v_mfma_f32_16x16x32_bf16 v[60:63], v[140:143], v[214:217], 0
	v_mfma_f32_16x16x32_bf16 v[56:59], v[166:169], v[214:217], 0
	v_mfma_f32_16x16x32_bf16 v[48:51], v[140:143], v[222:225], 0
	v_mfma_f32_16x16x32_bf16 v[40:43], v[166:169], v[222:225], 0
	v_mfma_f32_16x16x32_bf16 v[32:35], v[140:143], v[230:233], 0
	v_mfma_f32_16x16x32_bf16 v[24:27], v[166:169], v[230:233], 0
	v_mfma_f32_16x16x32_bf16 v[16:19], v[140:143], v[238:241], 0
	v_mfma_f32_16x16x32_bf16 v[8:11], v[166:169], v[238:241], 0
	v_mfma_f32_16x16x32_bf16 v[60:63], v[162:165], v[218:221], v[60:63]
	v_mfma_f32_16x16x32_bf16 v[56:59], v[176:179], v[218:221], v[56:59]
	v_mfma_f32_16x16x32_bf16 v[48:51], v[162:165], v[226:229], v[48:51]
	v_mfma_f32_16x16x32_bf16 v[40:43], v[176:179], v[226:229], v[40:43]
	v_mfma_f32_16x16x32_bf16 v[32:35], v[162:165], v[234:237], v[32:35]
	v_mfma_f32_16x16x32_bf16 v[24:27], v[176:179], v[234:237], v[24:27]
	v_mfma_f32_16x16x32_bf16 v[16:19], v[162:165], v[242:245], v[16:19]
	v_mfma_f32_16x16x32_bf16 v[8:11], v[176:179], v[242:245], v[8:11]
	v_mfma_f32_16x16x32_bf16 v[52:55], v[180:183], v[214:217], 0
	v_mfma_f32_16x16x32_bf16 v[44:47], v[188:191], v[214:217], 0
	v_mfma_f32_16x16x32_bf16 v[36:39], v[180:183], v[222:225], 0
	v_mfma_f32_16x16x32_bf16 v[28:31], v[188:191], v[222:225], 0
	v_mfma_f32_16x16x32_bf16 v[20:23], v[180:183], v[230:233], 0
	v_mfma_f32_16x16x32_bf16 v[12:15], v[188:191], v[230:233], 0
	v_mfma_f32_16x16x32_bf16 v[4:7], v[180:183], v[238:241], 0
	v_mfma_f32_16x16x32_bf16 v[0:3], v[188:191], v[238:241], 0
	v_mfma_f32_16x16x32_bf16 v[52:55], v[184:187], v[218:221], v[52:55]
	v_mfma_f32_16x16x32_bf16 v[44:47], v[210:213], v[218:221], v[44:47]
	v_mfma_f32_16x16x32_bf16 v[36:39], v[184:187], v[226:229], v[36:39]
	v_mfma_f32_16x16x32_bf16 v[28:31], v[210:213], v[226:229], v[28:31]
	v_mfma_f32_16x16x32_bf16 v[20:23], v[184:187], v[234:237], v[20:23]
	v_mfma_f32_16x16x32_bf16 v[12:15], v[210:213], v[234:237], v[12:15]
	v_mfma_f32_16x16x32_bf16 v[4:7], v[184:187], v[242:245], v[4:7]
	v_mfma_f32_16x16x32_bf16 v[0:3], v[210:213], v[242:245], v[0:3]
	s_setprio 0
	s_barrier
; #define PG8_STAGE(bufoff, gbase, voff) do { _Pragma("unroll") for (int _i = 0; _i < 2; ++_i) \
;         __builtin_amdgcn_global_load_lds((const unsigned*)((const char*)(gbase) + (voff)[_i]), (PG8_LAS unsigned*)(lds + (bufoff) + ldsw + _i * 8192), 16, 0, 0); } while (0)
; #define PG8_LDA(dst, b, h) do { _Pragma("unroll") for (int m = 0; m < 4; ++m) _Pragma("unroll") for (int k = 0; k < 2; ++k) dst[m][k] = *(const PG8_LAS bf16x8*)(lds + PG8_SA(b, h) + aoff + m * 2048 + k * 1024); } while (0)
; #define PG8_LDB(dst, b, h) do { _Pragma("unroll") for (int n = 0; n < 2; ++n) _Pragma("unroll") for (int k = 0; k < 2; ++k) dst[n][k] = *(const PG8_LAS bf16x8*)(lds + PG8_SB(b, h) + boff + n * 2048 + k * 1024); } while (0)
; #define PG8_MMA(ai, bj, At, Bt) do { __builtin_amdgcn_s_setprio(1); _Pragma("unroll") for (int m = 0; m < 4; ++m) _Pragma("unroll") for (int n = 0; n < 2; ++n) _Pragma("unroll") for (int k = 0; k < 2; ++k) \
;         acc[ai][bj][m][n] = __builtin_amdgcn_mfma_f32_16x16x32_bf16(Bt[n][k], At[m][k], acc[ai][bj][m][n], 0, 0, 0); __builtin_amdgcn_s_setprio(0); } while (0)
; #define PG8_WAIT_V(n) asm volatile("s_waitcnt vmcnt(" #n ")" ::: "memory")
; #define PG8_WAIT_L(n) asm volatile("s_waitcnt lgkmcnt(" #n ")" ::: "memory")
; #define PG8_BAR __builtin_amdgcn_s_barrier()
; #define PG8_SCHED __builtin_amdgcn_sched_barrier(0)
; template <class Epi, class Sched, bool ALIGN_EPI = false, bool SP2 = false>
; __device__ __forceinline__ void gemm_phase(PG8_LAS unsigned char* lds, const Gemm g, const Sched& S, const Epi& E) {
;     ...
;             PG8_LDB(B0, 1, 0); PG8_LDB(B1, 1, 1); PG8_SCHED; PG8_LDA(At, 1, 0); PG8_STAGE(PG8_SA(0, 1), a2 + hstep, voffA);
;             PG8_WAIT_V(8); PG8_WAIT_L(0); PG8_BAR; PG8_MMA(0, 0, At, B0); PG8_MMA(0, 1, At, B1); PG8_BAR; PG8_SCHED;
;             PG8_LDA(At, 1, 1); PG8_STAGE(PG8_SB(1, 0), b3, voffB); PG8_STAGE(PG8_SB(1, 1), b3 + hstep, voffB); PG8_STAGE(PG8_SA(1, 0), a3, voffA);
;             PG8_WAIT_V(8); PG8_WAIT_L(0); PG8_BAR; PG8_MMA(1, 0, At, B0); PG8_MMA(1, 1, At, B1); PG8_BAR; PG8_SCHED;
	ds_read_b128 v[140:143], v254 offset:32768
	ds_read_b128 v[162:165], v254 offset:33792
	ds_read_b128 v[166:169], v254 offset:34816
	ds_read_b128 v[176:179], v254 offset:35840
	ds_read_b128 v[180:183], v254 offset:49152
	ds_read_b128 v[184:187], v254 offset:50176
	ds_read_b128 v[188:191], v254 offset:51200
	ds_read_b128 v[210:213], v254 offset:52224
	s_add_u32 s4, s4, 0x40000
	s_addc_u32 s5, s5, 0
	s_mov_b32 m0, s33
	ds_read_b128 v[214:217], v173 offset:32768
	ds_read_b128 v[218:221], v173 offset:33792
	ds_read_b128 v[222:225], v173 offset:34816
	ds_read_b128 v[226:229], v173 offset:35840
	ds_read_b128 v[230:233], v173 offset:36864
	ds_read_b128 v[234:237], v173 offset:37888
	ds_read_b128 v[238:241], v173 offset:38912
	ds_read_b128 v[242:245], v173 offset:39936
	global_load_lds_dwordx4 v134, s[4:5]
	s_mov_b32 m0, s34
	s_nop 0
	global_load_lds_dwordx4 v130, s[4:5]
	s_waitcnt vmcnt(8)
	s_waitcnt lgkmcnt(0)
	s_barrier
	s_setprio 1
	v_mfma_f32_16x16x32_bf16 v[124:127], v[140:143], v[214:217], v[124:127]
	v_mfma_f32_16x16x32_bf16 v[120:123], v[166:169], v[214:217], v[120:123]
	v_mfma_f32_16x16x32_bf16 v[112:115], v[140:143], v[222:225], v[112:115]
	v_mfma_f32_16x16x32_bf16 v[104:107], v[166:169], v[222:225], v[104:107]
	v_mfma_f32_16x16x32_bf16 v[96:99], v[140:143], v[230:233], v[96:99]
	v_mfma_f32_16x16x32_bf16 v[88:91], v[166:169], v[230:233], v[88:91]
	v_mfma_f32_16x16x32_bf16 v[80:83], v[140:143], v[238:241], v[80:83]
	v_mfma_f32_16x16x32_bf16 v[72:75], v[166:169], v[238:241], v[72:75]
	v_mfma_f32_16x16x32_bf16 v[124:127], v[162:165], v[218:221], v[124:127]
	v_mfma_f32_16x16x32_bf16 v[120:123], v[176:179], v[218:221], v[120:123]
	v_mfma_f32_16x16x32_bf16 v[112:115], v[162:165], v[226:229], v[112:115]
	v_mfma_f32_16x16x32_bf16 v[104:107], v[176:179], v[226:229], v[104:107]
	v_mfma_f32_16x16x32_bf16 v[96:99], v[162:165], v[234:237], v[96:99]
	v_mfma_f32_16x16x32_bf16 v[88:91], v[176:179], v[234:237], v[88:91]
	v_mfma_f32_16x16x32_bf16 v[80:83], v[162:165], v[242:245], v[80:83]
	v_mfma_f32_16x16x32_bf16 v[72:75], v[176:179], v[242:245], v[72:75]
	v_mfma_f32_16x16x32_bf16 v[116:119], v[180:183], v[214:217], v[116:119]
	v_mfma_f32_16x16x32_bf16 v[108:111], v[188:191], v[214:217], v[108:111]
	v_mfma_f32_16x16x32_bf16 v[100:103], v[180:183], v[222:225], v[100:103]
	v_mfma_f32_16x16x32_bf16 v[92:95], v[188:191], v[222:225], v[92:95]
	v_mfma_f32_16x16x32_bf16 v[84:87], v[180:183], v[230:233], v[84:87]
	v_mfma_f32_16x16x32_bf16 v[76:79], v[188:191], v[230:233], v[76:79]
	v_mfma_f32_16x16x32_bf16 v[68:71], v[180:183], v[238:241], v[68:71]
	v_mfma_f32_16x16x32_bf16 v[64:67], v[188:191], v[238:241], v[64:67]
	v_mfma_f32_16x16x32_bf16 v[116:119], v[184:187], v[218:221], v[116:119]
	v_mfma_f32_16x16x32_bf16 v[108:111], v[210:213], v[218:221], v[108:111]
	v_mfma_f32_16x16x32_bf16 v[100:103], v[184:187], v[226:229], v[100:103]
	v_mfma_f32_16x16x32_bf16 v[92:95], v[210:213], v[226:229], v[92:95]
	v_mfma_f32_16x16x32_bf16 v[84:87], v[184:187], v[234:237], v[84:87]
	v_mfma_f32_16x16x32_bf16 v[76:79], v[210:213], v[234:237], v[76:79]
	v_mfma_f32_16x16x32_bf16 v[68:71], v[184:187], v[242:245], v[68:71]
	v_mfma_f32_16x16x32_bf16 v[64:67], v[210:213], v[242:245], v[64:67]
	s_setprio 0
	s_barrier
	s_mov_b32 m0, s37
	s_add_u32 s2, s2, 0x40080
	s_addc_u32 s3, s3, 0
	ds_read_b128 v[214:217], v173 offset:49152
	ds_read_b128 v[218:221], v173 offset:50176
	ds_read_b128 v[222:225], v173 offset:51200
	ds_read_b128 v[226:229], v173 offset:52224
	ds_read_b128 v[230:233], v173 offset:53248
	ds_read_b128 v[234:237], v173 offset:54272
	ds_read_b128 v[238:241], v173 offset:55296
	ds_read_b128 v[242:245], v173 offset:56320
	s_add_u32 s98, s2, 0xfffc0000
	s_addc_u32 s99, s3, -1
	global_load_lds_dwordx4 v132, s[98:99]
	s_mov_b32 m0, s38
	s_nop 0
	global_load_lds_dwordx4 v128, s[98:99]
	s_mov_b32 m0, s41
	s_nop 0
	global_load_lds_dwordx4 v132, s[2:3]
	s_mov_b32 m0, s42
	s_nop 0
	global_load_lds_dwordx4 v128, s[2:3]
	s_mov_b32 m0, s39
	s_nop 0
	s_add_u32 s100, s4, 0xfffc0080
	s_addc_u32 s101, s5, -1
	global_load_lds_dwordx4 v134, s[100:101]
	s_mov_b32 m0, s40
	s_nop 0
	global_load_lds_dwordx4 v130, s[100:101]
	s_add_i32 s52, s52, 2
	s_add_u32 s0, s0, 0x100
	s_addc_u32 s1, s1, 0
	s_add_u32 s50, s50, 0x100
	s_addc_u32 s51, s51, 0
	s_cmp_gt_u32 s52, 13
	s_waitcnt vmcnt(8)
	s_waitcnt lgkmcnt(0)
	s_barrier
	s_setprio 1
	v_mfma_f32_16x16x32_bf16 v[60:63], v[140:143], v[214:217], v[60:63]
	v_mfma_f32_16x16x32_bf16 v[56:59], v[166:169], v[214:217], v[56:59]
	v_mfma_f32_16x16x32_bf16 v[48:51], v[140:143], v[222:225], v[48:51]
	v_mfma_f32_16x16x32_bf16 v[40:43], v[166:169], v[222:225], v[40:43]
	v_mfma_f32_16x16x32_bf16 v[32:35], v[140:143], v[230:233], v[32:35]
	v_mfma_f32_16x16x32_bf16 v[24:27], v[166:169], v[230:233], v[24:27]
	v_mfma_f32_16x16x32_bf16 v[16:19], v[140:143], v[238:241], v[16:19]
	v_mfma_f32_16x16x32_bf16 v[8:11], v[166:169], v[238:241], v[8:11]
	v_mfma_f32_16x16x32_bf16 v[60:63], v[162:165], v[218:221], v[60:63]
	v_mfma_f32_16x16x32_bf16 v[56:59], v[176:179], v[218:221], v[56:59]
	v_mfma_f32_16x16x32_bf16 v[48:51], v[162:165], v[226:229], v[48:51]
	v_mfma_f32_16x16x32_bf16 v[40:43], v[176:179], v[226:229], v[40:43]
	v_mfma_f32_16x16x32_bf16 v[32:35], v[162:165], v[234:237], v[32:35]
	v_mfma_f32_16x16x32_bf16 v[24:27], v[176:179], v[234:237], v[24:27]
	v_mfma_f32_16x16x32_bf16 v[16:19], v[162:165], v[242:245], v[16:19]
	v_mfma_f32_16x16x32_bf16 v[8:11], v[176:179], v[242:245], v[8:11]
	v_mfma_f32_16x16x32_bf16 v[52:55], v[180:183], v[214:217], v[52:55]
	v_mfma_f32_16x16x32_bf16 v[44:47], v[188:191], v[214:217], v[44:47]
	v_mfma_f32_16x16x32_bf16 v[36:39], v[180:183], v[222:225], v[36:39]
	v_mfma_f32_16x16x32_bf16 v[28:31], v[188:191], v[222:225], v[28:31]
	v_mfma_f32_16x16x32_bf16 v[20:23], v[180:183], v[230:233], v[20:23]
	v_mfma_f32_16x16x32_bf16 v[12:15], v[188:191], v[230:233], v[12:15]
	v_mfma_f32_16x16x32_bf16 v[4:7], v[180:183], v[238:241], v[4:7]
	v_mfma_f32_16x16x32_bf16 v[0:3], v[188:191], v[238:241], v[0:3]
	v_mfma_f32_16x16x32_bf16 v[52:55], v[184:187], v[218:221], v[52:55]
	v_mfma_f32_16x16x32_bf16 v[44:47], v[210:213], v[218:221], v[44:47]
	v_mfma_f32_16x16x32_bf16 v[36:39], v[184:187], v[226:229], v[36:39]
	v_mfma_f32_16x16x32_bf16 v[28:31], v[210:213], v[226:229], v[28:31]
	v_mfma_f32_16x16x32_bf16 v[20:23], v[184:187], v[234:237], v[20:23]
	v_mfma_f32_16x16x32_bf16 v[12:15], v[210:213], v[234:237], v[12:15]
	v_mfma_f32_16x16x32_bf16 v[4:7], v[184:187], v[242:245], v[4:7]
	v_mfma_f32_16x16x32_bf16 v[0:3], v[210:213], v[242:245], v[0:3]
	s_setprio 0
	s_barrier
; #define PG8_STAGE(bufoff, gbase, voff) do { _Pragma("unroll") for (int _i = 0; _i < 2; ++_i) \
;         __builtin_amdgcn_global_load_lds((const unsigned*)((const char*)(gbase) + (voff)[_i]), (PG8_LAS unsigned*)(lds + (bufoff) + ldsw + _i * 8192), 16, 0, 0); } while (0)
; #define PG8_LDA(dst, b, h) do { _Pragma("unroll") for (int m = 0; m < 4; ++m) _Pragma("unroll") for (int k = 0; k < 2; ++k) dst[m][k] = *(const PG8_LAS bf16x8*)(lds + PG8_SA(b, h) + aoff + m * 2048 + k * 1024); } while (0)
; #define PG8_LDB(dst, b, h) do { _Pragma("unroll") for (int n = 0; n < 2; ++n) _Pragma("unroll") for (int k = 0; k < 2; ++k) dst[n][k] = *(const PG8_LAS bf16x8*)(lds + PG8_SB(b, h) + boff + n * 2048 + k * 1024); } while (0)
; #define PG8_MMA(ai, bj, At, Bt) do { __builtin_amdgcn_s_setprio(1); _Pragma("unroll") for (int m = 0; m < 4; ++m) _Pragma("unroll") for (int n = 0; n < 2; ++n) _Pragma("unroll") for (int k = 0; k < 2; ++k) \
;         acc[ai][bj][m][n] = __builtin_amdgcn_mfma_f32_16x16x32_bf16(Bt[n][k], At[m][k], acc[ai][bj][m][n], 0, 0, 0); __builtin_amdgcn_s_setprio(0); } while (0)
; #define PG8_WAIT_V(n) asm volatile("s_waitcnt vmcnt(" #n ")" ::: "memory")
; #define PG8_WAIT_L(n) asm volatile("s_waitcnt lgkmcnt(" #n ")" ::: "memory")
; #define PG8_BAR __builtin_amdgcn_s_barrier()
; #define PG8_SCHED __builtin_amdgcn_sched_barrier(0)
; template <class Epi, class Sched, bool ALIGN_EPI = false, bool SP2 = false>
; __device__ __forceinline__ void gemm_phase(PG8_LAS unsigned char* lds, const Gemm g, const Sched& S, const Epi& E) {
;     ...
;             PG8_LDB(B0, 0, 0); PG8_LDB(B1, 0, 1); PG8_SCHED; PG8_LDA(At, 0, 0); PG8_STAGE(PG8_SA(1, 1), a1 + hstep, voffA);
;             PG8_WAIT_V(8); PG8_WAIT_L(0); PG8_BAR; PG8_MMA(0, 0, At, B0); PG8_MMA(0, 1, At, B1); PG8_BAR; PG8_SCHED;
;             PG8_LDA(At, 0, 1); PG8_STAGE(PG8_SB(0, 0), b2, voffB); PG8_STAGE(PG8_SB(0, 1), b2 + hstep, voffB); PG8_STAGE(PG8_SA(0, 0), a2, voffA);
;             PG8_WAIT_V(8); PG8_WAIT_L(0); PG8_BAR; PG8_MMA(1, 0, At, B0); PG8_MMA(1, 1, At, B1); PG8_BAR; PG8_SCHED;
.LBB0_792:
	s_waitcnt lgkmcnt(0)
	ds_read_b128 v[140:143], v254
	ds_read_b128 v[162:165], v254 offset:1024
	ds_read_b128 v[166:169], v254 offset:2048
	ds_read_b128 v[176:179], v254 offset:3072
	ds_read_b128 v[180:183], v254 offset:16384
	ds_read_b128 v[184:187], v254 offset:17408
	ds_read_b128 v[188:191], v254 offset:18432
	ds_read_b128 v[210:213], v254 offset:19456
	s_add_u32 s2, s0, 0xfffc0080
	s_addc_u32 s3, s1, -1
	s_cmp_eq_u32 s52, 12
	s_cselect_b32 s5, s17, s3
	s_cselect_b32 s4, s48, s2
	s_cselect_b32 s3, s15, s51
	s_cselect_b32 s2, s49, s50
	s_add_i32 m0, s6, 0xc000
	ds_read_b128 v[214:217], v173
	ds_read_b128 v[218:221], v173 offset:1024
	ds_read_b128 v[222:225], v173 offset:2048
	ds_read_b128 v[226:229], v173 offset:3072
	ds_read_b128 v[230:233], v173 offset:4096
	ds_read_b128 v[234:237], v173 offset:5120
	ds_read_b128 v[238:241], v173 offset:6144
	ds_read_b128 v[242:245], v173 offset:7168
	global_load_lds_dwordx4 v136, s[0:1]
	s_add_i32 m0, s6, 0xe000
	s_nop 0
	global_load_lds_dwordx4 v138, s[0:1]
	s_waitcnt vmcnt(8)
	s_waitcnt lgkmcnt(0)
	s_barrier
	s_setprio 1
	v_mfma_f32_16x16x32_bf16 v[124:127], v[140:143], v[214:217], v[124:127]
	v_mfma_f32_16x16x32_bf16 v[120:123], v[166:169], v[214:217], v[120:123]
	v_mfma_f32_16x16x32_bf16 v[112:115], v[140:143], v[222:225], v[112:115]
	v_mfma_f32_16x16x32_bf16 v[104:107], v[166:169], v[222:225], v[104:107]
	v_mfma_f32_16x16x32_bf16 v[96:99], v[140:143], v[230:233], v[96:99]
	v_mfma_f32_16x16x32_bf16 v[88:91], v[166:169], v[230:233], v[88:91]
	v_mfma_f32_16x16x32_bf16 v[80:83], v[140:143], v[238:241], v[80:83]
	v_mfma_f32_16x16x32_bf16 v[72:75], v[166:169], v[238:241], v[72:75]
	v_mfma_f32_16x16x32_bf16 v[124:127], v[162:165], v[218:221], v[124:127]
	v_mfma_f32_16x16x32_bf16 v[120:123], v[176:179], v[218:221], v[120:123]
	v_mfma_f32_16x16x32_bf16 v[112:115], v[162:165], v[226:229], v[112:115]
	v_mfma_f32_16x16x32_bf16 v[104:107], v[176:179], v[226:229], v[104:107]
	v_mfma_f32_16x16x32_bf16 v[96:99], v[162:165], v[234:237], v[96:99]
	v_mfma_f32_16x16x32_bf16 v[88:91], v[176:179], v[234:237], v[88:91]
	v_mfma_f32_16x16x32_bf16 v[80:83], v[162:165], v[242:245], v[80:83]
	v_mfma_f32_16x16x32_bf16 v[72:75], v[176:179], v[242:245], v[72:75]
	v_mfma_f32_16x16x32_bf16 v[116:119], v[180:183], v[214:217], v[116:119]
	v_mfma_f32_16x16x32_bf16 v[108:111], v[188:191], v[214:217], v[108:111]
	v_mfma_f32_16x16x32_bf16 v[100:103], v[180:183], v[222:225], v[100:103]
	v_mfma_f32_16x16x32_bf16 v[92:95], v[188:191], v[222:225], v[92:95]
	v_mfma_f32_16x16x32_bf16 v[84:87], v[180:183], v[230:233], v[84:87]
	v_mfma_f32_16x16x32_bf16 v[76:79], v[188:191], v[230:233], v[76:79]
	v_mfma_f32_16x16x32_bf16 v[68:71], v[180:183], v[238:241], v[68:71]
	v_mfma_f32_16x16x32_bf16 v[64:67], v[188:191], v[238:241], v[64:67]
	v_mfma_f32_16x16x32_bf16 v[116:119], v[184:187], v[218:221], v[116:119]
	v_mfma_f32_16x16x32_bf16 v[108:111], v[210:213], v[218:221], v[108:111]
	v_mfma_f32_16x16x32_bf16 v[100:103], v[184:187], v[226:229], v[100:103]
	v_mfma_f32_16x16x32_bf16 v[92:95], v[210:213], v[226:229], v[92:95]
	v_mfma_f32_16x16x32_bf16 v[84:87], v[184:187], v[234:237], v[84:87]
	v_mfma_f32_16x16x32_bf16 v[76:79], v[210:213], v[234:237], v[76:79]
	v_mfma_f32_16x16x32_bf16 v[68:71], v[184:187], v[242:245], v[68:71]
	v_mfma_f32_16x16x32_bf16 v[64:67], v[210:213], v[242:245], v[64:67]
	s_setprio 0
	s_barrier
	s_mov_b32 m0, s27
	s_add_u32 s54, s2, 0x40000
	s_addc_u32 s55, s3, 0
	ds_read_b128 v[214:217], v173 offset:16384
	ds_read_b128 v[218:221], v173 offset:17408
	ds_read_b128 v[222:225], v173 offset:18432
	ds_read_b128 v[226:229], v173 offset:19456
	ds_read_b128 v[230:233], v173 offset:20480
	ds_read_b128 v[234:237], v173 offset:21504
	ds_read_b128 v[238:241], v173 offset:22528
	ds_read_b128 v[242:245], v173 offset:23552
	global_load_lds_dwordx4 v132, s[2:3]
	s_mov_b32 m0, s28
	s_nop 0
	global_load_lds_dwordx4 v128, s[2:3]
	s_mov_b32 m0, s29
	s_nop 0
	global_load_lds_dwordx4 v132, s[54:55]
	s_mov_b32 m0, s30
	s_nop 0
	global_load_lds_dwordx4 v128, s[54:55]
	s_mov_b32 m0, s6
	s_nop 0
	global_load_lds_dwordx4 v134, s[4:5]
	s_mov_b32 m0, s31
	s_nop 0
	global_load_lds_dwordx4 v130, s[4:5]
	s_waitcnt vmcnt(8)
	s_waitcnt lgkmcnt(0)
	s_barrier
	s_setprio 1
	v_mfma_f32_16x16x32_bf16 v[60:63], v[140:143], v[214:217], v[60:63]
	v_mfma_f32_16x16x32_bf16 v[56:59], v[166:169], v[214:217], v[56:59]
	v_mfma_f32_16x16x32_bf16 v[48:51], v[140:143], v[222:225], v[48:51]
	v_mfma_f32_16x16x32_bf16 v[40:43], v[166:169], v[222:225], v[40:43]
	v_mfma_f32_16x16x32_bf16 v[32:35], v[140:143], v[230:233], v[32:35]
	v_mfma_f32_16x16x32_bf16 v[24:27], v[166:169], v[230:233], v[24:27]
	v_mfma_f32_16x16x32_bf16 v[16:19], v[140:143], v[238:241], v[16:19]
	v_mfma_f32_16x16x32_bf16 v[8:11], v[166:169], v[238:241], v[8:11]
	v_mfma_f32_16x16x32_bf16 v[60:63], v[162:165], v[218:221], v[60:63]
	v_mfma_f32_16x16x32_bf16 v[56:59], v[176:179], v[218:221], v[56:59]
	v_mfma_f32_16x16x32_bf16 v[48:51], v[162:165], v[226:229], v[48:51]
	v_mfma_f32_16x16x32_bf16 v[40:43], v[176:179], v[226:229], v[40:43]
	v_mfma_f32_16x16x32_bf16 v[32:35], v[162:165], v[234:237], v[32:35]
	v_mfma_f32_16x16x32_bf16 v[24:27], v[176:179], v[234:237], v[24:27]
	v_mfma_f32_16x16x32_bf16 v[16:19], v[162:165], v[242:245], v[16:19]
	v_mfma_f32_16x16x32_bf16 v[8:11], v[176:179], v[242:245], v[8:11]
	v_mfma_f32_16x16x32_bf16 v[52:55], v[180:183], v[214:217], v[52:55]
	v_mfma_f32_16x16x32_bf16 v[44:47], v[188:191], v[214:217], v[44:47]
	v_mfma_f32_16x16x32_bf16 v[36:39], v[180:183], v[222:225], v[36:39]
	v_mfma_f32_16x16x32_bf16 v[28:31], v[188:191], v[222:225], v[28:31]
	v_mfma_f32_16x16x32_bf16 v[20:23], v[180:183], v[230:233], v[20:23]
	v_mfma_f32_16x16x32_bf16 v[12:15], v[188:191], v[230:233], v[12:15]
	v_mfma_f32_16x16x32_bf16 v[4:7], v[180:183], v[238:241], v[4:7]
	v_mfma_f32_16x16x32_bf16 v[0:3], v[188:191], v[238:241], v[0:3]
	v_mfma_f32_16x16x32_bf16 v[52:55], v[184:187], v[218:221], v[52:55]
	v_mfma_f32_16x16x32_bf16 v[44:47], v[210:213], v[218:221], v[44:47]
	v_mfma_f32_16x16x32_bf16 v[36:39], v[184:187], v[226:229], v[36:39]
	v_mfma_f32_16x16x32_bf16 v[28:31], v[210:213], v[226:229], v[28:31]
	v_mfma_f32_16x16x32_bf16 v[20:23], v[184:187], v[234:237], v[20:23]
	v_mfma_f32_16x16x32_bf16 v[12:15], v[210:213], v[234:237], v[12:15]
	v_mfma_f32_16x16x32_bf16 v[4:7], v[184:187], v[242:245], v[4:7]
	v_mfma_f32_16x16x32_bf16 v[0:3], v[210:213], v[242:245], v[0:3]
	s_setprio 0
	s_barrier
; #define PG8_STAGE(bufoff, gbase, voff) do { _Pragma("unroll") for (int _i = 0; _i < 2; ++_i) \
;         __builtin_amdgcn_global_load_lds((const unsigned*)((const char*)(gbase) + (voff)[_i]), (PG8_LAS unsigned*)(lds + (bufoff) + ldsw + _i * 8192), 16, 0, 0); } while (0)
; #define PG8_LDA(dst, b, h) do { _Pragma("unroll") for (int m = 0; m < 4; ++m) _Pragma("unroll") for (int k = 0; k < 2; ++k) dst[m][k] = *(const PG8_LAS bf16x8*)(lds + PG8_SA(b, h) + aoff + m * 2048 + k * 1024); } while (0)
; #define PG8_LDB(dst, b, h) do { _Pragma("unroll") for (int n = 0; n < 2; ++n) _Pragma("unroll") for (int k = 0; k < 2; ++k) dst[n][k] = *(const PG8_LAS bf16x8*)(lds + PG8_SB(b, h) + boff + n * 2048 + k * 1024); } while (0)
; #define PG8_MMA(ai, bj, At, Bt) do { __builtin_amdgcn_s_setprio(1); _Pragma("unroll") for (int m = 0; m < 4; ++m) _Pragma("unroll") for (int n = 0; n < 2; ++n) _Pragma("unroll") for (int k = 0; k < 2; ++k) \
;         acc[ai][bj][m][n] = __builtin_amdgcn_mfma_f32_16x16x32_bf16(Bt[n][k], At[m][k], acc[ai][bj][m][n], 0, 0, 0); __builtin_amdgcn_s_setprio(0); } while (0)
; #define PG8_WAIT_V(n) asm volatile("s_waitcnt vmcnt(" #n ")" ::: "memory")
; #define PG8_WAIT_L(n) asm volatile("s_waitcnt lgkmcnt(" #n ")" ::: "memory")
; #define PG8_BAR __builtin_amdgcn_s_barrier()
; #define PG8_SCHED __builtin_amdgcn_sched_barrier(0)
; template <class Epi, class Sched, bool ALIGN_EPI = false, bool SP2 = false>
; __device__ __forceinline__ void gemm_phase(PG8_LAS unsigned char* lds, const Gemm g, const Sched& S, const Epi& E) {
;     ...
;             PG8_LDB(B0, 1, 0); PG8_LDB(B1, 1, 1); PG8_SCHED; PG8_LDA(At, 1, 0); PG8_STAGE(PG8_SA(0, 1), a2 + hstep, voffA);
;             PG8_WAIT_V(8); PG8_WAIT_L(0); PG8_BAR; PG8_MMA(0, 0, At, B0); PG8_MMA(0, 1, At, B1); PG8_BAR; PG8_SCHED;
;             PG8_LDA(At, 1, 1); PG8_STAGE(PG8_SB(1, 0), b3, voffB); PG8_STAGE(PG8_SB(1, 1), b3 + hstep, voffB); PG8_STAGE(PG8_SA(1, 0), a3, voffA);
;             PG8_WAIT_V(8); PG8_WAIT_L(0); PG8_BAR; PG8_MMA(1, 0, At, B0); PG8_MMA(1, 1, At, B1); PG8_BAR; PG8_SCHED;
;     ...
;         if constexpr (ALIGN_EPI) { if (wr == 0) PG8_BAR; }
	ds_read_b128 v[140:143], v254 offset:32768
	ds_read_b128 v[162:165], v254 offset:33792
	ds_read_b128 v[166:169], v254 offset:34816
	ds_read_b128 v[176:179], v254 offset:35840
	ds_read_b128 v[180:183], v254 offset:49152
	ds_read_b128 v[184:187], v254 offset:50176
	ds_read_b128 v[188:191], v254 offset:51200
	ds_read_b128 v[210:213], v254 offset:52224
	s_add_u32 s4, s4, 0x40000
	s_addc_u32 s5, s5, 0
	s_mov_b32 m0, s33
	ds_read_b128 v[214:217], v173 offset:32768
	ds_read_b128 v[218:221], v173 offset:33792
	ds_read_b128 v[222:225], v173 offset:34816
	ds_read_b128 v[226:229], v173 offset:35840
	ds_read_b128 v[230:233], v173 offset:36864
	ds_read_b128 v[234:237], v173 offset:37888
	ds_read_b128 v[238:241], v173 offset:38912
	ds_read_b128 v[242:245], v173 offset:39936
	global_load_lds_dwordx4 v134, s[4:5]
	s_mov_b32 m0, s34
	s_nop 0
	global_load_lds_dwordx4 v130, s[4:5]
	s_waitcnt vmcnt(8)
	s_waitcnt lgkmcnt(0)
	s_barrier
	s_setprio 1
	v_mfma_f32_16x16x32_bf16 v[124:127], v[140:143], v[214:217], v[124:127]
	v_mfma_f32_16x16x32_bf16 v[120:123], v[166:169], v[214:217], v[120:123]
	v_mfma_f32_16x16x32_bf16 v[112:115], v[140:143], v[222:225], v[112:115]
	v_mfma_f32_16x16x32_bf16 v[104:107], v[166:169], v[222:225], v[104:107]
	v_mfma_f32_16x16x32_bf16 v[96:99], v[140:143], v[230:233], v[96:99]
	v_mfma_f32_16x16x32_bf16 v[88:91], v[166:169], v[230:233], v[88:91]
	v_mfma_f32_16x16x32_bf16 v[80:83], v[140:143], v[238:241], v[80:83]
	v_mfma_f32_16x16x32_bf16 v[72:75], v[166:169], v[238:241], v[72:75]
	v_mfma_f32_16x16x32_bf16 v[124:127], v[162:165], v[218:221], v[124:127]
	v_mfma_f32_16x16x32_bf16 v[120:123], v[176:179], v[218:221], v[120:123]
	v_mfma_f32_16x16x32_bf16 v[112:115], v[162:165], v[226:229], v[112:115]
	v_mfma_f32_16x16x32_bf16 v[104:107], v[176:179], v[226:229], v[104:107]
	v_mfma_f32_16x16x32_bf16 v[96:99], v[162:165], v[234:237], v[96:99]
	v_mfma_f32_16x16x32_bf16 v[88:91], v[176:179], v[234:237], v[88:91]
	v_mfma_f32_16x16x32_bf16 v[80:83], v[162:165], v[242:245], v[80:83]
	v_mfma_f32_16x16x32_bf16 v[72:75], v[176:179], v[242:245], v[72:75]
	v_mfma_f32_16x16x32_bf16 v[116:119], v[180:183], v[214:217], v[116:119]
	v_mfma_f32_16x16x32_bf16 v[108:111], v[188:191], v[214:217], v[108:111]
	v_mfma_f32_16x16x32_bf16 v[100:103], v[180:183], v[222:225], v[100:103]
	v_mfma_f32_16x16x32_bf16 v[92:95], v[188:191], v[222:225], v[92:95]
	v_mfma_f32_16x16x32_bf16 v[84:87], v[180:183], v[230:233], v[84:87]
	v_mfma_f32_16x16x32_bf16 v[76:79], v[188:191], v[230:233], v[76:79]
	v_mfma_f32_16x16x32_bf16 v[68:71], v[180:183], v[238:241], v[68:71]
	v_mfma_f32_16x16x32_bf16 v[64:67], v[188:191], v[238:241], v[64:67]
	v_mfma_f32_16x16x32_bf16 v[116:119], v[184:187], v[218:221], v[116:119]
	v_mfma_f32_16x16x32_bf16 v[108:111], v[210:213], v[218:221], v[108:111]
	v_mfma_f32_16x16x32_bf16 v[100:103], v[184:187], v[226:229], v[100:103]
	v_mfma_f32_16x16x32_bf16 v[92:95], v[210:213], v[226:229], v[92:95]
	v_mfma_f32_16x16x32_bf16 v[84:87], v[184:187], v[234:237], v[84:87]
	v_mfma_f32_16x16x32_bf16 v[76:79], v[210:213], v[234:237], v[76:79]
	v_mfma_f32_16x16x32_bf16 v[68:71], v[184:187], v[242:245], v[68:71]
	v_mfma_f32_16x16x32_bf16 v[64:67], v[210:213], v[242:245], v[64:67]
	s_setprio 0
	s_barrier
	s_mov_b32 m0, s37
	s_add_u32 s2, s2, 0x40080
	s_addc_u32 s3, s3, 0
	ds_read_b128 v[214:217], v173 offset:49152
	ds_read_b128 v[218:221], v173 offset:50176
	ds_read_b128 v[222:225], v173 offset:51200
	ds_read_b128 v[226:229], v173 offset:52224
	ds_read_b128 v[230:233], v173 offset:53248
	ds_read_b128 v[234:237], v173 offset:54272
	ds_read_b128 v[238:241], v173 offset:55296
	ds_read_b128 v[242:245], v173 offset:56320
	s_add_u32 s98, s2, 0xfffc0000
	s_addc_u32 s99, s3, -1
	global_load_lds_dwordx4 v132, s[98:99]
	s_mov_b32 m0, s38
	s_nop 0
	global_load_lds_dwordx4 v128, s[98:99]
	s_mov_b32 m0, s41
	s_nop 0
	global_load_lds_dwordx4 v132, s[2:3]
	s_mov_b32 m0, s42
	s_nop 0
	global_load_lds_dwordx4 v128, s[2:3]
	s_mov_b32 m0, s39
	s_nop 0
	s_add_u32 s100, s4, 0xfffc0080
	s_addc_u32 s101, s5, -1
	global_load_lds_dwordx4 v134, s[100:101]
	s_mov_b32 m0, s40
	s_nop 0
	global_load_lds_dwordx4 v130, s[100:101]
	s_add_i32 s52, s52, 2
	s_add_u32 s0, s0, 0x100
	s_addc_u32 s1, s1, 0
	s_add_u32 s50, s50, 0x100
	s_addc_u32 s51, s51, 0
	s_cmp_gt_u32 s52, 13
	s_waitcnt vmcnt(8)
	s_waitcnt lgkmcnt(0)
	s_barrier
	s_setprio 1
	v_mfma_f32_16x16x32_bf16 v[60:63], v[140:143], v[214:217], v[60:63]
	v_mfma_f32_16x16x32_bf16 v[56:59], v[166:169], v[214:217], v[56:59]
	v_mfma_f32_16x16x32_bf16 v[48:51], v[140:143], v[222:225], v[48:51]
	v_mfma_f32_16x16x32_bf16 v[40:43], v[166:169], v[222:225], v[40:43]
	v_mfma_f32_16x16x32_bf16 v[32:35], v[140:143], v[230:233], v[32:35]
	v_mfma_f32_16x16x32_bf16 v[24:27], v[166:169], v[230:233], v[24:27]
	v_mfma_f32_16x16x32_bf16 v[16:19], v[140:143], v[238:241], v[16:19]
	v_mfma_f32_16x16x32_bf16 v[8:11], v[166:169], v[238:241], v[8:11]
	v_mfma_f32_16x16x32_bf16 v[60:63], v[162:165], v[218:221], v[60:63]
	v_mfma_f32_16x16x32_bf16 v[56:59], v[176:179], v[218:221], v[56:59]
	v_mfma_f32_16x16x32_bf16 v[48:51], v[162:165], v[226:229], v[48:51]
	v_mfma_f32_16x16x32_bf16 v[40:43], v[176:179], v[226:229], v[40:43]
	v_mfma_f32_16x16x32_bf16 v[32:35], v[162:165], v[234:237], v[32:35]
	v_mfma_f32_16x16x32_bf16 v[24:27], v[176:179], v[234:237], v[24:27]
	v_mfma_f32_16x16x32_bf16 v[16:19], v[162:165], v[242:245], v[16:19]
	v_mfma_f32_16x16x32_bf16 v[8:11], v[176:179], v[242:245], v[8:11]
	v_mfma_f32_16x16x32_bf16 v[52:55], v[180:183], v[214:217], v[52:55]
	v_mfma_f32_16x16x32_bf16 v[44:47], v[188:191], v[214:217], v[44:47]
	v_mfma_f32_16x16x32_bf16 v[36:39], v[180:183], v[222:225], v[36:39]
	v_mfma_f32_16x16x32_bf16 v[28:31], v[188:191], v[222:225], v[28:31]
	v_mfma_f32_16x16x32_bf16 v[20:23], v[180:183], v[230:233], v[20:23]
	v_mfma_f32_16x16x32_bf16 v[12:15], v[188:191], v[230:233], v[12:15]
	v_mfma_f32_16x16x32_bf16 v[4:7], v[180:183], v[238:241], v[4:7]
	v_mfma_f32_16x16x32_bf16 v[0:3], v[188:191], v[238:241], v[0:3]
	v_mfma_f32_16x16x32_bf16 v[52:55], v[184:187], v[218:221], v[52:55]
	v_mfma_f32_16x16x32_bf16 v[44:47], v[210:213], v[218:221], v[44:47]
	v_mfma_f32_16x16x32_bf16 v[36:39], v[184:187], v[226:229], v[36:39]
	v_mfma_f32_16x16x32_bf16 v[28:31], v[210:213], v[226:229], v[28:31]
	v_mfma_f32_16x16x32_bf16 v[20:23], v[184:187], v[234:237], v[20:23]
	v_mfma_f32_16x16x32_bf16 v[12:15], v[210:213], v[234:237], v[12:15]
	v_mfma_f32_16x16x32_bf16 v[4:7], v[184:187], v[242:245], v[4:7]
	v_mfma_f32_16x16x32_bf16 v[0:3], v[210:213], v[242:245], v[0:3]
	s_setprio 0
	s_barrier
	s_cbranch_scc0 .LBB0_792
	s_and_b64 vcc, exec, s[12:13]
	s_cbranch_vccz .LBB0_795
	s_barrier

; #define PG8_STAGE(bufoff, gbase, voff) do { _Pragma("unroll") for (int _i = 0; _i < 2; ++_i) \
;         __builtin_amdgcn_global_load_lds((const unsigned*)((const char*)(gbase) + (voff)[_i]), (PG8_LAS unsigned*)(lds + (bufoff) + ldsw + _i * 8192), 16, 0, 0); } while (0)
; #define PG8_LDA(dst, b, h) do { _Pragma("unroll") for (int m = 0; m < 4; ++m) _Pragma("unroll") for (int k = 0; k < 2; ++k) dst[m][k] = *(const PG8_LAS bf16x8*)(lds + PG8_SA(b, h) + aoff + m * 2048 + k * 1024); } while (0)
; #define PG8_LDB(dst, b, h) do { _Pragma("unroll") for (int n = 0; n < 2; ++n) _Pragma("unroll") for (int k = 0; k < 2; ++k) dst[n][k] = *(const PG8_LAS bf16x8*)(lds + PG8_SB(b, h) + boff + n * 2048 + k * 1024); } while (0)
; #define PG8_MMA(ai, bj, At, Bt) do { __builtin_amdgcn_s_setprio(1); _Pragma("unroll") for (int m = 0; m < 4; ++m) _Pragma("unroll") for (int n = 0; n < 2; ++n) _Pragma("unroll") for (int k = 0; k < 2; ++k) \
;         acc[ai][bj][m][n] = __builtin_amdgcn_mfma_f32_16x16x32_bf16(Bt[n][k], At[m][k], acc[ai][bj][m][n], 0, 0, 0); __builtin_amdgcn_s_setprio(0); } while (0)
; #define PG8_WAIT_V(n) asm volatile("s_waitcnt vmcnt(" #n ")" ::: "memory")
; #define PG8_WAIT_L(n) asm volatile("s_waitcnt lgkmcnt(" #n ")" ::: "memory")
; #define PG8_BAR __builtin_amdgcn_s_barrier()
; #define PG8_SCHED __builtin_amdgcn_sched_barrier(0)
; template <class Epi, class Sched, bool ALIGN_EPI = false, bool SP2 = false>
; __device__ __forceinline__ void gemm_phase(PG8_LAS unsigned char* lds, const Gemm g, const Sched& S, const Epi& E) {
;     ...
;             PG8_LDB(B0, 0, 0); PG8_LDB(B1, 0, 1); PG8_SCHED; PG8_LDA(At, 0, 0); PG8_STAGE(PG8_SA(1, 1), a1 + hstep, voffA);
;             PG8_WAIT_V(8); PG8_WAIT_L(0); PG8_BAR; PG8_MMA(0, 0, At, B0); PG8_MMA(0, 1, At, B1); PG8_BAR; PG8_SCHED;
;             PG8_LDA(At, 0, 1); PG8_STAGE(PG8_SB(0, 0), b2, voffB); PG8_STAGE(PG8_SB(0, 1), b2 + hstep, voffB); PG8_STAGE(PG8_SA(0, 0), a2, voffA);
;             PG8_WAIT_V(8); PG8_WAIT_L(0); PG8_BAR; PG8_MMA(1, 0, At, B0); PG8_MMA(1, 1, At, B1); PG8_BAR; PG8_SCHED;
.Lsgo_peel:
	ds_read_b128 v[140:143], v254
	ds_read_b128 v[166:169], v254 offset:1024
	ds_read_b128 v[170:173], v254 offset:2048
	ds_read_b128 v[174:177], v254 offset:3072
	ds_read_b128 v[178:181], v254 offset:16384
	ds_read_b128 v[182:185], v254 offset:17408
	ds_read_b128 v[186:189], v254 offset:18432
	ds_read_b128 v[210:213], v254 offset:19456
	s_add_u32 s2, s0, 0xfffc0080
	s_addc_u32 s3, s1, -1
	s_cmp_eq_u32 s55, 12
	s_cselect_b32 s5, s23, s3
	s_cselect_b32 s4, s51, s2
	s_cselect_b32 s3, s21, s54
	s_cselect_b32 s2, s52, s53
	s_add_i32 m0, s31, 0xc000
	ds_read_b128 v[214:217], v163
	ds_read_b128 v[218:221], v163 offset:1024
	ds_read_b128 v[222:225], v163 offset:2048
	ds_read_b128 v[226:229], v163 offset:3072
	ds_read_b128 v[230:233], v163 offset:4096
	ds_read_b128 v[234:237], v163 offset:5120
	ds_read_b128 v[238:241], v163 offset:6144
	ds_read_b128 v[242:245], v163 offset:7168
	global_load_lds_dwordx4 v136, s[0:1]
	s_add_i32 m0, s31, 0xe000
	s_nop 0
	global_load_lds_dwordx4 v138, s[0:1]
	s_waitcnt vmcnt(8)
	s_waitcnt lgkmcnt(0)
	s_barrier
	s_setprio 1
	v_mfma_f32_16x16x32_bf16 v[124:127], v[140:143], v[214:217], 0
	v_mfma_f32_16x16x32_bf16 v[120:123], v[170:173], v[214:217], 0
	v_mfma_f32_16x16x32_bf16 v[108:111], v[140:143], v[222:225], 0
	v_mfma_f32_16x16x32_bf16 v[104:107], v[170:173], v[222:225], 0
	v_mfma_f32_16x16x32_bf16 v[92:95], v[140:143], v[230:233], 0
	v_mfma_f32_16x16x32_bf16 v[88:91], v[170:173], v[230:233], 0
	v_mfma_f32_16x16x32_bf16 v[76:79], v[140:143], v[238:241], 0
	v_mfma_f32_16x16x32_bf16 v[72:75], v[170:173], v[238:241], 0
	v_mfma_f32_16x16x32_bf16 v[124:127], v[166:169], v[218:221], v[124:127]
	v_mfma_f32_16x16x32_bf16 v[120:123], v[174:177], v[218:221], v[120:123]
	v_mfma_f32_16x16x32_bf16 v[108:111], v[166:169], v[226:229], v[108:111]
	v_mfma_f32_16x16x32_bf16 v[104:107], v[174:177], v[226:229], v[104:107]
	v_mfma_f32_16x16x32_bf16 v[92:95], v[166:169], v[234:237], v[92:95]
	v_mfma_f32_16x16x32_bf16 v[88:91], v[174:177], v[234:237], v[88:91]
	v_mfma_f32_16x16x32_bf16 v[76:79], v[166:169], v[242:245], v[76:79]
	v_mfma_f32_16x16x32_bf16 v[72:75], v[174:177], v[242:245], v[72:75]
	v_mfma_f32_16x16x32_bf16 v[116:119], v[178:181], v[214:217], 0
	v_mfma_f32_16x16x32_bf16 v[112:115], v[186:189], v[214:217], 0
	v_mfma_f32_16x16x32_bf16 v[100:103], v[178:181], v[222:225], 0
	v_mfma_f32_16x16x32_bf16 v[96:99], v[186:189], v[222:225], 0
	v_mfma_f32_16x16x32_bf16 v[84:87], v[178:181], v[230:233], 0
	v_mfma_f32_16x16x32_bf16 v[80:83], v[186:189], v[230:233], 0
	v_mfma_f32_16x16x32_bf16 v[68:71], v[178:181], v[238:241], 0
	v_mfma_f32_16x16x32_bf16 v[64:67], v[186:189], v[238:241], 0
	v_mfma_f32_16x16x32_bf16 v[116:119], v[182:185], v[218:221], v[116:119]
	v_mfma_f32_16x16x32_bf16 v[112:115], v[210:213], v[218:221], v[112:115]
	v_mfma_f32_16x16x32_bf16 v[100:103], v[182:185], v[226:229], v[100:103]
	v_mfma_f32_16x16x32_bf16 v[96:99], v[210:213], v[226:229], v[96:99]
	v_mfma_f32_16x16x32_bf16 v[84:87], v[182:185], v[234:237], v[84:87]
	v_mfma_f32_16x16x32_bf16 v[80:83], v[210:213], v[234:237], v[80:83]
	v_mfma_f32_16x16x32_bf16 v[68:71], v[182:185], v[242:245], v[68:71]
	v_mfma_f32_16x16x32_bf16 v[64:67], v[210:213], v[242:245], v[64:67]
	s_setprio 0
	s_barrier
	s_mov_b32 m0, s33
	s_add_u32 s56, s2, 0x40000
	s_addc_u32 s57, s3, 0
	ds_read_b128 v[214:217], v163 offset:16384
	ds_read_b128 v[218:221], v163 offset:17408
	ds_read_b128 v[222:225], v163 offset:18432
	ds_read_b128 v[226:229], v163 offset:19456
	ds_read_b128 v[230:233], v163 offset:20480
	ds_read_b128 v[234:237], v163 offset:21504
	ds_read_b128 v[238:241], v163 offset:22528
	ds_read_b128 v[242:245], v163 offset:23552
	global_load_lds_dwordx4 v132, s[2:3]
	s_mov_b32 m0, s34
	s_nop 0
	global_load_lds_dwordx4 v128, s[2:3]
	s_mov_b32 m0, s35
	s_nop 0
	global_load_lds_dwordx4 v132, s[56:57]
	s_mov_b32 m0, s36
	s_nop 0
	global_load_lds_dwordx4 v128, s[56:57]
	s_mov_b32 m0, s31
	s_nop 0
	global_load_lds_dwordx4 v134, s[4:5]
	s_mov_b32 m0, s37
	s_nop 0
	global_load_lds_dwordx4 v130, s[4:5]
	s_waitcnt vmcnt(8)
	s_waitcnt lgkmcnt(0)
	s_barrier
	s_setprio 1
	v_mfma_f32_16x16x32_bf16 v[60:63], v[140:143], v[214:217], 0
	v_mfma_f32_16x16x32_bf16 v[56:59], v[170:173], v[214:217], 0
	v_mfma_f32_16x16x32_bf16 v[44:47], v[140:143], v[222:225], 0
	v_mfma_f32_16x16x32_bf16 v[40:43], v[170:173], v[222:225], 0
	v_mfma_f32_16x16x32_bf16 v[28:31], v[140:143], v[230:233], 0
	v_mfma_f32_16x16x32_bf16 v[24:27], v[170:173], v[230:233], 0
	v_mfma_f32_16x16x32_bf16 v[12:15], v[140:143], v[238:241], 0
	v_mfma_f32_16x16x32_bf16 v[8:11], v[170:173], v[238:241], 0
	v_mfma_f32_16x16x32_bf16 v[60:63], v[166:169], v[218:221], v[60:63]
	v_mfma_f32_16x16x32_bf16 v[56:59], v[174:177], v[218:221], v[56:59]
	v_mfma_f32_16x16x32_bf16 v[44:47], v[166:169], v[226:229], v[44:47]
	v_mfma_f32_16x16x32_bf16 v[40:43], v[174:177], v[226:229], v[40:43]
	v_mfma_f32_16x16x32_bf16 v[28:31], v[166:169], v[234:237], v[28:31]
	v_mfma_f32_16x16x32_bf16 v[24:27], v[174:177], v[234:237], v[24:27]
	v_mfma_f32_16x16x32_bf16 v[12:15], v[166:169], v[242:245], v[12:15]
	v_mfma_f32_16x16x32_bf16 v[8:11], v[174:177], v[242:245], v[8:11]
	v_mfma_f32_16x16x32_bf16 v[52:55], v[178:181], v[214:217], 0
	v_mfma_f32_16x16x32_bf16 v[48:51], v[186:189], v[214:217], 0
	v_mfma_f32_16x16x32_bf16 v[36:39], v[178:181], v[222:225], 0
	v_mfma_f32_16x16x32_bf16 v[32:35], v[186:189], v[222:225], 0
	v_mfma_f32_16x16x32_bf16 v[20:23], v[178:181], v[230:233], 0
	v_mfma_f32_16x16x32_bf16 v[16:19], v[186:189], v[230:233], 0
	v_mfma_f32_16x16x32_bf16 v[4:7], v[178:181], v[238:241], 0
	v_mfma_f32_16x16x32_bf16 v[0:3], v[186:189], v[238:241], 0
	v_mfma_f32_16x16x32_bf16 v[52:55], v[182:185], v[218:221], v[52:55]
	v_mfma_f32_16x16x32_bf16 v[48:51], v[210:213], v[218:221], v[48:51]
	v_mfma_f32_16x16x32_bf16 v[36:39], v[182:185], v[226:229], v[36:39]
	v_mfma_f32_16x16x32_bf16 v[32:35], v[210:213], v[226:229], v[32:35]
	v_mfma_f32_16x16x32_bf16 v[20:23], v[182:185], v[234:237], v[20:23]
	v_mfma_f32_16x16x32_bf16 v[16:19], v[210:213], v[234:237], v[16:19]
	v_mfma_f32_16x16x32_bf16 v[4:7], v[182:185], v[242:245], v[4:7]
	v_mfma_f32_16x16x32_bf16 v[0:3], v[210:213], v[242:245], v[0:3]
	s_setprio 0
	s_barrier
; #define PG8_STAGE(bufoff, gbase, voff) do { _Pragma("unroll") for (int _i = 0; _i < 2; ++_i) \
;         __builtin_amdgcn_global_load_lds((const unsigned*)((const char*)(gbase) + (voff)[_i]), (PG8_LAS unsigned*)(lds + (bufoff) + ldsw + _i * 8192), 16, 0, 0); } while (0)
; #define PG8_LDA(dst, b, h) do { _Pragma("unroll") for (int m = 0; m < 4; ++m) _Pragma("unroll") for (int k = 0; k < 2; ++k) dst[m][k] = *(const PG8_LAS bf16x8*)(lds + PG8_SA(b, h) + aoff + m * 2048 + k * 1024); } while (0)
; #define PG8_LDB(dst, b, h) do { _Pragma("unroll") for (int n = 0; n < 2; ++n) _Pragma("unroll") for (int k = 0; k < 2; ++k) dst[n][k] = *(const PG8_LAS bf16x8*)(lds + PG8_SB(b, h) + boff + n * 2048 + k * 1024); } while (0)
; #define PG8_MMA(ai, bj, At, Bt) do { __builtin_amdgcn_s_setprio(1); _Pragma("unroll") for (int m = 0; m < 4; ++m) _Pragma("unroll") for (int n = 0; n < 2; ++n) _Pragma("unroll") for (int k = 0; k < 2; ++k) \
;         acc[ai][bj][m][n] = __builtin_amdgcn_mfma_f32_16x16x32_bf16(Bt[n][k], At[m][k], acc[ai][bj][m][n], 0, 0, 0); __builtin_amdgcn_s_setprio(0); } while (0)
; #define PG8_WAIT_V(n) asm volatile("s_waitcnt vmcnt(" #n ")" ::: "memory")
; #define PG8_WAIT_L(n) asm volatile("s_waitcnt lgkmcnt(" #n ")" ::: "memory")
; #define PG8_BAR __builtin_amdgcn_s_barrier()
; #define PG8_SCHED __builtin_amdgcn_sched_barrier(0)
; template <class Epi, class Sched, bool ALIGN_EPI = false, bool SP2 = false>
; __device__ __forceinline__ void gemm_phase(PG8_LAS unsigned char* lds, const Gemm g, const Sched& S, const Epi& E) {
;     ...
;             PG8_LDB(B0, 1, 0); PG8_LDB(B1, 1, 1); PG8_SCHED; PG8_LDA(At, 1, 0); PG8_STAGE(PG8_SA(0, 1), a2 + hstep, voffA);
;             PG8_WAIT_V(8); PG8_WAIT_L(0); PG8_BAR; PG8_MMA(0, 0, At, B0); PG8_MMA(0, 1, At, B1); PG8_BAR; PG8_SCHED;
;             PG8_LDA(At, 1, 1); PG8_STAGE(PG8_SB(1, 0), b3, voffB); PG8_STAGE(PG8_SB(1, 1), b3 + hstep, voffB); PG8_STAGE(PG8_SA(1, 0), a3, voffA);
;             PG8_WAIT_V(8); PG8_WAIT_L(0); PG8_BAR; PG8_MMA(1, 0, At, B0); PG8_MMA(1, 1, At, B1); PG8_BAR; PG8_SCHED;
	ds_read_b128 v[140:143], v254 offset:32768
	ds_read_b128 v[166:169], v254 offset:33792
	ds_read_b128 v[170:173], v254 offset:34816
	ds_read_b128 v[174:177], v254 offset:35840
	ds_read_b128 v[178:181], v254 offset:49152
	ds_read_b128 v[182:185], v254 offset:50176
	ds_read_b128 v[186:189], v254 offset:51200
	ds_read_b128 v[210:213], v254 offset:52224
	s_add_u32 s4, s4, 0x40000
	s_addc_u32 s5, s5, 0
	s_mov_b32 m0, s38
	ds_read_b128 v[214:217], v163 offset:32768
	ds_read_b128 v[218:221], v163 offset:33792
	ds_read_b128 v[222:225], v163 offset:34816
	ds_read_b128 v[226:229], v163 offset:35840
	ds_read_b128 v[230:233], v163 offset:36864
	ds_read_b128 v[234:237], v163 offset:37888
	ds_read_b128 v[238:241], v163 offset:38912
	ds_read_b128 v[242:245], v163 offset:39936
	global_load_lds_dwordx4 v134, s[4:5]
	s_mov_b32 m0, s39
	s_nop 0
	global_load_lds_dwordx4 v130, s[4:5]
	s_waitcnt vmcnt(8)
	s_waitcnt lgkmcnt(0)
	s_barrier
	s_setprio 1
	v_mfma_f32_16x16x32_bf16 v[124:127], v[140:143], v[214:217], v[124:127]
	v_mfma_f32_16x16x32_bf16 v[120:123], v[170:173], v[214:217], v[120:123]
	v_mfma_f32_16x16x32_bf16 v[108:111], v[140:143], v[222:225], v[108:111]
	v_mfma_f32_16x16x32_bf16 v[104:107], v[170:173], v[222:225], v[104:107]
	v_mfma_f32_16x16x32_bf16 v[92:95], v[140:143], v[230:233], v[92:95]
	v_mfma_f32_16x16x32_bf16 v[88:91], v[170:173], v[230:233], v[88:91]
	v_mfma_f32_16x16x32_bf16 v[76:79], v[140:143], v[238:241], v[76:79]
	v_mfma_f32_16x16x32_bf16 v[72:75], v[170:173], v[238:241], v[72:75]
	v_mfma_f32_16x16x32_bf16 v[124:127], v[166:169], v[218:221], v[124:127]
	v_mfma_f32_16x16x32_bf16 v[120:123], v[174:177], v[218:221], v[120:123]
	v_mfma_f32_16x16x32_bf16 v[108:111], v[166:169], v[226:229], v[108:111]
	v_mfma_f32_16x16x32_bf16 v[104:107], v[174:177], v[226:229], v[104:107]
	v_mfma_f32_16x16x32_bf16 v[92:95], v[166:169], v[234:237], v[92:95]
	v_mfma_f32_16x16x32_bf16 v[88:91], v[174:177], v[234:237], v[88:91]
	v_mfma_f32_16x16x32_bf16 v[76:79], v[166:169], v[242:245], v[76:79]
	v_mfma_f32_16x16x32_bf16 v[72:75], v[174:177], v[242:245], v[72:75]
	v_mfma_f32_16x16x32_bf16 v[116:119], v[178:181], v[214:217], v[116:119]
	v_mfma_f32_16x16x32_bf16 v[112:115], v[186:189], v[214:217], v[112:115]
	v_mfma_f32_16x16x32_bf16 v[100:103], v[178:181], v[222:225], v[100:103]
	v_mfma_f32_16x16x32_bf16 v[96:99], v[186:189], v[222:225], v[96:99]
	v_mfma_f32_16x16x32_bf16 v[84:87], v[178:181], v[230:233], v[84:87]
	v_mfma_f32_16x16x32_bf16 v[80:83], v[186:189], v[230:233], v[80:83]
	v_mfma_f32_16x16x32_bf16 v[68:71], v[178:181], v[238:241], v[68:71]
	v_mfma_f32_16x16x32_bf16 v[64:67], v[186:189], v[238:241], v[64:67]
	v_mfma_f32_16x16x32_bf16 v[116:119], v[182:185], v[218:221], v[116:119]
	v_mfma_f32_16x16x32_bf16 v[112:115], v[210:213], v[218:221], v[112:115]
	v_mfma_f32_16x16x32_bf16 v[100:103], v[182:185], v[226:229], v[100:103]
	v_mfma_f32_16x16x32_bf16 v[96:99], v[210:213], v[226:229], v[96:99]
	v_mfma_f32_16x16x32_bf16 v[84:87], v[182:185], v[234:237], v[84:87]
	v_mfma_f32_16x16x32_bf16 v[80:83], v[210:213], v[234:237], v[80:83]
	v_mfma_f32_16x16x32_bf16 v[68:71], v[182:185], v[242:245], v[68:71]
	v_mfma_f32_16x16x32_bf16 v[64:67], v[210:213], v[242:245], v[64:67]
	s_setprio 0
	s_barrier
	s_mov_b32 m0, s43
	s_add_u32 s2, s2, 0x40080
	s_addc_u32 s3, s3, 0
	ds_read_b128 v[214:217], v163 offset:49152
	ds_read_b128 v[218:221], v163 offset:50176
	ds_read_b128 v[222:225], v163 offset:51200
	ds_read_b128 v[226:229], v163 offset:52224
	ds_read_b128 v[230:233], v163 offset:53248
	ds_read_b128 v[234:237], v163 offset:54272
	ds_read_b128 v[238:241], v163 offset:55296
	ds_read_b128 v[242:245], v163 offset:56320
	s_add_u32 s98, s2, 0xfffc0000
	s_addc_u32 s99, s3, -1
	global_load_lds_dwordx4 v132, s[98:99]
	s_mov_b32 m0, s44
	s_nop 0
	global_load_lds_dwordx4 v128, s[98:99]
	s_mov_b32 m0, s48
	s_nop 0
	global_load_lds_dwordx4 v132, s[2:3]
	s_mov_b32 m0, s49
	s_nop 0
	global_load_lds_dwordx4 v128, s[2:3]
	s_mov_b32 m0, s45
	s_nop 0
	s_add_u32 s100, s4, 0xfffc0080
	s_addc_u32 s101, s5, -1
	global_load_lds_dwordx4 v134, s[100:101]
	s_mov_b32 m0, s47
	s_nop 0
	global_load_lds_dwordx4 v130, s[100:101]
	s_add_i32 s55, s55, 2
	s_add_u32 s0, s0, 0x100
	s_addc_u32 s1, s1, 0
	s_add_u32 s53, s53, 0x100
	s_addc_u32 s54, s54, 0
	s_cmp_gt_u32 s55, 13
	s_waitcnt vmcnt(8)
	s_waitcnt lgkmcnt(0)
	s_barrier
	s_setprio 1
	v_mfma_f32_16x16x32_bf16 v[60:63], v[140:143], v[214:217], v[60:63]
	v_mfma_f32_16x16x32_bf16 v[56:59], v[170:173], v[214:217], v[56:59]
	v_mfma_f32_16x16x32_bf16 v[44:47], v[140:143], v[222:225], v[44:47]
	v_mfma_f32_16x16x32_bf16 v[40:43], v[170:173], v[222:225], v[40:43]
	v_mfma_f32_16x16x32_bf16 v[28:31], v[140:143], v[230:233], v[28:31]
	v_mfma_f32_16x16x32_bf16 v[24:27], v[170:173], v[230:233], v[24:27]
	v_mfma_f32_16x16x32_bf16 v[12:15], v[140:143], v[238:241], v[12:15]
	v_mfma_f32_16x16x32_bf16 v[8:11], v[170:173], v[238:241], v[8:11]
	v_mfma_f32_16x16x32_bf16 v[60:63], v[166:169], v[218:221], v[60:63]
	v_mfma_f32_16x16x32_bf16 v[56:59], v[174:177], v[218:221], v[56:59]
	v_mfma_f32_16x16x32_bf16 v[44:47], v[166:169], v[226:229], v[44:47]
	v_mfma_f32_16x16x32_bf16 v[40:43], v[174:177], v[226:229], v[40:43]
	v_mfma_f32_16x16x32_bf16 v[28:31], v[166:169], v[234:237], v[28:31]
	v_mfma_f32_16x16x32_bf16 v[24:27], v[174:177], v[234:237], v[24:27]
	v_mfma_f32_16x16x32_bf16 v[12:15], v[166:169], v[242:245], v[12:15]
	v_mfma_f32_16x16x32_bf16 v[8:11], v[174:177], v[242:245], v[8:11]
	v_mfma_f32_16x16x32_bf16 v[52:55], v[178:181], v[214:217], v[52:55]
	v_mfma_f32_16x16x32_bf16 v[48:51], v[186:189], v[214:217], v[48:51]
	v_mfma_f32_16x16x32_bf16 v[36:39], v[178:181], v[222:225], v[36:39]
	v_mfma_f32_16x16x32_bf16 v[32:35], v[186:189], v[222:225], v[32:35]
	v_mfma_f32_16x16x32_bf16 v[20:23], v[178:181], v[230:233], v[20:23]
	v_mfma_f32_16x16x32_bf16 v[16:19], v[186:189], v[230:233], v[16:19]
	v_mfma_f32_16x16x32_bf16 v[4:7], v[178:181], v[238:241], v[4:7]
	v_mfma_f32_16x16x32_bf16 v[0:3], v[186:189], v[238:241], v[0:3]
	v_mfma_f32_16x16x32_bf16 v[52:55], v[182:185], v[218:221], v[52:55]
	v_mfma_f32_16x16x32_bf16 v[48:51], v[210:213], v[218:221], v[48:51]
	v_mfma_f32_16x16x32_bf16 v[36:39], v[182:185], v[226:229], v[36:39]
	v_mfma_f32_16x16x32_bf16 v[32:35], v[210:213], v[226:229], v[32:35]
	v_mfma_f32_16x16x32_bf16 v[20:23], v[182:185], v[234:237], v[20:23]
	v_mfma_f32_16x16x32_bf16 v[16:19], v[210:213], v[234:237], v[16:19]
	v_mfma_f32_16x16x32_bf16 v[4:7], v[182:185], v[242:245], v[4:7]
	v_mfma_f32_16x16x32_bf16 v[0:3], v[210:213], v[242:245], v[0:3]
	s_setprio 0
	s_barrier
; #define PG8_STAGE(bufoff, gbase, voff) do { _Pragma("unroll") for (int _i = 0; _i < 2; ++_i) \
;         __builtin_amdgcn_global_load_lds((const unsigned*)((const char*)(gbase) + (voff)[_i]), (PG8_LAS unsigned*)(lds + (bufoff) + ldsw + _i * 8192), 16, 0, 0); } while (0)
; #define PG8_LDA(dst, b, h) do { _Pragma("unroll") for (int m = 0; m < 4; ++m) _Pragma("unroll") for (int k = 0; k < 2; ++k) dst[m][k] = *(const PG8_LAS bf16x8*)(lds + PG8_SA(b, h) + aoff + m * 2048 + k * 1024); } while (0)
; #define PG8_LDB(dst, b, h) do { _Pragma("unroll") for (int n = 0; n < 2; ++n) _Pragma("unroll") for (int k = 0; k < 2; ++k) dst[n][k] = *(const PG8_LAS bf16x8*)(lds + PG8_SB(b, h) + boff + n * 2048 + k * 1024); } while (0)
; #define PG8_MMA(ai, bj, At, Bt) do { __builtin_amdgcn_s_setprio(1); _Pragma("unroll") for (int m = 0; m < 4; ++m) _Pragma("unroll") for (int n = 0; n < 2; ++n) _Pragma("unroll") for (int k = 0; k < 2; ++k) \
;         acc[ai][bj][m][n] = __builtin_amdgcn_mfma_f32_16x16x32_bf16(Bt[n][k], At[m][k], acc[ai][bj][m][n], 0, 0, 0); __builtin_amdgcn_s_setprio(0); } while (0)
; #define PG8_WAIT_V(n) asm volatile("s_waitcnt vmcnt(" #n ")" ::: "memory")
; #define PG8_WAIT_L(n) asm volatile("s_waitcnt lgkmcnt(" #n ")" ::: "memory")
; #define PG8_BAR __builtin_amdgcn_s_barrier()
; #define PG8_SCHED __builtin_amdgcn_sched_barrier(0)
; template <class Epi, class Sched, bool ALIGN_EPI = false, bool SP2 = false>
; __device__ __forceinline__ void gemm_phase(PG8_LAS unsigned char* lds, const Gemm g, const Sched& S, const Epi& E) {
;     ...
;             PG8_LDB(B0, 0, 0); PG8_LDB(B1, 0, 1); PG8_SCHED; PG8_LDA(At, 0, 0); PG8_STAGE(PG8_SA(1, 1), a1 + hstep, voffA);
;             PG8_WAIT_V(8); PG8_WAIT_L(0); PG8_BAR; PG8_MMA(0, 0, At, B0); PG8_MMA(0, 1, At, B1); PG8_BAR; PG8_SCHED;
;             PG8_LDA(At, 0, 1); PG8_STAGE(PG8_SB(0, 0), b2, voffB); PG8_STAGE(PG8_SB(0, 1), b2 + hstep, voffB); PG8_STAGE(PG8_SA(0, 0), a2, voffA);
;             PG8_WAIT_V(8); PG8_WAIT_L(0); PG8_BAR; PG8_MMA(1, 0, At, B0); PG8_MMA(1, 1, At, B1); PG8_BAR; PG8_SCHED;
.LBB0_1042:
	ds_read_b128 v[140:143], v254
	ds_read_b128 v[166:169], v254 offset:1024
	ds_read_b128 v[170:173], v254 offset:2048
	ds_read_b128 v[174:177], v254 offset:3072
	ds_read_b128 v[178:181], v254 offset:16384
	ds_read_b128 v[182:185], v254 offset:17408
	ds_read_b128 v[186:189], v254 offset:18432
	ds_read_b128 v[210:213], v254 offset:19456
	s_add_u32 s2, s0, 0xfffc0080
	s_addc_u32 s3, s1, -1
	s_cmp_eq_u32 s55, 12
	s_cselect_b32 s5, s23, s3
	s_cselect_b32 s4, s51, s2
	s_cselect_b32 s3, s21, s54
	s_cselect_b32 s2, s52, s53
	s_add_i32 m0, s31, 0xc000
	ds_read_b128 v[214:217], v163
	ds_read_b128 v[218:221], v163 offset:1024
	ds_read_b128 v[222:225], v163 offset:2048
	ds_read_b128 v[226:229], v163 offset:3072
	ds_read_b128 v[230:233], v163 offset:4096
	ds_read_b128 v[234:237], v163 offset:5120
	ds_read_b128 v[238:241], v163 offset:6144
	ds_read_b128 v[242:245], v163 offset:7168
	global_load_lds_dwordx4 v136, s[0:1]
	s_add_i32 m0, s31, 0xe000
	s_nop 0
	global_load_lds_dwordx4 v138, s[0:1]
	s_waitcnt vmcnt(8)
	s_waitcnt lgkmcnt(0)
	s_barrier
	s_setprio 1
	v_mfma_f32_16x16x32_bf16 v[124:127], v[140:143], v[214:217], v[124:127]
	v_mfma_f32_16x16x32_bf16 v[120:123], v[170:173], v[214:217], v[120:123]
	v_mfma_f32_16x16x32_bf16 v[108:111], v[140:143], v[222:225], v[108:111]
	v_mfma_f32_16x16x32_bf16 v[104:107], v[170:173], v[222:225], v[104:107]
	v_mfma_f32_16x16x32_bf16 v[92:95], v[140:143], v[230:233], v[92:95]
	v_mfma_f32_16x16x32_bf16 v[88:91], v[170:173], v[230:233], v[88:91]
	v_mfma_f32_16x16x32_bf16 v[76:79], v[140:143], v[238:241], v[76:79]
	v_mfma_f32_16x16x32_bf16 v[72:75], v[170:173], v[238:241], v[72:75]
	v_mfma_f32_16x16x32_bf16 v[124:127], v[166:169], v[218:221], v[124:127]
	v_mfma_f32_16x16x32_bf16 v[120:123], v[174:177], v[218:221], v[120:123]
	v_mfma_f32_16x16x32_bf16 v[108:111], v[166:169], v[226:229], v[108:111]
	v_mfma_f32_16x16x32_bf16 v[104:107], v[174:177], v[226:229], v[104:107]
	v_mfma_f32_16x16x32_bf16 v[92:95], v[166:169], v[234:237], v[92:95]
	v_mfma_f32_16x16x32_bf16 v[88:91], v[174:177], v[234:237], v[88:91]
	v_mfma_f32_16x16x32_bf16 v[76:79], v[166:169], v[242:245], v[76:79]
	v_mfma_f32_16x16x32_bf16 v[72:75], v[174:177], v[242:245], v[72:75]
	v_mfma_f32_16x16x32_bf16 v[116:119], v[178:181], v[214:217], v[116:119]
	v_mfma_f32_16x16x32_bf16 v[112:115], v[186:189], v[214:217], v[112:115]
	v_mfma_f32_16x16x32_bf16 v[100:103], v[178:181], v[222:225], v[100:103]
	v_mfma_f32_16x16x32_bf16 v[96:99], v[186:189], v[222:225], v[96:99]
	v_mfma_f32_16x16x32_bf16 v[84:87], v[178:181], v[230:233], v[84:87]
	v_mfma_f32_16x16x32_bf16 v[80:83], v[186:189], v[230:233], v[80:83]
	v_mfma_f32_16x16x32_bf16 v[68:71], v[178:181], v[238:241], v[68:71]
	v_mfma_f32_16x16x32_bf16 v[64:67], v[186:189], v[238:241], v[64:67]
	v_mfma_f32_16x16x32_bf16 v[116:119], v[182:185], v[218:221], v[116:119]
	v_mfma_f32_16x16x32_bf16 v[112:115], v[210:213], v[218:221], v[112:115]
	v_mfma_f32_16x16x32_bf16 v[100:103], v[182:185], v[226:229], v[100:103]
	v_mfma_f32_16x16x32_bf16 v[96:99], v[210:213], v[226:229], v[96:99]
	v_mfma_f32_16x16x32_bf16 v[84:87], v[182:185], v[234:237], v[84:87]
	v_mfma_f32_16x16x32_bf16 v[80:83], v[210:213], v[234:237], v[80:83]
	v_mfma_f32_16x16x32_bf16 v[68:71], v[182:185], v[242:245], v[68:71]
	v_mfma_f32_16x16x32_bf16 v[64:67], v[210:213], v[242:245], v[64:67]
	s_setprio 0
	s_barrier
	s_mov_b32 m0, s33
	s_add_u32 s56, s2, 0x40000
	s_addc_u32 s57, s3, 0
	ds_read_b128 v[214:217], v163 offset:16384
	ds_read_b128 v[218:221], v163 offset:17408
	ds_read_b128 v[222:225], v163 offset:18432
	ds_read_b128 v[226:229], v163 offset:19456
	ds_read_b128 v[230:233], v163 offset:20480
	ds_read_b128 v[234:237], v163 offset:21504
	ds_read_b128 v[238:241], v163 offset:22528
	ds_read_b128 v[242:245], v163 offset:23552
	global_load_lds_dwordx4 v132, s[2:3]
	s_mov_b32 m0, s34
	s_nop 0
	global_load_lds_dwordx4 v128, s[2:3]
	s_mov_b32 m0, s35
	s_nop 0
	global_load_lds_dwordx4 v132, s[56:57]
	s_mov_b32 m0, s36
	s_nop 0
	global_load_lds_dwordx4 v128, s[56:57]
	s_mov_b32 m0, s31
	s_nop 0
	global_load_lds_dwordx4 v134, s[4:5]
	s_mov_b32 m0, s37
	s_nop 0
	global_load_lds_dwordx4 v130, s[4:5]
	s_waitcnt vmcnt(8)
	s_waitcnt lgkmcnt(0)
	s_barrier
	s_setprio 1
	v_mfma_f32_16x16x32_bf16 v[60:63], v[140:143], v[214:217], v[60:63]
	v_mfma_f32_16x16x32_bf16 v[56:59], v[170:173], v[214:217], v[56:59]
	v_mfma_f32_16x16x32_bf16 v[44:47], v[140:143], v[222:225], v[44:47]
	v_mfma_f32_16x16x32_bf16 v[40:43], v[170:173], v[222:225], v[40:43]
	v_mfma_f32_16x16x32_bf16 v[28:31], v[140:143], v[230:233], v[28:31]
	v_mfma_f32_16x16x32_bf16 v[24:27], v[170:173], v[230:233], v[24:27]
	v_mfma_f32_16x16x32_bf16 v[12:15], v[140:143], v[238:241], v[12:15]
	v_mfma_f32_16x16x32_bf16 v[8:11], v[170:173], v[238:241], v[8:11]
	v_mfma_f32_16x16x32_bf16 v[60:63], v[166:169], v[218:221], v[60:63]
	v_mfma_f32_16x16x32_bf16 v[56:59], v[174:177], v[218:221], v[56:59]
	v_mfma_f32_16x16x32_bf16 v[44:47], v[166:169], v[226:229], v[44:47]
	v_mfma_f32_16x16x32_bf16 v[40:43], v[174:177], v[226:229], v[40:43]
	v_mfma_f32_16x16x32_bf16 v[28:31], v[166:169], v[234:237], v[28:31]
	v_mfma_f32_16x16x32_bf16 v[24:27], v[174:177], v[234:237], v[24:27]
	v_mfma_f32_16x16x32_bf16 v[12:15], v[166:169], v[242:245], v[12:15]
	v_mfma_f32_16x16x32_bf16 v[8:11], v[174:177], v[242:245], v[8:11]
	v_mfma_f32_16x16x32_bf16 v[52:55], v[178:181], v[214:217], v[52:55]
	v_mfma_f32_16x16x32_bf16 v[48:51], v[186:189], v[214:217], v[48:51]
	v_mfma_f32_16x16x32_bf16 v[36:39], v[178:181], v[222:225], v[36:39]
	v_mfma_f32_16x16x32_bf16 v[32:35], v[186:189], v[222:225], v[32:35]
	v_mfma_f32_16x16x32_bf16 v[20:23], v[178:181], v[230:233], v[20:23]
	v_mfma_f32_16x16x32_bf16 v[16:19], v[186:189], v[230:233], v[16:19]
	v_mfma_f32_16x16x32_bf16 v[4:7], v[178:181], v[238:241], v[4:7]
	v_mfma_f32_16x16x32_bf16 v[0:3], v[186:189], v[238:241], v[0:3]
	v_mfma_f32_16x16x32_bf16 v[52:55], v[182:185], v[218:221], v[52:55]
	v_mfma_f32_16x16x32_bf16 v[48:51], v[210:213], v[218:221], v[48:51]
	v_mfma_f32_16x16x32_bf16 v[36:39], v[182:185], v[226:229], v[36:39]
	v_mfma_f32_16x16x32_bf16 v[32:35], v[210:213], v[226:229], v[32:35]
	v_mfma_f32_16x16x32_bf16 v[20:23], v[182:185], v[234:237], v[20:23]
	v_mfma_f32_16x16x32_bf16 v[16:19], v[210:213], v[234:237], v[16:19]
	v_mfma_f32_16x16x32_bf16 v[4:7], v[182:185], v[242:245], v[4:7]
	v_mfma_f32_16x16x32_bf16 v[0:3], v[210:213], v[242:245], v[0:3]
	s_setprio 0
	s_barrier
; #define PG8_STAGE(bufoff, gbase, voff) do { _Pragma("unroll") for (int _i = 0; _i < 2; ++_i) \
;         __builtin_amdgcn_global_load_lds((const unsigned*)((const char*)(gbase) + (voff)[_i]), (PG8_LAS unsigned*)(lds + (bufoff) + ldsw + _i * 8192), 16, 0, 0); } while (0)
; #define PG8_LDA(dst, b, h) do { _Pragma("unroll") for (int m = 0; m < 4; ++m) _Pragma("unroll") for (int k = 0; k < 2; ++k) dst[m][k] = *(const PG8_LAS bf16x8*)(lds + PG8_SA(b, h) + aoff + m * 2048 + k * 1024); } while (0)
; #define PG8_LDB(dst, b, h) do { _Pragma("unroll") for (int n = 0; n < 2; ++n) _Pragma("unroll") for (int k = 0; k < 2; ++k) dst[n][k] = *(const PG8_LAS bf16x8*)(lds + PG8_SB(b, h) + boff + n * 2048 + k * 1024); } while (0)
; #define PG8_MMA(ai, bj, At, Bt) do { __builtin_amdgcn_s_setprio(1); _Pragma("unroll") for (int m = 0; m < 4; ++m) _Pragma("unroll") for (int n = 0; n < 2; ++n) _Pragma("unroll") for (int k = 0; k < 2; ++k) \
;         acc[ai][bj][m][n] = __builtin_amdgcn_mfma_f32_16x16x32_bf16(Bt[n][k], At[m][k], acc[ai][bj][m][n], 0, 0, 0); __builtin_amdgcn_s_setprio(0); } while (0)
; #define PG8_WAIT_V(n) asm volatile("s_waitcnt vmcnt(" #n ")" ::: "memory")
; #define PG8_WAIT_L(n) asm volatile("s_waitcnt lgkmcnt(" #n ")" ::: "memory")
; #define PG8_BAR __builtin_amdgcn_s_barrier()
; #define PG8_SCHED __builtin_amdgcn_sched_barrier(0)
; template <class Epi, class Sched, bool ALIGN_EPI = false, bool SP2 = false>
; __device__ __forceinline__ void gemm_phase(PG8_LAS unsigned char* lds, const Gemm g, const Sched& S, const Epi& E) {
;     ...
;             PG8_LDB(B0, 1, 0); PG8_LDB(B1, 1, 1); PG8_SCHED; PG8_LDA(At, 1, 0); PG8_STAGE(PG8_SA(0, 1), a2 + hstep, voffA);
;             PG8_WAIT_V(8); PG8_WAIT_L(0); PG8_BAR; PG8_MMA(0, 0, At, B0); PG8_MMA(0, 1, At, B1); PG8_BAR; PG8_SCHED;
;             PG8_LDA(At, 1, 1); PG8_STAGE(PG8_SB(1, 0), b3, voffB); PG8_STAGE(PG8_SB(1, 1), b3 + hstep, voffB); PG8_STAGE(PG8_SA(1, 0), a3, voffA);
;             PG8_WAIT_V(8); PG8_WAIT_L(0); PG8_BAR; PG8_MMA(1, 0, At, B0); PG8_MMA(1, 1, At, B1); PG8_BAR; PG8_SCHED;
;     ...
;         if constexpr (ALIGN_EPI) { if (wr == 0) PG8_BAR; }
	ds_read_b128 v[140:143], v254 offset:32768
	ds_read_b128 v[166:169], v254 offset:33792
	ds_read_b128 v[170:173], v254 offset:34816
	ds_read_b128 v[174:177], v254 offset:35840
	ds_read_b128 v[178:181], v254 offset:49152
	ds_read_b128 v[182:185], v254 offset:50176
	ds_read_b128 v[186:189], v254 offset:51200
	ds_read_b128 v[210:213], v254 offset:52224
	s_add_u32 s4, s4, 0x40000
	s_addc_u32 s5, s5, 0
	s_mov_b32 m0, s38
	ds_read_b128 v[214:217], v163 offset:32768
	ds_read_b128 v[218:221], v163 offset:33792
	ds_read_b128 v[222:225], v163 offset:34816
	ds_read_b128 v[226:229], v163 offset:35840
	ds_read_b128 v[230:233], v163 offset:36864
	ds_read_b128 v[234:237], v163 offset:37888
	ds_read_b128 v[238:241], v163 offset:38912
	ds_read_b128 v[242:245], v163 offset:39936
	global_load_lds_dwordx4 v134, s[4:5]
	s_mov_b32 m0, s39
	s_nop 0
	global_load_lds_dwordx4 v130, s[4:5]
	s_waitcnt vmcnt(8)
	s_waitcnt lgkmcnt(0)
	s_barrier
	s_setprio 1
	v_mfma_f32_16x16x32_bf16 v[124:127], v[140:143], v[214:217], v[124:127]
	v_mfma_f32_16x16x32_bf16 v[120:123], v[170:173], v[214:217], v[120:123]
	v_mfma_f32_16x16x32_bf16 v[108:111], v[140:143], v[222:225], v[108:111]
	v_mfma_f32_16x16x32_bf16 v[104:107], v[170:173], v[222:225], v[104:107]
	v_mfma_f32_16x16x32_bf16 v[92:95], v[140:143], v[230:233], v[92:95]
	v_mfma_f32_16x16x32_bf16 v[88:91], v[170:173], v[230:233], v[88:91]
	v_mfma_f32_16x16x32_bf16 v[76:79], v[140:143], v[238:241], v[76:79]
	v_mfma_f32_16x16x32_bf16 v[72:75], v[170:173], v[238:241], v[72:75]
	v_mfma_f32_16x16x32_bf16 v[124:127], v[166:169], v[218:221], v[124:127]
	v_mfma_f32_16x16x32_bf16 v[120:123], v[174:177], v[218:221], v[120:123]
	v_mfma_f32_16x16x32_bf16 v[108:111], v[166:169], v[226:229], v[108:111]
	v_mfma_f32_16x16x32_bf16 v[104:107], v[174:177], v[226:229], v[104:107]
	v_mfma_f32_16x16x32_bf16 v[92:95], v[166:169], v[234:237], v[92:95]
	v_mfma_f32_16x16x32_bf16 v[88:91], v[174:177], v[234:237], v[88:91]
	v_mfma_f32_16x16x32_bf16 v[76:79], v[166:169], v[242:245], v[76:79]
	v_mfma_f32_16x16x32_bf16 v[72:75], v[174:177], v[242:245], v[72:75]
	v_mfma_f32_16x16x32_bf16 v[116:119], v[178:181], v[214:217], v[116:119]
	v_mfma_f32_16x16x32_bf16 v[112:115], v[186:189], v[214:217], v[112:115]
	v_mfma_f32_16x16x32_bf16 v[100:103], v[178:181], v[222:225], v[100:103]
	v_mfma_f32_16x16x32_bf16 v[96:99], v[186:189], v[222:225], v[96:99]
	v_mfma_f32_16x16x32_bf16 v[84:87], v[178:181], v[230:233], v[84:87]
	v_mfma_f32_16x16x32_bf16 v[80:83], v[186:189], v[230:233], v[80:83]
	v_mfma_f32_16x16x32_bf16 v[68:71], v[178:181], v[238:241], v[68:71]
	v_mfma_f32_16x16x32_bf16 v[64:67], v[186:189], v[238:241], v[64:67]
	v_mfma_f32_16x16x32_bf16 v[116:119], v[182:185], v[218:221], v[116:119]
	v_mfma_f32_16x16x32_bf16 v[112:115], v[210:213], v[218:221], v[112:115]
	v_mfma_f32_16x16x32_bf16 v[100:103], v[182:185], v[226:229], v[100:103]
	v_mfma_f32_16x16x32_bf16 v[96:99], v[210:213], v[226:229], v[96:99]
	v_mfma_f32_16x16x32_bf16 v[84:87], v[182:185], v[234:237], v[84:87]
	v_mfma_f32_16x16x32_bf16 v[80:83], v[210:213], v[234:237], v[80:83]
	v_mfma_f32_16x16x32_bf16 v[68:71], v[182:185], v[242:245], v[68:71]
	v_mfma_f32_16x16x32_bf16 v[64:67], v[210:213], v[242:245], v[64:67]
	s_setprio 0
	s_barrier
	s_mov_b32 m0, s43
	s_add_u32 s2, s2, 0x40080
	s_addc_u32 s3, s3, 0
	ds_read_b128 v[214:217], v163 offset:49152
	ds_read_b128 v[218:221], v163 offset:50176
	ds_read_b128 v[222:225], v163 offset:51200
	ds_read_b128 v[226:229], v163 offset:52224
	ds_read_b128 v[230:233], v163 offset:53248
	ds_read_b128 v[234:237], v163 offset:54272
	ds_read_b128 v[238:241], v163 offset:55296
	ds_read_b128 v[242:245], v163 offset:56320
	s_add_u32 s98, s2, 0xfffc0000
	s_addc_u32 s99, s3, -1
	global_load_lds_dwordx4 v132, s[98:99]
	s_mov_b32 m0, s44
	s_nop 0
	global_load_lds_dwordx4 v128, s[98:99]
	s_mov_b32 m0, s48
	s_nop 0
	global_load_lds_dwordx4 v132, s[2:3]
	s_mov_b32 m0, s49
	s_nop 0
	global_load_lds_dwordx4 v128, s[2:3]
	s_mov_b32 m0, s45
	s_nop 0
	s_add_u32 s100, s4, 0xfffc0080
	s_addc_u32 s101, s5, -1
	global_load_lds_dwordx4 v134, s[100:101]
	s_mov_b32 m0, s47
	s_nop 0
	global_load_lds_dwordx4 v130, s[100:101]
	s_add_i32 s55, s55, 2
	s_add_u32 s0, s0, 0x100
	s_addc_u32 s1, s1, 0
	s_add_u32 s53, s53, 0x100
	s_addc_u32 s54, s54, 0
	s_cmp_gt_u32 s55, 13
	s_waitcnt vmcnt(8)
	s_waitcnt lgkmcnt(0)
	s_barrier
	s_setprio 1
	v_mfma_f32_16x16x32_bf16 v[60:63], v[140:143], v[214:217], v[60:63]
	v_mfma_f32_16x16x32_bf16 v[56:59], v[170:173], v[214:217], v[56:59]
	v_mfma_f32_16x16x32_bf16 v[44:47], v[140:143], v[222:225], v[44:47]
	v_mfma_f32_16x16x32_bf16 v[40:43], v[170:173], v[222:225], v[40:43]
	v_mfma_f32_16x16x32_bf16 v[28:31], v[140:143], v[230:233], v[28:31]
	v_mfma_f32_16x16x32_bf16 v[24:27], v[170:173], v[230:233], v[24:27]
	v_mfma_f32_16x16x32_bf16 v[12:15], v[140:143], v[238:241], v[12:15]
	v_mfma_f32_16x16x32_bf16 v[8:11], v[170:173], v[238:241], v[8:11]
	v_mfma_f32_16x16x32_bf16 v[60:63], v[166:169], v[218:221], v[60:63]
	v_mfma_f32_16x16x32_bf16 v[56:59], v[174:177], v[218:221], v[56:59]
	v_mfma_f32_16x16x32_bf16 v[44:47], v[166:169], v[226:229], v[44:47]
	v_mfma_f32_16x16x32_bf16 v[40:43], v[174:177], v[226:229], v[40:43]
	v_mfma_f32_16x16x32_bf16 v[28:31], v[166:169], v[234:237], v[28:31]
	v_mfma_f32_16x16x32_bf16 v[24:27], v[174:177], v[234:237], v[24:27]
	v_mfma_f32_16x16x32_bf16 v[12:15], v[166:169], v[242:245], v[12:15]
	v_mfma_f32_16x16x32_bf16 v[8:11], v[174:177], v[242:245], v[8:11]
	v_mfma_f32_16x16x32_bf16 v[52:55], v[178:181], v[214:217], v[52:55]
	v_mfma_f32_16x16x32_bf16 v[48:51], v[186:189], v[214:217], v[48:51]
	v_mfma_f32_16x16x32_bf16 v[36:39], v[178:181], v[222:225], v[36:39]
	v_mfma_f32_16x16x32_bf16 v[32:35], v[186:189], v[222:225], v[32:35]
	v_mfma_f32_16x16x32_bf16 v[20:23], v[178:181], v[230:233], v[20:23]
	v_mfma_f32_16x16x32_bf16 v[16:19], v[186:189], v[230:233], v[16:19]
	v_mfma_f32_16x16x32_bf16 v[4:7], v[178:181], v[238:241], v[4:7]
	v_mfma_f32_16x16x32_bf16 v[0:3], v[186:189], v[238:241], v[0:3]
	v_mfma_f32_16x16x32_bf16 v[52:55], v[182:185], v[218:221], v[52:55]
	v_mfma_f32_16x16x32_bf16 v[48:51], v[210:213], v[218:221], v[48:51]
	v_mfma_f32_16x16x32_bf16 v[36:39], v[182:185], v[226:229], v[36:39]
	v_mfma_f32_16x16x32_bf16 v[32:35], v[210:213], v[226:229], v[32:35]
	v_mfma_f32_16x16x32_bf16 v[20:23], v[182:185], v[234:237], v[20:23]
	v_mfma_f32_16x16x32_bf16 v[16:19], v[210:213], v[234:237], v[16:19]
	v_mfma_f32_16x16x32_bf16 v[4:7], v[182:185], v[242:245], v[4:7]
	v_mfma_f32_16x16x32_bf16 v[0:3], v[210:213], v[242:245], v[0:3]
	s_setprio 0
	s_barrier
	s_cbranch_scc0 .LBB0_1042
	s_and_b64 vcc, exec, s[18:19]
	s_cbranch_vccz .LBB0_1045
	s_barrier
